# GEMM K-loops: redundant mid-cluster s_setprio 0/1 pairs removed (outer raise/lower kept)
# baseline (speedup 1.0000x reference)
; #define PG8_STAGE(bufoff, gbase, voff) do { _Pragma("unroll") for (int _i = 0; _i < 2; ++_i) \
;         __builtin_amdgcn_global_load_lds((const unsigned*)((const char*)(gbase) + (voff)[_i]), (LAS unsigned*)(lds + (bufoff) + ldsw + _i * 8192), 16, 0, 0); } while (0)
; #define PG8_LDA(dst, b, h) do { _Pragma("unroll") for (int m = 0; m < 4; ++m) _Pragma("unroll") for (int k = 0; k < 2; ++k) dst[m][k] = *(const LAS bf16x8*)(lds + PG8_SA(b, h) + aoff + m * 2048 + k * 1024); } while (0)
; #define PG8_LDB(dst, b, h) do { _Pragma("unroll") for (int n = 0; n < 2; ++n) _Pragma("unroll") for (int k = 0; k < 2; ++k) dst[n][k] = *(const LAS bf16x8*)(lds + PG8_SB(b, h) + boff + n * 2048 + k * 1024); } while (0)
; #define PG8_MMA(ai, bj, At, Bt) do { __builtin_amdgcn_s_setprio(1); _Pragma("unroll") for (int m = 0; m < 4; ++m) _Pragma("unroll") for (int n = 0; n < 2; ++n) _Pragma("unroll") for (int k = 0; k < 2; ++k) \
;         acc[ai][bj][m][n] = __builtin_amdgcn_mfma_f32_16x16x32_bf16(Bt[n][k], At[m][k], acc[ai][bj][m][n], 0, 0, 0); __builtin_amdgcn_s_setprio(0); } while (0)
; #define PG8_WAIT_V(n) asm volatile("s_waitcnt vmcnt(" #n ")" ::: "memory")
; #define PG8_BAR __builtin_amdgcn_s_barrier()
; template <class Epi, class Sched>
; DI void gemm_phase(LAS unsigned char* lds, const int tid, const int K, const int lda, const int ldb, const Sched& S_, const Epi& E) {
;     ...
;         const bool has_next = S_.next(ui + 1, nxt);
;         const char* nA = has_next ? nxt.a : cA; const char* nB = has_next ? nxt.b : cB;
;         for (int t = 0; t < nt; t += 2) {
;             const bool last = (t == nt - 2);
;             const char* a1 = cA + (size_t)(t + 1) * kstep;
;             const char* a2 = last ? nA : cA + (size_t)(t + 2) * kstep; const char* b2 = last ? nB : cB + (size_t)(t + 2) * kstep;
;             const char* a3 = a2 + kstep; const char* b3 = b2 + kstep;
;             PG8_LDB(B0, 0, 0); PG8_LDB(B1, 0, 1); PG8_SCHED; PG8_LDA(At, 0, 0); PG8_STAGE(PG8_SA(1, 1), a1 + hstepA, voffA);
;             PG8_WAIT_V(8); PG8_WAIT_L(0); PG8_BAR; PG8_MMA(0, 0, At, B0); PG8_MMA(0, 1, At, B1); PG8_BAR; PG8_SCHED;
;             PG8_LDA(At, 0, 1); PG8_STAGE(PG8_SB(0, 0), b2, voffB); PG8_STAGE(PG8_SB(0, 1), b2 + hstepB, voffB); PG8_STAGE(PG8_SA(0, 0), a2, voffA);
;             PG8_WAIT_V(8); PG8_WAIT_L(0); PG8_BAR; PG8_MMA(1, 0, At, B0); PG8_MMA(1, 1, At, B1); PG8_BAR; PG8_SCHED;
.LBB0_130:
	s_add_u32 s6, s4, 0xfff80080
	s_addc_u32 s7, s5, -1
	s_add_i32 s16, 0, 0x10000
	s_cmp_eq_u32 s14, 28
	s_cselect_b32 s9, s31, s7
	s_cselect_b32 s8, s30, s6
	v_add_u32_e32 v128, s16, v196
	s_cselect_b32 s7, s55, s11
	s_cselect_b32 s6, s54, s3
	s_add_i32 s20, 0, 0x14000
	ds_read_b128 v[130:133], v128
	ds_read_b128 v[134:137], v128 offset:1024
	ds_read_b128 v[156:159], v128 offset:2048
	ds_read_b128 v[160:163], v128 offset:3072
	v_add_u32_e32 v128, s20, v196
	ds_read_b128 v[164:167], v128
	ds_read_b128 v[168:171], v128 offset:1024
	ds_read_b128 v[172:175], v128 offset:2048
	ds_read_b128 v[176:179], v128 offset:3072
	v_lshl_add_u64 v[184:185], s[4:5], 0, v[152:153]
	s_add_i32 m0, s78, 0xc000
	ds_read_b128 v[180:183], v200
	ds_read_b128 v[190:193], v200 offset:1024
	ds_read_b128 v[202:205], v200 offset:2048
	ds_read_b128 v[206:209], v200 offset:3072
	ds_read_b128 v[222:225], v200 offset:4096
	ds_read_b128 v[226:229], v200 offset:5120
	ds_read_b128 v[230:233], v200 offset:6144
	ds_read_b128 v[234:237], v200 offset:7168
	global_load_lds_dwordx4 v[184:185], off
	v_lshl_add_u64 v[184:185], s[4:5], 0, v[154:155]
	s_add_i32 m0, s78, 0xe000
	s_nop 0
	global_load_lds_dwordx4 v[184:185], off
	s_waitcnt vmcnt(8)
	s_waitcnt lgkmcnt(0)
	s_barrier
	s_setprio 1
	s_waitcnt lgkmcnt(0)
	v_mfma_f32_16x16x32_bf16 v[124:127], v[130:133], v[180:183], v[124:127]
	v_mfma_f32_16x16x32_bf16 v[120:123], v[156:159], v[180:183], v[120:123]
	v_mfma_f32_16x16x32_bf16 v[108:111], v[130:133], v[202:205], v[108:111]
	v_mfma_f32_16x16x32_bf16 v[104:107], v[156:159], v[202:205], v[104:107]
	v_mfma_f32_16x16x32_bf16 v[92:95], v[130:133], v[222:225], v[92:95]
	v_mfma_f32_16x16x32_bf16 v[88:91], v[156:159], v[222:225], v[88:91]
	v_mfma_f32_16x16x32_bf16 v[76:79], v[130:133], v[230:233], v[76:79]
	v_mfma_f32_16x16x32_bf16 v[72:75], v[156:159], v[230:233], v[72:75]
	v_mfma_f32_16x16x32_bf16 v[124:127], v[134:137], v[190:193], v[124:127]
	v_mfma_f32_16x16x32_bf16 v[120:123], v[160:163], v[190:193], v[120:123]
	v_mfma_f32_16x16x32_bf16 v[108:111], v[134:137], v[206:209], v[108:111]
	v_mfma_f32_16x16x32_bf16 v[104:107], v[160:163], v[206:209], v[104:107]
	v_mfma_f32_16x16x32_bf16 v[92:95], v[134:137], v[226:229], v[92:95]
	v_mfma_f32_16x16x32_bf16 v[88:91], v[160:163], v[226:229], v[88:91]
	v_mfma_f32_16x16x32_bf16 v[76:79], v[134:137], v[234:237], v[76:79]
	v_mfma_f32_16x16x32_bf16 v[72:75], v[160:163], v[234:237], v[72:75]
	v_mfma_f32_16x16x32_bf16 v[116:119], v[164:167], v[180:183], v[116:119]
	v_mfma_f32_16x16x32_bf16 v[112:115], v[172:175], v[180:183], v[112:115]
	v_mfma_f32_16x16x32_bf16 v[100:103], v[164:167], v[202:205], v[100:103]
	v_mfma_f32_16x16x32_bf16 v[96:99], v[172:175], v[202:205], v[96:99]
	v_mfma_f32_16x16x32_bf16 v[84:87], v[164:167], v[222:225], v[84:87]
	v_mfma_f32_16x16x32_bf16 v[80:83], v[172:175], v[222:225], v[80:83]
	v_mfma_f32_16x16x32_bf16 v[68:71], v[164:167], v[230:233], v[68:71]
	v_mfma_f32_16x16x32_bf16 v[64:67], v[172:175], v[230:233], v[64:67]
	v_mfma_f32_16x16x32_bf16 v[116:119], v[168:171], v[190:193], v[116:119]
	v_mfma_f32_16x16x32_bf16 v[112:115], v[176:179], v[190:193], v[112:115]
	v_mfma_f32_16x16x32_bf16 v[100:103], v[168:171], v[206:209], v[100:103]
	v_mfma_f32_16x16x32_bf16 v[96:99], v[176:179], v[206:209], v[96:99]
	v_mfma_f32_16x16x32_bf16 v[84:87], v[168:171], v[226:229], v[84:87]
	v_mfma_f32_16x16x32_bf16 v[80:83], v[176:179], v[226:229], v[80:83]
	v_mfma_f32_16x16x32_bf16 v[68:71], v[168:171], v[234:237], v[68:71]
	v_mfma_f32_16x16x32_bf16 v[64:67], v[176:179], v[234:237], v[64:67]
	s_setprio 0
	s_barrier
	s_add_i32 s16, s16, s77
	v_lshl_add_u64 v[184:185], s[6:7], 0, v[140:141]
	s_mov_b32 m0, s16
	ds_read_b128 v[180:183], v200 offset:16384
	ds_read_b128 v[190:193], v200 offset:17408
	ds_read_b128 v[202:205], v200 offset:18432
	ds_read_b128 v[206:209], v200 offset:19456
	ds_read_b128 v[222:225], v200 offset:20480
	ds_read_b128 v[226:229], v200 offset:21504
	ds_read_b128 v[230:233], v200 offset:22528
	ds_read_b128 v[234:237], v200 offset:23552
	global_load_lds_dwordx4 v[184:185], off
	s_add_i32 m0, s16, 0x2000
	s_add_u32 s16, s6, 0x80000
	v_lshl_add_u64 v[186:187], s[6:7], 0, v[144:145]
	s_addc_u32 s17, s7, 0
	s_add_i32 s20, s20, s77
	global_load_lds_dwordx4 v[186:187], off
	v_lshl_add_u64 v[188:189], s[16:17], 0, v[140:141]
	s_mov_b32 m0, s20
	v_lshl_add_u64 v[194:195], s[8:9], 0, v[142:143]
	global_load_lds_dwordx4 v[188:189], off
	v_lshl_add_u64 v[188:189], s[16:17], 0, v[144:145]
	s_add_i32 m0, s20, 0x2000
	s_nop 0
	global_load_lds_dwordx4 v[188:189], off
	v_lshl_add_u64 v[188:189], s[8:9], 0, v[138:139]
	s_mov_b32 m0, s78
	s_nop 0
	global_load_lds_dwordx4 v[188:189], off
	s_mov_b32 m0, s79
	s_nop 0
	global_load_lds_dwordx4 v[194:195], off
	s_waitcnt vmcnt(8)
	s_waitcnt lgkmcnt(0)
	s_barrier
; #define PG8_STAGE(bufoff, gbase, voff) do { _Pragma("unroll") for (int _i = 0; _i < 2; ++_i) \
;         __builtin_amdgcn_global_load_lds((const unsigned*)((const char*)(gbase) + (voff)[_i]), (LAS unsigned*)(lds + (bufoff) + ldsw + _i * 8192), 16, 0, 0); } while (0)
; #define PG8_LDA(dst, b, h) do { _Pragma("unroll") for (int m = 0; m < 4; ++m) _Pragma("unroll") for (int k = 0; k < 2; ++k) dst[m][k] = *(const LAS bf16x8*)(lds + PG8_SA(b, h) + aoff + m * 2048 + k * 1024); } while (0)
; #define PG8_LDB(dst, b, h) do { _Pragma("unroll") for (int n = 0; n < 2; ++n) _Pragma("unroll") for (int k = 0; k < 2; ++k) dst[n][k] = *(const LAS bf16x8*)(lds + PG8_SB(b, h) + boff + n * 2048 + k * 1024); } while (0)
; #define PG8_MMA(ai, bj, At, Bt) do { __builtin_amdgcn_s_setprio(1); _Pragma("unroll") for (int m = 0; m < 4; ++m) _Pragma("unroll") for (int n = 0; n < 2; ++n) _Pragma("unroll") for (int k = 0; k < 2; ++k) \
;         acc[ai][bj][m][n] = __builtin_amdgcn_mfma_f32_16x16x32_bf16(Bt[n][k], At[m][k], acc[ai][bj][m][n], 0, 0, 0); __builtin_amdgcn_s_setprio(0); } while (0)
; #define PG8_WAIT_V(n) asm volatile("s_waitcnt vmcnt(" #n ")" ::: "memory")
; #define PG8_WAIT_L(n) asm volatile("s_waitcnt lgkmcnt(" #n ")" ::: "memory")
; #define PG8_BAR __builtin_amdgcn_s_barrier()
; #define PG8_SCHED __builtin_amdgcn_sched_barrier(0)
; template <class Epi, class Sched>
; DI void gemm_phase(LAS unsigned char* lds, const int tid, const int K, const int lda, const int ldb, const Sched& S_, const Epi& E) {
;     ...
;             PG8_WAIT_V(8); PG8_WAIT_L(0); PG8_BAR; PG8_MMA(1, 0, At, B0); PG8_MMA(1, 1, At, B1); PG8_BAR; PG8_SCHED;
;             PG8_LDB(B0, 1, 0); PG8_LDB(B1, 1, 1); PG8_SCHED; PG8_LDA(At, 1, 0); PG8_STAGE(PG8_SA(0, 1), a2 + hstepA, voffA);
;             PG8_WAIT_V(8); PG8_WAIT_L(0); PG8_BAR; PG8_MMA(0, 0, At, B0); PG8_MMA(0, 1, At, B1); PG8_BAR; PG8_SCHED;
	s_setprio 1
	s_waitcnt lgkmcnt(0)
	v_mfma_f32_16x16x32_bf16 v[60:63], v[130:133], v[180:183], v[60:63]
	v_mfma_f32_16x16x32_bf16 v[56:59], v[156:159], v[180:183], v[56:59]
	v_mfma_f32_16x16x32_bf16 v[44:47], v[130:133], v[202:205], v[44:47]
	v_mfma_f32_16x16x32_bf16 v[40:43], v[156:159], v[202:205], v[40:43]
	v_mfma_f32_16x16x32_bf16 v[28:31], v[130:133], v[222:225], v[28:31]
	v_mfma_f32_16x16x32_bf16 v[24:27], v[156:159], v[222:225], v[24:27]
	v_mfma_f32_16x16x32_bf16 v[12:15], v[130:133], v[230:233], v[12:15]
	v_mfma_f32_16x16x32_bf16 v[8:11], v[156:159], v[230:233], v[8:11]
	v_mfma_f32_16x16x32_bf16 v[60:63], v[134:137], v[190:193], v[60:63]
	v_mfma_f32_16x16x32_bf16 v[56:59], v[160:163], v[190:193], v[56:59]
	v_mfma_f32_16x16x32_bf16 v[44:47], v[134:137], v[206:209], v[44:47]
	v_mfma_f32_16x16x32_bf16 v[40:43], v[160:163], v[206:209], v[40:43]
	v_mfma_f32_16x16x32_bf16 v[28:31], v[134:137], v[226:229], v[28:31]
	v_mfma_f32_16x16x32_bf16 v[24:27], v[160:163], v[226:229], v[24:27]
	v_mfma_f32_16x16x32_bf16 v[12:15], v[134:137], v[234:237], v[12:15]
	v_mfma_f32_16x16x32_bf16 v[8:11], v[160:163], v[234:237], v[8:11]
	v_mfma_f32_16x16x32_bf16 v[52:55], v[164:167], v[180:183], v[52:55]
	v_mfma_f32_16x16x32_bf16 v[48:51], v[172:175], v[180:183], v[48:51]
	v_mfma_f32_16x16x32_bf16 v[36:39], v[164:167], v[202:205], v[36:39]
	v_mfma_f32_16x16x32_bf16 v[32:35], v[172:175], v[202:205], v[32:35]
	v_mfma_f32_16x16x32_bf16 v[20:23], v[164:167], v[222:225], v[20:23]
	v_mfma_f32_16x16x32_bf16 v[16:19], v[172:175], v[222:225], v[16:19]
	v_mfma_f32_16x16x32_bf16 v[4:7], v[164:167], v[230:233], v[4:7]
	v_mfma_f32_16x16x32_bf16 v[0:3], v[172:175], v[230:233], v[0:3]
	v_mfma_f32_16x16x32_bf16 v[52:55], v[168:171], v[190:193], v[52:55]
	v_mfma_f32_16x16x32_bf16 v[48:51], v[176:179], v[190:193], v[48:51]
	v_mfma_f32_16x16x32_bf16 v[36:39], v[168:171], v[206:209], v[36:39]
	v_mfma_f32_16x16x32_bf16 v[32:35], v[176:179], v[206:209], v[32:35]
	v_mfma_f32_16x16x32_bf16 v[20:23], v[168:171], v[226:229], v[20:23]
	v_mfma_f32_16x16x32_bf16 v[16:19], v[176:179], v[226:229], v[16:19]
	v_mfma_f32_16x16x32_bf16 v[4:7], v[168:171], v[234:237], v[4:7]
	v_mfma_f32_16x16x32_bf16 v[0:3], v[176:179], v[234:237], v[0:3]
	s_setprio 0
	s_barrier
	s_add_i32 s16, 0, 0x18000
	v_add_u32_e32 v128, s16, v196
	s_add_i32 s17, 0, 0x1c000
	ds_read_b128 v[130:133], v128
	ds_read_b128 v[134:137], v128 offset:1024
	ds_read_b128 v[156:159], v128 offset:2048
	ds_read_b128 v[160:163], v128 offset:3072
	v_add_u32_e32 v128, s17, v196
	ds_read_b128 v[164:167], v128
	ds_read_b128 v[168:171], v128 offset:1024
	ds_read_b128 v[172:175], v128 offset:2048
	ds_read_b128 v[176:179], v128 offset:3072
	s_add_u32 s8, s8, 0x80000
	s_addc_u32 s9, s9, 0
	s_mov_b32 m0, s80
	v_lshl_add_u64 v[210:211], s[8:9], 0, v[138:139]
	ds_read_b128 v[180:183], v200 offset:32768
	ds_read_b128 v[190:193], v200 offset:33792
	ds_read_b128 v[202:205], v200 offset:34816
	ds_read_b128 v[206:209], v200 offset:35840
	ds_read_b128 v[222:225], v200 offset:36864
	ds_read_b128 v[226:229], v200 offset:37888
	ds_read_b128 v[230:233], v200 offset:38912
	ds_read_b128 v[234:237], v200 offset:39936
	global_load_lds_dwordx4 v[210:211], off
	v_lshl_add_u64 v[210:211], s[8:9], 0, v[142:143]
	s_mov_b32 m0, s81
	s_nop 0
	global_load_lds_dwordx4 v[210:211], off
	s_waitcnt vmcnt(8)
	s_waitcnt lgkmcnt(0)
	s_barrier
	s_setprio 1
	s_waitcnt lgkmcnt(0)
	v_mfma_f32_16x16x32_bf16 v[124:127], v[130:133], v[180:183], v[124:127]
	v_mfma_f32_16x16x32_bf16 v[120:123], v[156:159], v[180:183], v[120:123]
	v_mfma_f32_16x16x32_bf16 v[108:111], v[130:133], v[202:205], v[108:111]
	v_mfma_f32_16x16x32_bf16 v[104:107], v[156:159], v[202:205], v[104:107]
	v_mfma_f32_16x16x32_bf16 v[92:95], v[130:133], v[222:225], v[92:95]
	v_mfma_f32_16x16x32_bf16 v[88:91], v[156:159], v[222:225], v[88:91]
	v_mfma_f32_16x16x32_bf16 v[76:79], v[130:133], v[230:233], v[76:79]
	v_mfma_f32_16x16x32_bf16 v[72:75], v[156:159], v[230:233], v[72:75]
	v_mfma_f32_16x16x32_bf16 v[124:127], v[134:137], v[190:193], v[124:127]
	v_mfma_f32_16x16x32_bf16 v[120:123], v[160:163], v[190:193], v[120:123]
	v_mfma_f32_16x16x32_bf16 v[108:111], v[134:137], v[206:209], v[108:111]
	v_mfma_f32_16x16x32_bf16 v[104:107], v[160:163], v[206:209], v[104:107]
	v_mfma_f32_16x16x32_bf16 v[92:95], v[134:137], v[226:229], v[92:95]
	v_mfma_f32_16x16x32_bf16 v[88:91], v[160:163], v[226:229], v[88:91]
	v_mfma_f32_16x16x32_bf16 v[76:79], v[134:137], v[234:237], v[76:79]
	v_mfma_f32_16x16x32_bf16 v[72:75], v[160:163], v[234:237], v[72:75]
	v_mfma_f32_16x16x32_bf16 v[116:119], v[164:167], v[180:183], v[116:119]
	v_mfma_f32_16x16x32_bf16 v[112:115], v[172:175], v[180:183], v[112:115]
	v_mfma_f32_16x16x32_bf16 v[100:103], v[164:167], v[202:205], v[100:103]
	v_mfma_f32_16x16x32_bf16 v[96:99], v[172:175], v[202:205], v[96:99]
	v_mfma_f32_16x16x32_bf16 v[84:87], v[164:167], v[222:225], v[84:87]
	v_mfma_f32_16x16x32_bf16 v[80:83], v[172:175], v[222:225], v[80:83]
	v_mfma_f32_16x16x32_bf16 v[68:71], v[164:167], v[230:233], v[68:71]
	v_mfma_f32_16x16x32_bf16 v[64:67], v[172:175], v[230:233], v[64:67]
	v_mfma_f32_16x16x32_bf16 v[116:119], v[168:171], v[190:193], v[116:119]
	v_mfma_f32_16x16x32_bf16 v[112:115], v[176:179], v[190:193], v[112:115]
	v_mfma_f32_16x16x32_bf16 v[100:103], v[168:171], v[206:209], v[100:103]
	v_mfma_f32_16x16x32_bf16 v[96:99], v[176:179], v[206:209], v[96:99]
	v_mfma_f32_16x16x32_bf16 v[84:87], v[168:171], v[226:229], v[84:87]
	v_mfma_f32_16x16x32_bf16 v[80:83], v[176:179], v[226:229], v[80:83]
	v_mfma_f32_16x16x32_bf16 v[68:71], v[168:171], v[234:237], v[68:71]
	v_mfma_f32_16x16x32_bf16 v[64:67], v[176:179], v[234:237], v[64:67]
	s_setprio 0
	s_barrier
; #define PG8_STAGE(bufoff, gbase, voff) do { _Pragma("unroll") for (int _i = 0; _i < 2; ++_i) \
;         __builtin_amdgcn_global_load_lds((const unsigned*)((const char*)(gbase) + (voff)[_i]), (LAS unsigned*)(lds + (bufoff) + ldsw + _i * 8192), 16, 0, 0); } while (0)
; #define PG8_LDA(dst, b, h) do { _Pragma("unroll") for (int m = 0; m < 4; ++m) _Pragma("unroll") for (int k = 0; k < 2; ++k) dst[m][k] = *(const LAS bf16x8*)(lds + PG8_SA(b, h) + aoff + m * 2048 + k * 1024); } while (0)
; #define PG8_MMA(ai, bj, At, Bt) do { __builtin_amdgcn_s_setprio(1); _Pragma("unroll") for (int m = 0; m < 4; ++m) _Pragma("unroll") for (int n = 0; n < 2; ++n) _Pragma("unroll") for (int k = 0; k < 2; ++k) \
;         acc[ai][bj][m][n] = __builtin_amdgcn_mfma_f32_16x16x32_bf16(Bt[n][k], At[m][k], acc[ai][bj][m][n], 0, 0, 0); __builtin_amdgcn_s_setprio(0); } while (0)
; #define PG8_WAIT_V(n) asm volatile("s_waitcnt vmcnt(" #n ")" ::: "memory")
; #define PG8_WAIT_L(n) asm volatile("s_waitcnt lgkmcnt(" #n ")" ::: "memory")
; #define PG8_BAR __builtin_amdgcn_s_barrier()
; #define PG8_SCHED __builtin_amdgcn_sched_barrier(0)
; template <class Epi, class Sched>
; DI void gemm_phase(LAS unsigned char* lds, const int tid, const int K, const int lda, const int ldb, const Sched& S_, const Epi& E) {
;     ...
;             PG8_LDA(At, 1, 1); PG8_STAGE(PG8_SB(1, 0), b3, voffB); PG8_STAGE(PG8_SB(1, 1), b3 + hstepB, voffB); PG8_STAGE(PG8_SA(1, 0), a3, voffA);
;             PG8_WAIT_V(8); PG8_WAIT_L(0); PG8_BAR; PG8_MMA(1, 0, At, B0); PG8_MMA(1, 1, At, B1); PG8_BAR; PG8_SCHED;
;             if constexpr (Epi::HOOK) { if (((t + 2) & 7) == 0 && !last) { E.hook(acc, cur, (t + 2) >> 3, wr, wc, fr, fq); PG8_SCHED; } }
;         }
	s_add_i32 s8, s16, s77
	v_lshl_add_u64 v[184:185], v[184:185], 0, s[94:95]
	s_mov_b32 m0, s8
	ds_read_b128 v[180:183], v200 offset:49152
	ds_read_b128 v[190:193], v200 offset:50176
	ds_read_b128 v[202:205], v200 offset:51200
	ds_read_b128 v[206:209], v200 offset:52224
	ds_read_b128 v[222:225], v200 offset:53248
	ds_read_b128 v[226:229], v200 offset:54272
	ds_read_b128 v[230:233], v200 offset:55296
	ds_read_b128 v[234:237], v200 offset:56320
	global_load_lds_dwordx4 v[184:185], off
	s_add_i32 m0, s8, 0x2000
	s_add_u32 s6, s6, 0x80080
	v_lshl_add_u64 v[184:185], v[186:187], 0, s[94:95]
	s_addc_u32 s7, s7, 0
	s_add_i32 s8, s17, s77
	global_load_lds_dwordx4 v[184:185], off
	v_lshl_add_u64 v[184:185], s[6:7], 0, v[140:141]
	s_mov_b32 m0, s8
	s_nop 0
	global_load_lds_dwordx4 v[184:185], off
	v_lshl_add_u64 v[184:185], s[6:7], 0, v[144:145]
	s_add_i32 m0, s8, 0x2000
	s_nop 0
	global_load_lds_dwordx4 v[184:185], off
	v_lshl_add_u64 v[184:185], v[188:189], 0, s[94:95]
	s_mov_b32 m0, s84
	s_nop 0
	global_load_lds_dwordx4 v[184:185], off
	v_lshl_add_u64 v[184:185], v[194:195], 0, s[94:95]
	s_mov_b32 m0, s85
	s_nop 0
	global_load_lds_dwordx4 v[184:185], off
	s_waitcnt vmcnt(8)
	s_waitcnt lgkmcnt(0)
	s_barrier
	s_setprio 1
	s_waitcnt lgkmcnt(0)
	v_mfma_f32_16x16x32_bf16 v[60:63], v[130:133], v[180:183], v[60:63]
	v_mfma_f32_16x16x32_bf16 v[56:59], v[156:159], v[180:183], v[56:59]
	v_mfma_f32_16x16x32_bf16 v[44:47], v[130:133], v[202:205], v[44:47]
	v_mfma_f32_16x16x32_bf16 v[40:43], v[156:159], v[202:205], v[40:43]
	v_mfma_f32_16x16x32_bf16 v[28:31], v[130:133], v[222:225], v[28:31]
	v_mfma_f32_16x16x32_bf16 v[24:27], v[156:159], v[222:225], v[24:27]
	v_mfma_f32_16x16x32_bf16 v[12:15], v[130:133], v[230:233], v[12:15]
	v_mfma_f32_16x16x32_bf16 v[8:11], v[156:159], v[230:233], v[8:11]
	v_mfma_f32_16x16x32_bf16 v[60:63], v[134:137], v[190:193], v[60:63]
	v_mfma_f32_16x16x32_bf16 v[56:59], v[160:163], v[190:193], v[56:59]
	v_mfma_f32_16x16x32_bf16 v[44:47], v[134:137], v[206:209], v[44:47]
	v_mfma_f32_16x16x32_bf16 v[40:43], v[160:163], v[206:209], v[40:43]
	v_mfma_f32_16x16x32_bf16 v[28:31], v[134:137], v[226:229], v[28:31]
	v_mfma_f32_16x16x32_bf16 v[24:27], v[160:163], v[226:229], v[24:27]
	v_mfma_f32_16x16x32_bf16 v[12:15], v[134:137], v[234:237], v[12:15]
	v_mfma_f32_16x16x32_bf16 v[8:11], v[160:163], v[234:237], v[8:11]
	v_mfma_f32_16x16x32_bf16 v[52:55], v[164:167], v[180:183], v[52:55]
	v_mfma_f32_16x16x32_bf16 v[48:51], v[172:175], v[180:183], v[48:51]
	v_mfma_f32_16x16x32_bf16 v[36:39], v[164:167], v[202:205], v[36:39]
	v_mfma_f32_16x16x32_bf16 v[32:35], v[172:175], v[202:205], v[32:35]
	v_mfma_f32_16x16x32_bf16 v[20:23], v[164:167], v[222:225], v[20:23]
	v_mfma_f32_16x16x32_bf16 v[16:19], v[172:175], v[222:225], v[16:19]
	v_mfma_f32_16x16x32_bf16 v[4:7], v[164:167], v[230:233], v[4:7]
	v_mfma_f32_16x16x32_bf16 v[0:3], v[172:175], v[230:233], v[0:3]
	v_mfma_f32_16x16x32_bf16 v[52:55], v[168:171], v[190:193], v[52:55]
	v_mfma_f32_16x16x32_bf16 v[48:51], v[176:179], v[190:193], v[48:51]
	v_mfma_f32_16x16x32_bf16 v[36:39], v[168:171], v[206:209], v[36:39]
	v_mfma_f32_16x16x32_bf16 v[32:35], v[176:179], v[206:209], v[32:35]
	v_mfma_f32_16x16x32_bf16 v[20:23], v[168:171], v[226:229], v[20:23]
	v_mfma_f32_16x16x32_bf16 v[16:19], v[176:179], v[226:229], v[16:19]
	v_mfma_f32_16x16x32_bf16 v[4:7], v[168:171], v[234:237], v[4:7]
	v_mfma_f32_16x16x32_bf16 v[0:3], v[176:179], v[234:237], v[0:3]
	s_setprio 0
	s_barrier
	s_add_i32 s14, s14, 2
	s_add_u32 s4, s4, 0x100
	s_addc_u32 s5, s5, 0
	s_add_u32 s3, s3, 0x100
	s_addc_u32 s11, s11, 0
	s_cmp_gt_u32 s14, 29
	s_cbranch_scc0 .LBB0_130
	s_and_b64 vcc, exec, s[60:61]
	s_cbranch_vccz .LBB0_133
	s_barrier

; #define PG8_STAGE(bufoff, gbase, voff) do { _Pragma("unroll") for (int _i = 0; _i < 2; ++_i) \
;         __builtin_amdgcn_global_load_lds((const unsigned*)((const char*)(gbase) + (voff)[_i]), (LAS unsigned*)(lds + (bufoff) + ldsw + _i * 8192), 16, 0, 0); } while (0)
; #define PG8_LDA(dst, b, h) do { _Pragma("unroll") for (int m = 0; m < 4; ++m) _Pragma("unroll") for (int k = 0; k < 2; ++k) dst[m][k] = *(const LAS bf16x8*)(lds + PG8_SA(b, h) + aoff + m * 2048 + k * 1024); } while (0)
; #define PG8_LDB(dst, b, h) do { _Pragma("unroll") for (int n = 0; n < 2; ++n) _Pragma("unroll") for (int k = 0; k < 2; ++k) dst[n][k] = *(const LAS bf16x8*)(lds + PG8_SB(b, h) + boff + n * 2048 + k * 1024); } while (0)
; #define PG8_MMA(ai, bj, At, Bt) do { __builtin_amdgcn_s_setprio(1); _Pragma("unroll") for (int m = 0; m < 4; ++m) _Pragma("unroll") for (int n = 0; n < 2; ++n) _Pragma("unroll") for (int k = 0; k < 2; ++k) \
;         acc[ai][bj][m][n] = __builtin_amdgcn_mfma_f32_16x16x32_bf16(Bt[n][k], At[m][k], acc[ai][bj][m][n], 0, 0, 0); __builtin_amdgcn_s_setprio(0); } while (0)
; #define PG8_WAIT_V(n) asm volatile("s_waitcnt vmcnt(" #n ")" ::: "memory")
; #define PG8_BAR __builtin_amdgcn_s_barrier()
; template <class Epi, class Sched>
; DI void gemm_phase(LAS unsigned char* lds, const int tid, const int K, const int lda, const int ldb, const Sched& S_, const Epi& E) {
;     ...
;         const bool has_next = S_.next(ui + 1, nxt);
;         const char* nA = has_next ? nxt.a : cA; const char* nB = has_next ? nxt.b : cB;
;         for (int t = 0; t < nt; t += 2) {
;             const bool last = (t == nt - 2);
;             const char* a1 = cA + (size_t)(t + 1) * kstep;
;             const char* a2 = last ? nA : cA + (size_t)(t + 2) * kstep; const char* b2 = last ? nB : cB + (size_t)(t + 2) * kstep;
;             const char* a3 = a2 + kstep; const char* b3 = b2 + kstep;
;             PG8_LDB(B0, 0, 0); PG8_LDB(B1, 0, 1); PG8_SCHED; PG8_LDA(At, 0, 0); PG8_STAGE(PG8_SA(1, 1), a1 + hstepA, voffA);
;             PG8_WAIT_V(8); PG8_WAIT_L(0); PG8_BAR; PG8_MMA(0, 0, At, B0); PG8_MMA(0, 1, At, B1); PG8_BAR; PG8_SCHED;
;             PG8_LDA(At, 0, 1); PG8_STAGE(PG8_SB(0, 0), b2, voffB); PG8_STAGE(PG8_SB(0, 1), b2 + hstepB, voffB); PG8_STAGE(PG8_SA(0, 0), a2, voffA);
;             PG8_WAIT_V(8); PG8_WAIT_L(0); PG8_BAR; PG8_MMA(1, 0, At, B0); PG8_MMA(1, 1, At, B1); PG8_BAR; PG8_SCHED;
.LBB0_318:
	s_add_u32 s20, s16, 0x100
	s_addc_u32 s21, s17, 0
	s_add_i32 s29, 0, 0x10000
	s_cmp_eq_u32 s80, 2
	s_cselect_b32 s35, s9, s21
	s_cselect_b32 s34, s8, s20
	v_add_u32_e32 v153, s29, v150
	s_cselect_b32 s31, s11, s79
	s_cselect_b32 s30, s10, s78
	s_add_i32 s72, 0, 0x14000
	ds_read_b128 v[154:157], v153
	ds_read_b128 v[158:161], v153 offset:1024
	ds_read_b128 v[162:165], v153 offset:2048
	ds_read_b128 v[166:169], v153 offset:3072
	v_add_u32_e32 v153, s72, v150
	ds_read_b128 v[170:173], v153
	ds_read_b128 v[174:177], v153 offset:1024
	ds_read_b128 v[178:181], v153 offset:2048
	ds_read_b128 v[182:185], v153 offset:3072
	v_lshl_add_u64 v[186:187], s[16:17], 0, v[136:137]
	s_add_i32 m0, s58, 0xc000
	ds_read_b128 v[190:193], v152
	ds_read_b128 v[194:197], v152 offset:1024
	ds_read_b128 v[198:201], v152 offset:2048
	ds_read_b128 v[202:205], v152 offset:3072
	ds_read_b128 v[206:209], v152 offset:4096
	ds_read_b128 v[222:225], v152 offset:5120
	ds_read_b128 v[226:229], v152 offset:6144
	ds_read_b128 v[230:233], v152 offset:7168
	global_load_lds_dwordx4 v[186:187], off
	v_lshl_add_u64 v[186:187], s[16:17], 0, v[138:139]
	s_add_i32 m0, s58, 0xe000
	s_nop 0
	global_load_lds_dwordx4 v[186:187], off
	s_waitcnt vmcnt(8)
	s_waitcnt lgkmcnt(0)
	s_barrier
	s_setprio 1
	s_waitcnt lgkmcnt(0)
	v_mfma_f32_16x16x32_bf16 v[124:127], v[154:157], v[190:193], v[124:127]
	v_mfma_f32_16x16x32_bf16 v[120:123], v[162:165], v[190:193], v[120:123]
	v_mfma_f32_16x16x32_bf16 v[116:119], v[154:157], v[198:201], v[116:119]
	v_mfma_f32_16x16x32_bf16 v[112:115], v[162:165], v[198:201], v[112:115]
	v_mfma_f32_16x16x32_bf16 v[100:103], v[154:157], v[206:209], v[100:103]
	v_mfma_f32_16x16x32_bf16 v[96:99], v[162:165], v[206:209], v[96:99]
	v_mfma_f32_16x16x32_bf16 v[84:87], v[154:157], v[226:229], v[84:87]
	v_mfma_f32_16x16x32_bf16 v[80:83], v[162:165], v[226:229], v[80:83]
	v_mfma_f32_16x16x32_bf16 v[124:127], v[158:161], v[194:197], v[124:127]
	v_mfma_f32_16x16x32_bf16 v[120:123], v[166:169], v[194:197], v[120:123]
	v_mfma_f32_16x16x32_bf16 v[116:119], v[158:161], v[202:205], v[116:119]
	v_mfma_f32_16x16x32_bf16 v[112:115], v[166:169], v[202:205], v[112:115]
	v_mfma_f32_16x16x32_bf16 v[100:103], v[158:161], v[222:225], v[100:103]
	v_mfma_f32_16x16x32_bf16 v[96:99], v[166:169], v[222:225], v[96:99]
	v_mfma_f32_16x16x32_bf16 v[84:87], v[158:161], v[230:233], v[84:87]
	v_mfma_f32_16x16x32_bf16 v[80:83], v[166:169], v[230:233], v[80:83]
	v_mfma_f32_16x16x32_bf16 v[108:111], v[170:173], v[190:193], v[108:111]
	v_mfma_f32_16x16x32_bf16 v[104:107], v[178:181], v[190:193], v[104:107]
	v_mfma_f32_16x16x32_bf16 v[92:95], v[170:173], v[198:201], v[92:95]
	v_mfma_f32_16x16x32_bf16 v[88:91], v[178:181], v[198:201], v[88:91]
	v_mfma_f32_16x16x32_bf16 v[76:79], v[170:173], v[206:209], v[76:79]
	v_mfma_f32_16x16x32_bf16 v[72:75], v[178:181], v[206:209], v[72:75]
	v_mfma_f32_16x16x32_bf16 v[68:71], v[170:173], v[226:229], v[68:71]
	v_mfma_f32_16x16x32_bf16 v[64:67], v[178:181], v[226:229], v[64:67]
	v_mfma_f32_16x16x32_bf16 v[108:111], v[174:177], v[194:197], v[108:111]
	v_mfma_f32_16x16x32_bf16 v[104:107], v[182:185], v[194:197], v[104:107]
	v_mfma_f32_16x16x32_bf16 v[92:95], v[174:177], v[202:205], v[92:95]
	v_mfma_f32_16x16x32_bf16 v[88:91], v[182:185], v[202:205], v[88:91]
	v_mfma_f32_16x16x32_bf16 v[76:79], v[174:177], v[222:225], v[76:79]
	v_mfma_f32_16x16x32_bf16 v[72:75], v[182:185], v[222:225], v[72:75]
	v_mfma_f32_16x16x32_bf16 v[68:71], v[174:177], v[230:233], v[68:71]
	v_mfma_f32_16x16x32_bf16 v[64:67], v[182:185], v[230:233], v[64:67]
	s_setprio 0
	s_barrier
	s_add_i32 s16, s29, s57
	v_lshl_add_u64 v[186:187], s[30:31], 0, v[128:129]
	s_mov_b32 m0, s16
	ds_read_b128 v[190:193], v152 offset:16384
	ds_read_b128 v[194:197], v152 offset:17408
	ds_read_b128 v[198:201], v152 offset:18432
	ds_read_b128 v[202:205], v152 offset:19456
	ds_read_b128 v[206:209], v152 offset:20480
	ds_read_b128 v[222:225], v152 offset:21504
	ds_read_b128 v[226:229], v152 offset:22528
	ds_read_b128 v[230:233], v152 offset:23552
	global_load_lds_dwordx4 v[186:187], off
	s_add_i32 m0, s16, 0x2000
	s_add_u32 s16, s30, 0x18000
	v_lshl_add_u64 v[188:189], s[30:31], 0, v[134:135]
	s_addc_u32 s17, s31, 0
	s_add_i32 s29, s72, s57
	global_load_lds_dwordx4 v[188:189], off
	v_lshl_add_u64 v[210:211], s[16:17], 0, v[128:129]
	s_mov_b32 m0, s29
	v_lshl_add_u64 v[212:213], s[34:35], 0, v[132:133]
	global_load_lds_dwordx4 v[210:211], off
	v_lshl_add_u64 v[210:211], s[16:17], 0, v[134:135]
	s_add_i32 m0, s29, 0x2000
	s_nop 0
	global_load_lds_dwordx4 v[210:211], off
	v_lshl_add_u64 v[210:211], s[34:35], 0, v[130:131]
	s_mov_b32 m0, s58
	s_nop 0
	global_load_lds_dwordx4 v[210:211], off
	s_mov_b32 m0, s59
	s_nop 0
	global_load_lds_dwordx4 v[212:213], off
	s_waitcnt vmcnt(8)
	s_waitcnt lgkmcnt(0)
	s_barrier
; #define PG8_STAGE(bufoff, gbase, voff) do { _Pragma("unroll") for (int _i = 0; _i < 2; ++_i) \
;         __builtin_amdgcn_global_load_lds((const unsigned*)((const char*)(gbase) + (voff)[_i]), (LAS unsigned*)(lds + (bufoff) + ldsw + _i * 8192), 16, 0, 0); } while (0)
; #define PG8_LDA(dst, b, h) do { _Pragma("unroll") for (int m = 0; m < 4; ++m) _Pragma("unroll") for (int k = 0; k < 2; ++k) dst[m][k] = *(const LAS bf16x8*)(lds + PG8_SA(b, h) + aoff + m * 2048 + k * 1024); } while (0)
; #define PG8_LDB(dst, b, h) do { _Pragma("unroll") for (int n = 0; n < 2; ++n) _Pragma("unroll") for (int k = 0; k < 2; ++k) dst[n][k] = *(const LAS bf16x8*)(lds + PG8_SB(b, h) + boff + n * 2048 + k * 1024); } while (0)
; #define PG8_MMA(ai, bj, At, Bt) do { __builtin_amdgcn_s_setprio(1); _Pragma("unroll") for (int m = 0; m < 4; ++m) _Pragma("unroll") for (int n = 0; n < 2; ++n) _Pragma("unroll") for (int k = 0; k < 2; ++k) \
;         acc[ai][bj][m][n] = __builtin_amdgcn_mfma_f32_16x16x32_bf16(Bt[n][k], At[m][k], acc[ai][bj][m][n], 0, 0, 0); __builtin_amdgcn_s_setprio(0); } while (0)
; #define PG8_WAIT_V(n) asm volatile("s_waitcnt vmcnt(" #n ")" ::: "memory")
; #define PG8_WAIT_L(n) asm volatile("s_waitcnt lgkmcnt(" #n ")" ::: "memory")
; #define PG8_BAR __builtin_amdgcn_s_barrier()
; #define PG8_SCHED __builtin_amdgcn_sched_barrier(0)
; template <class Epi, class Sched>
; DI void gemm_phase(LAS unsigned char* lds, const int tid, const int K, const int lda, const int ldb, const Sched& S_, const Epi& E) {
;     ...
;             PG8_WAIT_V(8); PG8_WAIT_L(0); PG8_BAR; PG8_MMA(1, 0, At, B0); PG8_MMA(1, 1, At, B1); PG8_BAR; PG8_SCHED;
;             PG8_LDB(B0, 1, 0); PG8_LDB(B1, 1, 1); PG8_SCHED; PG8_LDA(At, 1, 0); PG8_STAGE(PG8_SA(0, 1), a2 + hstepA, voffA);
;             PG8_WAIT_V(8); PG8_WAIT_L(0); PG8_BAR; PG8_MMA(0, 0, At, B0); PG8_MMA(0, 1, At, B1); PG8_BAR; PG8_SCHED;
	s_setprio 1
	s_waitcnt lgkmcnt(0)
	v_mfma_f32_16x16x32_bf16 v[60:63], v[154:157], v[190:193], v[60:63]
	v_mfma_f32_16x16x32_bf16 v[56:59], v[162:165], v[190:193], v[56:59]
	v_mfma_f32_16x16x32_bf16 v[52:55], v[154:157], v[198:201], v[52:55]
	v_mfma_f32_16x16x32_bf16 v[48:51], v[162:165], v[198:201], v[48:51]
	v_mfma_f32_16x16x32_bf16 v[36:39], v[154:157], v[206:209], v[36:39]
	v_mfma_f32_16x16x32_bf16 v[32:35], v[162:165], v[206:209], v[32:35]
	v_mfma_f32_16x16x32_bf16 v[20:23], v[154:157], v[226:229], v[20:23]
	v_mfma_f32_16x16x32_bf16 v[16:19], v[162:165], v[226:229], v[16:19]
	v_mfma_f32_16x16x32_bf16 v[60:63], v[158:161], v[194:197], v[60:63]
	v_mfma_f32_16x16x32_bf16 v[56:59], v[166:169], v[194:197], v[56:59]
	v_mfma_f32_16x16x32_bf16 v[52:55], v[158:161], v[202:205], v[52:55]
	v_mfma_f32_16x16x32_bf16 v[48:51], v[166:169], v[202:205], v[48:51]
	v_mfma_f32_16x16x32_bf16 v[36:39], v[158:161], v[222:225], v[36:39]
	v_mfma_f32_16x16x32_bf16 v[32:35], v[166:169], v[222:225], v[32:35]
	v_mfma_f32_16x16x32_bf16 v[20:23], v[158:161], v[230:233], v[20:23]
	v_mfma_f32_16x16x32_bf16 v[16:19], v[166:169], v[230:233], v[16:19]
	v_mfma_f32_16x16x32_bf16 v[44:47], v[170:173], v[190:193], v[44:47]
	v_mfma_f32_16x16x32_bf16 v[40:43], v[178:181], v[190:193], v[40:43]
	v_mfma_f32_16x16x32_bf16 v[28:31], v[170:173], v[198:201], v[28:31]
	v_mfma_f32_16x16x32_bf16 v[24:27], v[178:181], v[198:201], v[24:27]
	v_mfma_f32_16x16x32_bf16 v[12:15], v[170:173], v[206:209], v[12:15]
	v_mfma_f32_16x16x32_bf16 v[8:11], v[178:181], v[206:209], v[8:11]
	v_mfma_f32_16x16x32_bf16 v[4:7], v[170:173], v[226:229], v[4:7]
	v_mfma_f32_16x16x32_bf16 v[0:3], v[178:181], v[226:229], v[0:3]
	v_mfma_f32_16x16x32_bf16 v[44:47], v[174:177], v[194:197], v[44:47]
	v_mfma_f32_16x16x32_bf16 v[40:43], v[182:185], v[194:197], v[40:43]
	v_mfma_f32_16x16x32_bf16 v[28:31], v[174:177], v[202:205], v[28:31]
	v_mfma_f32_16x16x32_bf16 v[24:27], v[182:185], v[202:205], v[24:27]
	v_mfma_f32_16x16x32_bf16 v[12:15], v[174:177], v[222:225], v[12:15]
	v_mfma_f32_16x16x32_bf16 v[8:11], v[182:185], v[222:225], v[8:11]
	v_mfma_f32_16x16x32_bf16 v[4:7], v[174:177], v[230:233], v[4:7]
	v_mfma_f32_16x16x32_bf16 v[0:3], v[182:185], v[230:233], v[0:3]
	s_setprio 0
	s_barrier
	s_add_i32 s29, 0, 0x18000
	v_add_u32_e32 v153, s29, v150
	s_add_i32 s72, 0, 0x1c000
	ds_read_b128 v[154:157], v153
	ds_read_b128 v[158:161], v153 offset:1024
	ds_read_b128 v[162:165], v153 offset:2048
	ds_read_b128 v[166:169], v153 offset:3072
	v_add_u32_e32 v153, s72, v150
	ds_read_b128 v[170:173], v153
	ds_read_b128 v[174:177], v153 offset:1024
	ds_read_b128 v[178:181], v153 offset:2048
	ds_read_b128 v[182:185], v153 offset:3072
	s_add_u32 s16, s34, 0x460000
	s_addc_u32 s17, s35, 0
	s_mov_b32 m0, s60
	v_lshl_add_u64 v[214:215], s[16:17], 0, v[130:131]
	ds_read_b128 v[190:193], v152 offset:32768
	ds_read_b128 v[194:197], v152 offset:33792
	ds_read_b128 v[198:201], v152 offset:34816
	ds_read_b128 v[202:205], v152 offset:35840
	ds_read_b128 v[206:209], v152 offset:36864
	ds_read_b128 v[222:225], v152 offset:37888
	ds_read_b128 v[226:229], v152 offset:38912
	ds_read_b128 v[230:233], v152 offset:39936
	global_load_lds_dwordx4 v[214:215], off
	v_lshl_add_u64 v[214:215], s[16:17], 0, v[132:133]
	s_mov_b32 m0, s61
	s_nop 0
	global_load_lds_dwordx4 v[214:215], off
	s_waitcnt vmcnt(8)
	s_waitcnt lgkmcnt(0)
	s_barrier
	s_setprio 1
	s_waitcnt lgkmcnt(0)
	v_mfma_f32_16x16x32_bf16 v[124:127], v[154:157], v[190:193], v[124:127]
	v_mfma_f32_16x16x32_bf16 v[120:123], v[162:165], v[190:193], v[120:123]
	v_mfma_f32_16x16x32_bf16 v[116:119], v[154:157], v[198:201], v[116:119]
	v_mfma_f32_16x16x32_bf16 v[112:115], v[162:165], v[198:201], v[112:115]
	v_mfma_f32_16x16x32_bf16 v[100:103], v[154:157], v[206:209], v[100:103]
	v_mfma_f32_16x16x32_bf16 v[96:99], v[162:165], v[206:209], v[96:99]
	v_mfma_f32_16x16x32_bf16 v[84:87], v[154:157], v[226:229], v[84:87]
	v_mfma_f32_16x16x32_bf16 v[80:83], v[162:165], v[226:229], v[80:83]
	v_mfma_f32_16x16x32_bf16 v[124:127], v[158:161], v[194:197], v[124:127]
	v_mfma_f32_16x16x32_bf16 v[120:123], v[166:169], v[194:197], v[120:123]
	v_mfma_f32_16x16x32_bf16 v[116:119], v[158:161], v[202:205], v[116:119]
	v_mfma_f32_16x16x32_bf16 v[112:115], v[166:169], v[202:205], v[112:115]
	v_mfma_f32_16x16x32_bf16 v[100:103], v[158:161], v[222:225], v[100:103]
	v_mfma_f32_16x16x32_bf16 v[96:99], v[166:169], v[222:225], v[96:99]
	v_mfma_f32_16x16x32_bf16 v[84:87], v[158:161], v[230:233], v[84:87]
	v_mfma_f32_16x16x32_bf16 v[80:83], v[166:169], v[230:233], v[80:83]
	v_mfma_f32_16x16x32_bf16 v[108:111], v[170:173], v[190:193], v[108:111]
	v_mfma_f32_16x16x32_bf16 v[104:107], v[178:181], v[190:193], v[104:107]
	v_mfma_f32_16x16x32_bf16 v[92:95], v[170:173], v[198:201], v[92:95]
	v_mfma_f32_16x16x32_bf16 v[88:91], v[178:181], v[198:201], v[88:91]
	v_mfma_f32_16x16x32_bf16 v[76:79], v[170:173], v[206:209], v[76:79]
	v_mfma_f32_16x16x32_bf16 v[72:75], v[178:181], v[206:209], v[72:75]
	v_mfma_f32_16x16x32_bf16 v[68:71], v[170:173], v[226:229], v[68:71]
	v_mfma_f32_16x16x32_bf16 v[64:67], v[178:181], v[226:229], v[64:67]
	v_mfma_f32_16x16x32_bf16 v[108:111], v[174:177], v[194:197], v[108:111]
	v_mfma_f32_16x16x32_bf16 v[104:107], v[182:185], v[194:197], v[104:107]
	v_mfma_f32_16x16x32_bf16 v[92:95], v[174:177], v[202:205], v[92:95]
	v_mfma_f32_16x16x32_bf16 v[88:91], v[182:185], v[202:205], v[88:91]
	v_mfma_f32_16x16x32_bf16 v[76:79], v[174:177], v[222:225], v[76:79]
	v_mfma_f32_16x16x32_bf16 v[72:75], v[182:185], v[222:225], v[72:75]
	v_mfma_f32_16x16x32_bf16 v[68:71], v[174:177], v[230:233], v[68:71]
	v_mfma_f32_16x16x32_bf16 v[64:67], v[182:185], v[230:233], v[64:67]
	s_setprio 0
	s_barrier
; #define PG8_STAGE(bufoff, gbase, voff) do { _Pragma("unroll") for (int _i = 0; _i < 2; ++_i) \
;         __builtin_amdgcn_global_load_lds((const unsigned*)((const char*)(gbase) + (voff)[_i]), (LAS unsigned*)(lds + (bufoff) + ldsw + _i * 8192), 16, 0, 0); } while (0)
; #define PG8_LDA(dst, b, h) do { _Pragma("unroll") for (int m = 0; m < 4; ++m) _Pragma("unroll") for (int k = 0; k < 2; ++k) dst[m][k] = *(const LAS bf16x8*)(lds + PG8_SA(b, h) + aoff + m * 2048 + k * 1024); } while (0)
; #define PG8_MMA(ai, bj, At, Bt) do { __builtin_amdgcn_s_setprio(1); _Pragma("unroll") for (int m = 0; m < 4; ++m) _Pragma("unroll") for (int n = 0; n < 2; ++n) _Pragma("unroll") for (int k = 0; k < 2; ++k) \
;         acc[ai][bj][m][n] = __builtin_amdgcn_mfma_f32_16x16x32_bf16(Bt[n][k], At[m][k], acc[ai][bj][m][n], 0, 0, 0); __builtin_amdgcn_s_setprio(0); } while (0)
; #define PG8_WAIT_V(n) asm volatile("s_waitcnt vmcnt(" #n ")" ::: "memory")
; #define PG8_WAIT_L(n) asm volatile("s_waitcnt lgkmcnt(" #n ")" ::: "memory")
; #define PG8_BAR __builtin_amdgcn_s_barrier()
; #define PG8_SCHED __builtin_amdgcn_sched_barrier(0)
; template <class Epi, class Sched>
; DI void gemm_phase(LAS unsigned char* lds, const int tid, const int K, const int lda, const int ldb, const Sched& S_, const Epi& E) {
;     ...
;             PG8_LDA(At, 1, 1); PG8_STAGE(PG8_SB(1, 0), b3, voffB); PG8_STAGE(PG8_SB(1, 1), b3 + hstepB, voffB); PG8_STAGE(PG8_SA(1, 0), a3, voffA);
;             PG8_WAIT_V(8); PG8_WAIT_L(0); PG8_BAR; PG8_MMA(1, 0, At, B0); PG8_MMA(1, 1, At, B1); PG8_BAR; PG8_SCHED;
;             if constexpr (Epi::HOOK) { if (((t + 2) & 7) == 0 && !last) { E.hook(acc, cur, (t + 2) >> 3, wr, wc, fr, fq); PG8_SCHED; } }
;         }
	s_add_i32 s16, s29, s57
	v_lshl_add_u64 v[186:187], v[186:187], 0, s[94:95]
	s_mov_b32 m0, s16
	ds_read_b128 v[190:193], v152 offset:49152
	ds_read_b128 v[194:197], v152 offset:50176
	ds_read_b128 v[198:201], v152 offset:51200
	ds_read_b128 v[202:205], v152 offset:52224
	ds_read_b128 v[206:209], v152 offset:53248
	ds_read_b128 v[222:225], v152 offset:54272
	ds_read_b128 v[226:229], v152 offset:55296
	ds_read_b128 v[230:233], v152 offset:56320
	global_load_lds_dwordx4 v[186:187], off
	s_add_i32 m0, s16, 0x2000
	s_add_u32 s16, s30, 0x18080
	v_lshl_add_u64 v[186:187], v[188:189], 0, s[94:95]
	s_addc_u32 s17, s31, 0
	s_add_i32 s29, s72, s57
	global_load_lds_dwordx4 v[186:187], off
	v_lshl_add_u64 v[186:187], s[16:17], 0, v[128:129]
	s_mov_b32 m0, s29
	s_nop 0
	global_load_lds_dwordx4 v[186:187], off
	v_lshl_add_u64 v[186:187], s[16:17], 0, v[134:135]
	s_add_i32 m0, s29, 0x2000
	s_nop 0
	global_load_lds_dwordx4 v[186:187], off
	v_lshl_add_u64 v[186:187], v[210:211], 0, s[94:95]
	s_mov_b32 m0, s62
	s_nop 0
	global_load_lds_dwordx4 v[186:187], off
	v_lshl_add_u64 v[186:187], v[212:213], 0, s[94:95]
	s_mov_b32 m0, s63
	s_nop 0
	global_load_lds_dwordx4 v[186:187], off
	s_waitcnt vmcnt(8)
	s_waitcnt lgkmcnt(0)
	s_barrier
	s_setprio 1
	s_waitcnt lgkmcnt(0)
	v_mfma_f32_16x16x32_bf16 v[60:63], v[154:157], v[190:193], v[60:63]
	v_mfma_f32_16x16x32_bf16 v[56:59], v[162:165], v[190:193], v[56:59]
	v_mfma_f32_16x16x32_bf16 v[52:55], v[154:157], v[198:201], v[52:55]
	v_mfma_f32_16x16x32_bf16 v[48:51], v[162:165], v[198:201], v[48:51]
	v_mfma_f32_16x16x32_bf16 v[36:39], v[154:157], v[206:209], v[36:39]
	v_mfma_f32_16x16x32_bf16 v[32:35], v[162:165], v[206:209], v[32:35]
	v_mfma_f32_16x16x32_bf16 v[20:23], v[154:157], v[226:229], v[20:23]
	v_mfma_f32_16x16x32_bf16 v[16:19], v[162:165], v[226:229], v[16:19]
	v_mfma_f32_16x16x32_bf16 v[60:63], v[158:161], v[194:197], v[60:63]
	v_mfma_f32_16x16x32_bf16 v[56:59], v[166:169], v[194:197], v[56:59]
	v_mfma_f32_16x16x32_bf16 v[52:55], v[158:161], v[202:205], v[52:55]
	v_mfma_f32_16x16x32_bf16 v[48:51], v[166:169], v[202:205], v[48:51]
	v_mfma_f32_16x16x32_bf16 v[36:39], v[158:161], v[222:225], v[36:39]
	v_mfma_f32_16x16x32_bf16 v[32:35], v[166:169], v[222:225], v[32:35]
	v_mfma_f32_16x16x32_bf16 v[20:23], v[158:161], v[230:233], v[20:23]
	v_mfma_f32_16x16x32_bf16 v[16:19], v[166:169], v[230:233], v[16:19]
	v_mfma_f32_16x16x32_bf16 v[44:47], v[170:173], v[190:193], v[44:47]
	v_mfma_f32_16x16x32_bf16 v[40:43], v[178:181], v[190:193], v[40:43]
	v_mfma_f32_16x16x32_bf16 v[28:31], v[170:173], v[198:201], v[28:31]
	v_mfma_f32_16x16x32_bf16 v[24:27], v[178:181], v[198:201], v[24:27]
	v_mfma_f32_16x16x32_bf16 v[12:15], v[170:173], v[206:209], v[12:15]
	v_mfma_f32_16x16x32_bf16 v[8:11], v[178:181], v[206:209], v[8:11]
	v_mfma_f32_16x16x32_bf16 v[4:7], v[170:173], v[226:229], v[4:7]
	v_mfma_f32_16x16x32_bf16 v[0:3], v[178:181], v[226:229], v[0:3]
	v_mfma_f32_16x16x32_bf16 v[44:47], v[174:177], v[194:197], v[44:47]
	v_mfma_f32_16x16x32_bf16 v[40:43], v[182:185], v[194:197], v[40:43]
	v_mfma_f32_16x16x32_bf16 v[28:31], v[174:177], v[202:205], v[28:31]
	v_mfma_f32_16x16x32_bf16 v[24:27], v[182:185], v[202:205], v[24:27]
	v_mfma_f32_16x16x32_bf16 v[12:15], v[174:177], v[222:225], v[12:15]
	v_mfma_f32_16x16x32_bf16 v[8:11], v[182:185], v[222:225], v[8:11]
	v_mfma_f32_16x16x32_bf16 v[4:7], v[174:177], v[230:233], v[4:7]
	v_mfma_f32_16x16x32_bf16 v[0:3], v[182:185], v[230:233], v[0:3]
	s_setprio 0
	s_barrier
	s_add_i32 s80, s80, 2
	s_add_u32 s78, s78, 0x100
	s_addc_u32 s79, s79, 0
	s_cmp_gt_u32 s80, 3
	s_mov_b64 s[16:17], s[20:21]
	s_cbranch_scc0 .LBB0_318
	s_and_b64 vcc, exec, s[6:7]
	s_cbranch_vccz .LBB0_321
	s_barrier

; #define PG8_STAGE(bufoff, gbase, voff) do { _Pragma("unroll") for (int _i = 0; _i < 2; ++_i) \
;         __builtin_amdgcn_global_load_lds((const unsigned*)((const char*)(gbase) + (voff)[_i]), (LAS unsigned*)(lds + (bufoff) + ldsw + _i * 8192), 16, 0, 0); } while (0)
; #define PG8_LDA(dst, b, h) do { _Pragma("unroll") for (int m = 0; m < 4; ++m) _Pragma("unroll") for (int k = 0; k < 2; ++k) dst[m][k] = *(const LAS bf16x8*)(lds + PG8_SA(b, h) + aoff + m * 2048 + k * 1024); } while (0)
; #define PG8_LDB(dst, b, h) do { _Pragma("unroll") for (int n = 0; n < 2; ++n) _Pragma("unroll") for (int k = 0; k < 2; ++k) dst[n][k] = *(const LAS bf16x8*)(lds + PG8_SB(b, h) + boff + n * 2048 + k * 1024); } while (0)
; #define PG8_MMA(ai, bj, At, Bt) do { __builtin_amdgcn_s_setprio(1); _Pragma("unroll") for (int m = 0; m < 4; ++m) _Pragma("unroll") for (int n = 0; n < 2; ++n) _Pragma("unroll") for (int k = 0; k < 2; ++k) \
;         acc[ai][bj][m][n] = __builtin_amdgcn_mfma_f32_16x16x32_bf16(Bt[n][k], At[m][k], acc[ai][bj][m][n], 0, 0, 0); __builtin_amdgcn_s_setprio(0); } while (0)
; #define PG8_WAIT_V(n) asm volatile("s_waitcnt vmcnt(" #n ")" ::: "memory")
; #define PG8_BAR __builtin_amdgcn_s_barrier()
; template <class Epi, class Sched>
; DI void gemm_phase(LAS unsigned char* lds, const int tid, const int K, const int lda, const int ldb, const Sched& S_, const Epi& E) {
;     ...
;         const bool has_next = S_.next(ui + 1, nxt);
;         const char* nA = has_next ? nxt.a : cA; const char* nB = has_next ? nxt.b : cB;
;         for (int t = 0; t < nt; t += 2) {
;             const bool last = (t == nt - 2);
;             const char* a1 = cA + (size_t)(t + 1) * kstep;
;             const char* a2 = last ? nA : cA + (size_t)(t + 2) * kstep; const char* b2 = last ? nB : cB + (size_t)(t + 2) * kstep;
;             const char* a3 = a2 + kstep; const char* b3 = b2 + kstep;
;             PG8_LDB(B0, 0, 0); PG8_LDB(B1, 0, 1); PG8_SCHED; PG8_LDA(At, 0, 0); PG8_STAGE(PG8_SA(1, 1), a1 + hstepA, voffA);
;             PG8_WAIT_V(8); PG8_WAIT_L(0); PG8_BAR; PG8_MMA(0, 0, At, B0); PG8_MMA(0, 1, At, B1); PG8_BAR; PG8_SCHED;
;             PG8_LDA(At, 0, 1); PG8_STAGE(PG8_SB(0, 0), b2, voffB); PG8_STAGE(PG8_SB(0, 1), b2 + hstepB, voffB); PG8_STAGE(PG8_SA(0, 0), a2, voffA);
;             PG8_WAIT_V(8); PG8_WAIT_L(0); PG8_BAR; PG8_MMA(1, 0, At, B0); PG8_MMA(1, 1, At, B1); PG8_BAR; PG8_SCHED;
.LBB0_342:
	s_add_u32 s29, s20, s9
	s_addc_u32 s58, s21, 0
	s_add_u32 s54, s29, 0x100
	s_addc_u32 s55, s58, 0
	s_and_b64 s[52:53], s[50:51], exec
	s_cselect_b32 s55, s11, s55
	s_cselect_b32 s54, s10, s54
	s_add_u32 s9, s30, s9
	s_addc_u32 s52, s31, 0
	s_add_u32 s9, s9, 0x100
	s_addc_u32 s52, s52, 0
	s_add_i32 s72, 0, 0x10000
	s_and_b64 s[50:51], s[50:51], exec
	s_cselect_b32 s57, s17, s52
	s_cselect_b32 s56, s16, s9
	s_add_i32 s51, 0, 0x14000
	s_add_u32 s60, s29, 0x460080
	s_addc_u32 s61, s58, 0
	s_add_i32 s91, s72, s77
	s_add_i32 m0, s36, 0xc000
	s_add_i32 s78, s36, 0xe000
	s_add_i32 s88, s91, 0x2000
	s_add_u32 s58, s56, 0x10000
	v_add_u32_e32 v152, s72, v137
	v_add_u32_e32 v168, s51, v137
	s_addc_u32 s59, s57, 0
	s_add_i32 s89, s51, s77
	ds_read_b128 v[140:143], v152
	ds_read_b128 v[144:147], v152 offset:1024
	ds_read_b128 v[148:151], v152 offset:2048
	ds_read_b128 v[152:155], v152 offset:3072
	ds_read_b128 v[156:159], v168
	ds_read_b128 v[160:163], v168 offset:1024
	ds_read_b128 v[164:167], v168 offset:2048
	ds_read_b128 v[168:171], v168 offset:3072
	s_add_i32 s90, s89, 0x2000
	s_add_i32 vcc_hi, 0, 0x18000
	s_add_i32 vcc_lo, 0, 0x1c000
	s_add_u32 s52, s54, 0x460000
	s_addc_u32 s53, s55, 0
	s_add_i32 s87, vcc_hi, s77
	s_add_i32 s9, s87, 0x2000
	s_add_u32 s50, s56, 0x10080
	s_addc_u32 s51, s57, 0
	s_add_i32 s72, vcc_lo, s77
	s_add_i32 s29, s72, 0x2000
	v_lshl_add_u64 v[184:185], s[60:61], 0, v[130:131]
	ds_read_b128 v[172:175], v139
	ds_read_b128 v[176:179], v139 offset:1024
	ds_read_b128 v[180:183], v139 offset:2048
	ds_read_b128 v[190:193], v139 offset:3072
	ds_read_b128 v[194:197], v139 offset:4096
	ds_read_b128 v[198:201], v139 offset:5120
	ds_read_b128 v[202:205], v139 offset:6144
	ds_read_b128 v[206:209], v139 offset:7168
	global_load_lds_dwordx4 v[184:185], off
	v_lshl_add_u64 v[184:185], s[60:61], 0, v[132:133]
	s_mov_b32 m0, s78
	s_nop 0
	global_load_lds_dwordx4 v[184:185], off
	s_waitcnt vmcnt(8)
	s_waitcnt lgkmcnt(0)
	s_barrier
	s_setprio 1
	s_waitcnt lgkmcnt(0)
	v_mfma_f32_16x16x32_bf16 v[124:127], v[140:143], v[172:175], v[124:127]
	v_mfma_f32_16x16x32_bf16 v[120:123], v[148:151], v[172:175], v[120:123]
	v_mfma_f32_16x16x32_bf16 v[116:119], v[140:143], v[180:183], v[116:119]
	v_mfma_f32_16x16x32_bf16 v[112:115], v[148:151], v[180:183], v[112:115]
	v_mfma_f32_16x16x32_bf16 v[100:103], v[140:143], v[194:197], v[100:103]
	v_mfma_f32_16x16x32_bf16 v[96:99], v[148:151], v[194:197], v[96:99]
	v_mfma_f32_16x16x32_bf16 v[84:87], v[140:143], v[202:205], v[84:87]
	v_mfma_f32_16x16x32_bf16 v[80:83], v[148:151], v[202:205], v[80:83]
	v_mfma_f32_16x16x32_bf16 v[124:127], v[144:147], v[176:179], v[124:127]
	v_mfma_f32_16x16x32_bf16 v[120:123], v[152:155], v[176:179], v[120:123]
	v_mfma_f32_16x16x32_bf16 v[116:119], v[144:147], v[190:193], v[116:119]
	v_mfma_f32_16x16x32_bf16 v[112:115], v[152:155], v[190:193], v[112:115]
	v_mfma_f32_16x16x32_bf16 v[100:103], v[144:147], v[198:201], v[100:103]
	v_mfma_f32_16x16x32_bf16 v[96:99], v[152:155], v[198:201], v[96:99]
	v_mfma_f32_16x16x32_bf16 v[84:87], v[144:147], v[206:209], v[84:87]
	v_mfma_f32_16x16x32_bf16 v[80:83], v[152:155], v[206:209], v[80:83]
	v_mfma_f32_16x16x32_bf16 v[108:111], v[156:159], v[172:175], v[108:111]
	v_mfma_f32_16x16x32_bf16 v[104:107], v[164:167], v[172:175], v[104:107]
	v_mfma_f32_16x16x32_bf16 v[92:95], v[156:159], v[180:183], v[92:95]
	v_mfma_f32_16x16x32_bf16 v[88:91], v[164:167], v[180:183], v[88:91]
	v_mfma_f32_16x16x32_bf16 v[76:79], v[156:159], v[194:197], v[76:79]
	v_mfma_f32_16x16x32_bf16 v[72:75], v[164:167], v[194:197], v[72:75]
	v_mfma_f32_16x16x32_bf16 v[68:71], v[156:159], v[202:205], v[68:71]
	v_mfma_f32_16x16x32_bf16 v[64:67], v[164:167], v[202:205], v[64:67]
	v_mfma_f32_16x16x32_bf16 v[108:111], v[160:163], v[176:179], v[108:111]
	v_mfma_f32_16x16x32_bf16 v[104:107], v[168:171], v[176:179], v[104:107]
	v_mfma_f32_16x16x32_bf16 v[92:95], v[160:163], v[190:193], v[92:95]
	v_mfma_f32_16x16x32_bf16 v[88:91], v[168:171], v[190:193], v[88:91]
	v_mfma_f32_16x16x32_bf16 v[76:79], v[160:163], v[198:201], v[76:79]
	v_mfma_f32_16x16x32_bf16 v[72:75], v[168:171], v[198:201], v[72:75]
	v_mfma_f32_16x16x32_bf16 v[68:71], v[160:163], v[206:209], v[68:71]
	v_mfma_f32_16x16x32_bf16 v[64:67], v[168:171], v[206:209], v[64:67]
	s_setprio 0
	s_barrier
	s_mov_b32 m0, s91
	v_lshl_add_u64 v[184:185], s[56:57], 0, v[128:129]
	ds_read_b128 v[172:175], v139 offset:16384
	ds_read_b128 v[176:179], v139 offset:17408
	ds_read_b128 v[180:183], v139 offset:18432
	ds_read_b128 v[190:193], v139 offset:19456
	ds_read_b128 v[194:197], v139 offset:20480
	ds_read_b128 v[198:201], v139 offset:21504
	ds_read_b128 v[202:205], v139 offset:22528
	ds_read_b128 v[206:209], v139 offset:23552
	global_load_lds_dwordx4 v[184:185], off
	v_lshl_add_u64 v[186:187], s[56:57], 0, v[134:135]
	s_mov_b32 m0, s88
	v_lshl_add_u64 v[188:189], s[58:59], 0, v[128:129]
	global_load_lds_dwordx4 v[186:187], off
	s_mov_b32 m0, s89
	v_lshl_add_u64 v[210:211], s[54:55], 0, v[132:133]
	global_load_lds_dwordx4 v[188:189], off
	v_lshl_add_u64 v[188:189], s[58:59], 0, v[134:135]
	s_mov_b32 m0, s90
	s_nop 0
	global_load_lds_dwordx4 v[188:189], off
	v_lshl_add_u64 v[188:189], s[54:55], 0, v[130:131]
	s_mov_b32 m0, s36
	s_nop 0
	global_load_lds_dwordx4 v[188:189], off
	s_mov_b32 m0, s79
	s_nop 0
	global_load_lds_dwordx4 v[210:211], off
	s_waitcnt vmcnt(8)
	s_waitcnt lgkmcnt(0)
	s_barrier
; #define PG8_STAGE(bufoff, gbase, voff) do { _Pragma("unroll") for (int _i = 0; _i < 2; ++_i) \
;         __builtin_amdgcn_global_load_lds((const unsigned*)((const char*)(gbase) + (voff)[_i]), (LAS unsigned*)(lds + (bufoff) + ldsw + _i * 8192), 16, 0, 0); } while (0)
; #define PG8_LDA(dst, b, h) do { _Pragma("unroll") for (int m = 0; m < 4; ++m) _Pragma("unroll") for (int k = 0; k < 2; ++k) dst[m][k] = *(const LAS bf16x8*)(lds + PG8_SA(b, h) + aoff + m * 2048 + k * 1024); } while (0)
; #define PG8_LDB(dst, b, h) do { _Pragma("unroll") for (int n = 0; n < 2; ++n) _Pragma("unroll") for (int k = 0; k < 2; ++k) dst[n][k] = *(const LAS bf16x8*)(lds + PG8_SB(b, h) + boff + n * 2048 + k * 1024); } while (0)
; #define PG8_MMA(ai, bj, At, Bt) do { __builtin_amdgcn_s_setprio(1); _Pragma("unroll") for (int m = 0; m < 4; ++m) _Pragma("unroll") for (int n = 0; n < 2; ++n) _Pragma("unroll") for (int k = 0; k < 2; ++k) \
;         acc[ai][bj][m][n] = __builtin_amdgcn_mfma_f32_16x16x32_bf16(Bt[n][k], At[m][k], acc[ai][bj][m][n], 0, 0, 0); __builtin_amdgcn_s_setprio(0); } while (0)
; #define PG8_WAIT_V(n) asm volatile("s_waitcnt vmcnt(" #n ")" ::: "memory")
; #define PG8_WAIT_L(n) asm volatile("s_waitcnt lgkmcnt(" #n ")" ::: "memory")
; #define PG8_BAR __builtin_amdgcn_s_barrier()
; #define PG8_SCHED __builtin_amdgcn_sched_barrier(0)
; template <class Epi, class Sched>
; DI void gemm_phase(LAS unsigned char* lds, const int tid, const int K, const int lda, const int ldb, const Sched& S_, const Epi& E) {
;     ...
;             PG8_WAIT_V(8); PG8_WAIT_L(0); PG8_BAR; PG8_MMA(1, 0, At, B0); PG8_MMA(1, 1, At, B1); PG8_BAR; PG8_SCHED;
;             PG8_LDB(B0, 1, 0); PG8_LDB(B1, 1, 1); PG8_SCHED; PG8_LDA(At, 1, 0); PG8_STAGE(PG8_SA(0, 1), a2 + hstepA, voffA);
;             PG8_WAIT_V(8); PG8_WAIT_L(0); PG8_BAR; PG8_MMA(0, 0, At, B0); PG8_MMA(0, 1, At, B1); PG8_BAR; PG8_SCHED;
	s_setprio 1
	s_waitcnt lgkmcnt(0)
	v_mfma_f32_16x16x32_bf16 v[60:63], v[140:143], v[172:175], v[60:63]
	v_mfma_f32_16x16x32_bf16 v[56:59], v[148:151], v[172:175], v[56:59]
	v_mfma_f32_16x16x32_bf16 v[52:55], v[140:143], v[180:183], v[52:55]
	v_mfma_f32_16x16x32_bf16 v[48:51], v[148:151], v[180:183], v[48:51]
	v_mfma_f32_16x16x32_bf16 v[36:39], v[140:143], v[194:197], v[36:39]
	v_mfma_f32_16x16x32_bf16 v[32:35], v[148:151], v[194:197], v[32:35]
	v_mfma_f32_16x16x32_bf16 v[20:23], v[140:143], v[202:205], v[20:23]
	v_mfma_f32_16x16x32_bf16 v[16:19], v[148:151], v[202:205], v[16:19]
	v_mfma_f32_16x16x32_bf16 v[60:63], v[144:147], v[176:179], v[60:63]
	v_mfma_f32_16x16x32_bf16 v[56:59], v[152:155], v[176:179], v[56:59]
	v_mfma_f32_16x16x32_bf16 v[52:55], v[144:147], v[190:193], v[52:55]
	v_mfma_f32_16x16x32_bf16 v[48:51], v[152:155], v[190:193], v[48:51]
	v_mfma_f32_16x16x32_bf16 v[36:39], v[144:147], v[198:201], v[36:39]
	v_mfma_f32_16x16x32_bf16 v[32:35], v[152:155], v[198:201], v[32:35]
	v_mfma_f32_16x16x32_bf16 v[20:23], v[144:147], v[206:209], v[20:23]
	v_mfma_f32_16x16x32_bf16 v[16:19], v[152:155], v[206:209], v[16:19]
	v_mfma_f32_16x16x32_bf16 v[44:47], v[156:159], v[172:175], v[44:47]
	v_mfma_f32_16x16x32_bf16 v[40:43], v[164:167], v[172:175], v[40:43]
	v_mfma_f32_16x16x32_bf16 v[28:31], v[156:159], v[180:183], v[28:31]
	v_mfma_f32_16x16x32_bf16 v[24:27], v[164:167], v[180:183], v[24:27]
	v_mfma_f32_16x16x32_bf16 v[12:15], v[156:159], v[194:197], v[12:15]
	v_mfma_f32_16x16x32_bf16 v[8:11], v[164:167], v[194:197], v[8:11]
	v_mfma_f32_16x16x32_bf16 v[4:7], v[156:159], v[202:205], v[4:7]
	v_mfma_f32_16x16x32_bf16 v[0:3], v[164:167], v[202:205], v[0:3]
	v_mfma_f32_16x16x32_bf16 v[44:47], v[160:163], v[176:179], v[44:47]
	v_mfma_f32_16x16x32_bf16 v[40:43], v[168:171], v[176:179], v[40:43]
	v_mfma_f32_16x16x32_bf16 v[28:31], v[160:163], v[190:193], v[28:31]
	v_mfma_f32_16x16x32_bf16 v[24:27], v[168:171], v[190:193], v[24:27]
	v_mfma_f32_16x16x32_bf16 v[12:15], v[160:163], v[198:201], v[12:15]
	v_mfma_f32_16x16x32_bf16 v[8:11], v[168:171], v[198:201], v[8:11]
	v_mfma_f32_16x16x32_bf16 v[4:7], v[160:163], v[206:209], v[4:7]
	v_mfma_f32_16x16x32_bf16 v[0:3], v[168:171], v[206:209], v[0:3]
	s_setprio 0
	s_barrier
	v_add_u32_e32 v152, vcc_hi, v137
	v_add_u32_e32 v168, vcc_lo, v137
	ds_read_b128 v[140:143], v152
	ds_read_b128 v[144:147], v152 offset:1024
	ds_read_b128 v[148:151], v152 offset:2048
	ds_read_b128 v[152:155], v152 offset:3072
	ds_read_b128 v[156:159], v168
	ds_read_b128 v[160:163], v168 offset:1024
	ds_read_b128 v[164:167], v168 offset:2048
	ds_read_b128 v[168:171], v168 offset:3072
	s_mov_b32 m0, s80
	v_lshl_add_u64 v[212:213], s[52:53], 0, v[130:131]
	ds_read_b128 v[172:175], v139 offset:32768
	ds_read_b128 v[176:179], v139 offset:33792
	ds_read_b128 v[180:183], v139 offset:34816
	ds_read_b128 v[190:193], v139 offset:35840
	ds_read_b128 v[194:197], v139 offset:36864
	ds_read_b128 v[198:201], v139 offset:37888
	ds_read_b128 v[202:205], v139 offset:38912
	ds_read_b128 v[206:209], v139 offset:39936
	global_load_lds_dwordx4 v[212:213], off
	v_lshl_add_u64 v[212:213], s[52:53], 0, v[132:133]
	s_mov_b32 m0, s81
	s_nop 0
	global_load_lds_dwordx4 v[212:213], off
	s_waitcnt vmcnt(8)
	s_waitcnt lgkmcnt(0)
	s_barrier
	s_setprio 1
	s_waitcnt lgkmcnt(0)
	v_mfma_f32_16x16x32_bf16 v[124:127], v[140:143], v[172:175], v[124:127]
	v_mfma_f32_16x16x32_bf16 v[120:123], v[148:151], v[172:175], v[120:123]
	v_mfma_f32_16x16x32_bf16 v[116:119], v[140:143], v[180:183], v[116:119]
	v_mfma_f32_16x16x32_bf16 v[112:115], v[148:151], v[180:183], v[112:115]
	v_mfma_f32_16x16x32_bf16 v[100:103], v[140:143], v[194:197], v[100:103]
	v_mfma_f32_16x16x32_bf16 v[96:99], v[148:151], v[194:197], v[96:99]
	v_mfma_f32_16x16x32_bf16 v[84:87], v[140:143], v[202:205], v[84:87]
	v_mfma_f32_16x16x32_bf16 v[80:83], v[148:151], v[202:205], v[80:83]
	v_mfma_f32_16x16x32_bf16 v[124:127], v[144:147], v[176:179], v[124:127]
	v_mfma_f32_16x16x32_bf16 v[120:123], v[152:155], v[176:179], v[120:123]
	v_mfma_f32_16x16x32_bf16 v[116:119], v[144:147], v[190:193], v[116:119]
	v_mfma_f32_16x16x32_bf16 v[112:115], v[152:155], v[190:193], v[112:115]
	v_mfma_f32_16x16x32_bf16 v[100:103], v[144:147], v[198:201], v[100:103]
	v_mfma_f32_16x16x32_bf16 v[96:99], v[152:155], v[198:201], v[96:99]
	v_mfma_f32_16x16x32_bf16 v[84:87], v[144:147], v[206:209], v[84:87]
	v_mfma_f32_16x16x32_bf16 v[80:83], v[152:155], v[206:209], v[80:83]
	v_mfma_f32_16x16x32_bf16 v[108:111], v[156:159], v[172:175], v[108:111]
	v_mfma_f32_16x16x32_bf16 v[104:107], v[164:167], v[172:175], v[104:107]
	v_mfma_f32_16x16x32_bf16 v[92:95], v[156:159], v[180:183], v[92:95]
	v_mfma_f32_16x16x32_bf16 v[88:91], v[164:167], v[180:183], v[88:91]
	v_mfma_f32_16x16x32_bf16 v[76:79], v[156:159], v[194:197], v[76:79]
	v_mfma_f32_16x16x32_bf16 v[72:75], v[164:167], v[194:197], v[72:75]
	v_mfma_f32_16x16x32_bf16 v[68:71], v[156:159], v[202:205], v[68:71]
	v_mfma_f32_16x16x32_bf16 v[64:67], v[164:167], v[202:205], v[64:67]
	v_mfma_f32_16x16x32_bf16 v[108:111], v[160:163], v[176:179], v[108:111]
	v_mfma_f32_16x16x32_bf16 v[104:107], v[168:171], v[176:179], v[104:107]
	v_mfma_f32_16x16x32_bf16 v[92:95], v[160:163], v[190:193], v[92:95]
	v_mfma_f32_16x16x32_bf16 v[88:91], v[168:171], v[190:193], v[88:91]
	v_mfma_f32_16x16x32_bf16 v[76:79], v[160:163], v[198:201], v[76:79]
	v_mfma_f32_16x16x32_bf16 v[72:75], v[168:171], v[198:201], v[72:75]
	v_mfma_f32_16x16x32_bf16 v[68:71], v[160:163], v[206:209], v[68:71]
	v_mfma_f32_16x16x32_bf16 v[64:67], v[168:171], v[206:209], v[64:67]
	s_setprio 0
	s_barrier
; #define PG8_STAGE(bufoff, gbase, voff) do { _Pragma("unroll") for (int _i = 0; _i < 2; ++_i) \
;         __builtin_amdgcn_global_load_lds((const unsigned*)((const char*)(gbase) + (voff)[_i]), (LAS unsigned*)(lds + (bufoff) + ldsw + _i * 8192), 16, 0, 0); } while (0)
; #define PG8_LDA(dst, b, h) do { _Pragma("unroll") for (int m = 0; m < 4; ++m) _Pragma("unroll") for (int k = 0; k < 2; ++k) dst[m][k] = *(const LAS bf16x8*)(lds + PG8_SA(b, h) + aoff + m * 2048 + k * 1024); } while (0)
; #define PG8_MMA(ai, bj, At, Bt) do { __builtin_amdgcn_s_setprio(1); _Pragma("unroll") for (int m = 0; m < 4; ++m) _Pragma("unroll") for (int n = 0; n < 2; ++n) _Pragma("unroll") for (int k = 0; k < 2; ++k) \
;         acc[ai][bj][m][n] = __builtin_amdgcn_mfma_f32_16x16x32_bf16(Bt[n][k], At[m][k], acc[ai][bj][m][n], 0, 0, 0); __builtin_amdgcn_s_setprio(0); } while (0)
; #define PG8_WAIT_V(n) asm volatile("s_waitcnt vmcnt(" #n ")" ::: "memory")
; #define PG8_WAIT_L(n) asm volatile("s_waitcnt lgkmcnt(" #n ")" ::: "memory")
; #define PG8_BAR __builtin_amdgcn_s_barrier()
; #define PG8_SCHED __builtin_amdgcn_sched_barrier(0)
; template <class Epi, class Sched>
; DI void gemm_phase(LAS unsigned char* lds, const int tid, const int K, const int lda, const int ldb, const Sched& S_, const Epi& E) {
;     ...
;             PG8_LDA(At, 1, 1); PG8_STAGE(PG8_SB(1, 0), b3, voffB); PG8_STAGE(PG8_SB(1, 1), b3 + hstepB, voffB); PG8_STAGE(PG8_SA(1, 0), a3, voffA);
;             PG8_WAIT_V(8); PG8_WAIT_L(0); PG8_BAR; PG8_MMA(1, 0, At, B0); PG8_MMA(1, 1, At, B1); PG8_BAR; PG8_SCHED;
;             if constexpr (Epi::HOOK) { if (((t + 2) & 7) == 0 && !last) { E.hook(acc, cur, (t + 2) >> 3, wr, wc, fr, fq); PG8_SCHED; } }
;         }
	s_mov_b32 m0, s87
	v_lshl_add_u64 v[184:185], v[184:185], 0, s[94:95]
	ds_read_b128 v[172:175], v139 offset:49152
	ds_read_b128 v[176:179], v139 offset:50176
	ds_read_b128 v[180:183], v139 offset:51200
	ds_read_b128 v[190:193], v139 offset:52224
	ds_read_b128 v[194:197], v139 offset:53248
	ds_read_b128 v[198:201], v139 offset:54272
	ds_read_b128 v[202:205], v139 offset:55296
	ds_read_b128 v[206:209], v139 offset:56320
	global_load_lds_dwordx4 v[184:185], off
	v_lshl_add_u64 v[184:185], v[186:187], 0, s[94:95]
	s_mov_b32 m0, s9
	s_nop 0
	global_load_lds_dwordx4 v[184:185], off
	v_lshl_add_u64 v[184:185], s[50:51], 0, v[128:129]
	s_mov_b32 m0, s72
	s_nop 0
	global_load_lds_dwordx4 v[184:185], off
	v_lshl_add_u64 v[184:185], s[50:51], 0, v[134:135]
	s_mov_b32 m0, s29
	s_nop 0
	global_load_lds_dwordx4 v[184:185], off
	v_lshl_add_u64 v[184:185], v[188:189], 0, s[94:95]
	s_mov_b32 m0, s14
	s_nop 0
	global_load_lds_dwordx4 v[184:185], off
	v_lshl_add_u64 v[184:185], v[210:211], 0, s[94:95]
	s_mov_b32 m0, s82
	s_nop 0
	global_load_lds_dwordx4 v[184:185], off
	s_waitcnt vmcnt(8)
	s_waitcnt lgkmcnt(0)
	s_barrier
	s_setprio 1
	s_waitcnt lgkmcnt(0)
	v_mfma_f32_16x16x32_bf16 v[60:63], v[140:143], v[172:175], v[60:63]
	v_mfma_f32_16x16x32_bf16 v[56:59], v[148:151], v[172:175], v[56:59]
	v_mfma_f32_16x16x32_bf16 v[52:55], v[140:143], v[180:183], v[52:55]
	v_mfma_f32_16x16x32_bf16 v[48:51], v[148:151], v[180:183], v[48:51]
	v_mfma_f32_16x16x32_bf16 v[36:39], v[140:143], v[194:197], v[36:39]
	v_mfma_f32_16x16x32_bf16 v[32:35], v[148:151], v[194:197], v[32:35]
	v_mfma_f32_16x16x32_bf16 v[20:23], v[140:143], v[202:205], v[20:23]
	v_mfma_f32_16x16x32_bf16 v[16:19], v[148:151], v[202:205], v[16:19]
	v_mfma_f32_16x16x32_bf16 v[60:63], v[144:147], v[176:179], v[60:63]
	v_mfma_f32_16x16x32_bf16 v[56:59], v[152:155], v[176:179], v[56:59]
	v_mfma_f32_16x16x32_bf16 v[52:55], v[144:147], v[190:193], v[52:55]
	v_mfma_f32_16x16x32_bf16 v[48:51], v[152:155], v[190:193], v[48:51]
	v_mfma_f32_16x16x32_bf16 v[36:39], v[144:147], v[198:201], v[36:39]
	v_mfma_f32_16x16x32_bf16 v[32:35], v[152:155], v[198:201], v[32:35]
	v_mfma_f32_16x16x32_bf16 v[20:23], v[144:147], v[206:209], v[20:23]
	v_mfma_f32_16x16x32_bf16 v[16:19], v[152:155], v[206:209], v[16:19]
	v_mfma_f32_16x16x32_bf16 v[44:47], v[156:159], v[172:175], v[44:47]
	v_mfma_f32_16x16x32_bf16 v[40:43], v[164:167], v[172:175], v[40:43]
	v_mfma_f32_16x16x32_bf16 v[28:31], v[156:159], v[180:183], v[28:31]
	v_mfma_f32_16x16x32_bf16 v[24:27], v[164:167], v[180:183], v[24:27]
	v_mfma_f32_16x16x32_bf16 v[12:15], v[156:159], v[194:197], v[12:15]
	v_mfma_f32_16x16x32_bf16 v[8:11], v[164:167], v[194:197], v[8:11]
	v_mfma_f32_16x16x32_bf16 v[4:7], v[156:159], v[202:205], v[4:7]
	v_mfma_f32_16x16x32_bf16 v[0:3], v[164:167], v[202:205], v[0:3]
	v_mfma_f32_16x16x32_bf16 v[44:47], v[160:163], v[176:179], v[44:47]
	v_mfma_f32_16x16x32_bf16 v[40:43], v[168:171], v[176:179], v[40:43]
	v_mfma_f32_16x16x32_bf16 v[28:31], v[160:163], v[190:193], v[28:31]
	v_mfma_f32_16x16x32_bf16 v[24:27], v[168:171], v[190:193], v[24:27]
	v_mfma_f32_16x16x32_bf16 v[12:15], v[160:163], v[198:201], v[12:15]
	v_mfma_f32_16x16x32_bf16 v[8:11], v[168:171], v[198:201], v[8:11]
	v_mfma_f32_16x16x32_bf16 v[4:7], v[160:163], v[206:209], v[4:7]
	v_mfma_f32_16x16x32_bf16 v[0:3], v[168:171], v[206:209], v[0:3]
	s_setprio 0
	s_barrier
	s_movk_i32 s9, 0x100
	s_andn2_b64 vcc, exec, s[34:35]
	s_mov_b64 s[50:51], -1
	s_mov_b64 s[34:35], 0
	s_cbranch_vccz .LBB0_342
	s_and_b64 vcc, exec, s[6:7]
	s_cbranch_vccz .LBB0_345
	s_barrier

; #define PG8_STAGE(bufoff, gbase, voff) do { _Pragma("unroll") for (int _i = 0; _i < 2; ++_i) \
;         __builtin_amdgcn_global_load_lds((const unsigned*)((const char*)(gbase) + (voff)[_i]), (LAS unsigned*)(lds + (bufoff) + ldsw + _i * 8192), 16, 0, 0); } while (0)
; #define PG8_LDA(dst, b, h) do { _Pragma("unroll") for (int m = 0; m < 4; ++m) _Pragma("unroll") for (int k = 0; k < 2; ++k) dst[m][k] = *(const LAS bf16x8*)(lds + PG8_SA(b, h) + aoff + m * 2048 + k * 1024); } while (0)
; #define PG8_LDB(dst, b, h) do { _Pragma("unroll") for (int n = 0; n < 2; ++n) _Pragma("unroll") for (int k = 0; k < 2; ++k) dst[n][k] = *(const LAS bf16x8*)(lds + PG8_SB(b, h) + boff + n * 2048 + k * 1024); } while (0)
; #define PG8_MMA(ai, bj, At, Bt) do { __builtin_amdgcn_s_setprio(1); _Pragma("unroll") for (int m = 0; m < 4; ++m) _Pragma("unroll") for (int n = 0; n < 2; ++n) _Pragma("unroll") for (int k = 0; k < 2; ++k) \
;         acc[ai][bj][m][n] = __builtin_amdgcn_mfma_f32_16x16x32_bf16(Bt[n][k], At[m][k], acc[ai][bj][m][n], 0, 0, 0); __builtin_amdgcn_s_setprio(0); } while (0)
; #define PG8_WAIT_V(n) asm volatile("s_waitcnt vmcnt(" #n ")" ::: "memory")
; #define PG8_BAR __builtin_amdgcn_s_barrier()
; template <class Epi, class Sched>
; DI void gemm_phase(LAS unsigned char* lds, const int tid, const int K, const int lda, const int ldb, const Sched& S_, const Epi& E) {
;     ...
;         const bool has_next = S_.next(ui + 1, nxt);
;         const char* nA = has_next ? nxt.a : cA; const char* nB = has_next ? nxt.b : cB;
;         for (int t = 0; t < nt; t += 2) {
;             const bool last = (t == nt - 2);
;             const char* a1 = cA + (size_t)(t + 1) * kstep;
;             const char* a2 = last ? nA : cA + (size_t)(t + 2) * kstep; const char* b2 = last ? nB : cB + (size_t)(t + 2) * kstep;
;             const char* a3 = a2 + kstep; const char* b3 = b2 + kstep;
;             PG8_LDB(B0, 0, 0); PG8_LDB(B1, 0, 1); PG8_SCHED; PG8_LDA(At, 0, 0); PG8_STAGE(PG8_SA(1, 1), a1 + hstepA, voffA);
;             PG8_WAIT_V(8); PG8_WAIT_L(0); PG8_BAR; PG8_MMA(0, 0, At, B0); PG8_MMA(0, 1, At, B1); PG8_BAR; PG8_SCHED;
;             PG8_LDA(At, 0, 1); PG8_STAGE(PG8_SB(0, 0), b2, voffB); PG8_STAGE(PG8_SB(0, 1), b2 + hstepB, voffB); PG8_STAGE(PG8_SA(0, 0), a2, voffA);
;             PG8_WAIT_V(8); PG8_WAIT_L(0); PG8_BAR; PG8_MMA(1, 0, At, B0); PG8_MMA(1, 1, At, B1); PG8_BAR; PG8_SCHED;
.LBB0_713:
	s_add_u32 s14, s58, 0xfff80080
	s_addc_u32 s16, s59, -1
	s_add_i32 s29, 0, 0x10000
	s_cmpk_eq_i32 s60, 0x3c00
	s_cselect_b64 s[8:9], -1, 0
	s_and_b64 s[10:11], s[8:9], exec
	s_cselect_b32 s17, s55, s16
	s_cselect_b32 s16, s54, s14
	v_add_u32_e32 v128, s29, v155
	s_cselect_b32 s11, s57, s21
	s_cselect_b32 s10, s56, s20
	s_add_i32 s14, 0, 0x14000
	ds_read_b128 v[130:133], v128
	ds_read_b128 v[150:153], v128 offset:1024
	ds_read_b128 v[158:161], v128 offset:2048
	ds_read_b128 v[162:165], v128 offset:3072
	v_add_u32_e32 v128, s14, v155
	ds_read_b128 v[166:169], v128
	ds_read_b128 v[170:173], v128 offset:1024
	ds_read_b128 v[174:177], v128 offset:2048
	ds_read_b128 v[178:181], v128 offset:3072
	v_lshl_add_u64 v[214:215], s[58:59], 0, v[142:143]
	s_add_i32 m0, s2, 0xc000
	ds_read_b128 v[182:185], v157
	ds_read_b128 v[186:189], v157 offset:1024
	ds_read_b128 v[190:193], v157 offset:2048
	ds_read_b128 v[194:197], v157 offset:3072
	ds_read_b128 v[198:201], v157 offset:4096
	ds_read_b128 v[202:205], v157 offset:5120
	ds_read_b128 v[206:209], v157 offset:6144
	ds_read_b128 v[210:213], v157 offset:7168
	global_load_lds_dwordx4 v[214:215], off
	v_lshl_add_u64 v[214:215], s[58:59], 0, v[144:145]
	s_add_i32 m0, s2, 0xe000
	s_nop 0
	global_load_lds_dwordx4 v[214:215], off
	s_waitcnt vmcnt(8)
	s_waitcnt lgkmcnt(0)
	s_barrier
	s_setprio 1
	s_waitcnt lgkmcnt(0)
	v_mfma_f32_16x16x32_bf16 v[124:127], v[130:133], v[182:185], v[124:127]
	v_mfma_f32_16x16x32_bf16 v[120:123], v[158:161], v[182:185], v[120:123]
	v_mfma_f32_16x16x32_bf16 v[108:111], v[130:133], v[190:193], v[108:111]
	v_mfma_f32_16x16x32_bf16 v[104:107], v[158:161], v[190:193], v[104:107]
	v_mfma_f32_16x16x32_bf16 v[92:95], v[130:133], v[198:201], v[92:95]
	v_mfma_f32_16x16x32_bf16 v[88:91], v[158:161], v[198:201], v[88:91]
	v_mfma_f32_16x16x32_bf16 v[76:79], v[130:133], v[206:209], v[76:79]
	v_mfma_f32_16x16x32_bf16 v[72:75], v[158:161], v[206:209], v[72:75]
	v_mfma_f32_16x16x32_bf16 v[124:127], v[150:153], v[186:189], v[124:127]
	v_mfma_f32_16x16x32_bf16 v[120:123], v[162:165], v[186:189], v[120:123]
	v_mfma_f32_16x16x32_bf16 v[108:111], v[150:153], v[194:197], v[108:111]
	v_mfma_f32_16x16x32_bf16 v[104:107], v[162:165], v[194:197], v[104:107]
	v_mfma_f32_16x16x32_bf16 v[92:95], v[150:153], v[202:205], v[92:95]
	v_mfma_f32_16x16x32_bf16 v[88:91], v[162:165], v[202:205], v[88:91]
	v_mfma_f32_16x16x32_bf16 v[76:79], v[150:153], v[210:213], v[76:79]
	v_mfma_f32_16x16x32_bf16 v[72:75], v[162:165], v[210:213], v[72:75]
	v_mfma_f32_16x16x32_bf16 v[116:119], v[166:169], v[182:185], v[116:119]
	v_mfma_f32_16x16x32_bf16 v[112:115], v[174:177], v[182:185], v[112:115]
	v_mfma_f32_16x16x32_bf16 v[100:103], v[166:169], v[190:193], v[100:103]
	v_mfma_f32_16x16x32_bf16 v[96:99], v[174:177], v[190:193], v[96:99]
	v_mfma_f32_16x16x32_bf16 v[84:87], v[166:169], v[198:201], v[84:87]
	v_mfma_f32_16x16x32_bf16 v[80:83], v[174:177], v[198:201], v[80:83]
	v_mfma_f32_16x16x32_bf16 v[68:71], v[166:169], v[206:209], v[68:71]
	v_mfma_f32_16x16x32_bf16 v[64:67], v[174:177], v[206:209], v[64:67]
	v_mfma_f32_16x16x32_bf16 v[116:119], v[170:173], v[186:189], v[116:119]
	v_mfma_f32_16x16x32_bf16 v[112:115], v[178:181], v[186:189], v[112:115]
	v_mfma_f32_16x16x32_bf16 v[100:103], v[170:173], v[194:197], v[100:103]
	v_mfma_f32_16x16x32_bf16 v[96:99], v[178:181], v[194:197], v[96:99]
	v_mfma_f32_16x16x32_bf16 v[84:87], v[170:173], v[202:205], v[84:87]
	v_mfma_f32_16x16x32_bf16 v[80:83], v[178:181], v[202:205], v[80:83]
	v_mfma_f32_16x16x32_bf16 v[68:71], v[170:173], v[210:213], v[68:71]
	v_mfma_f32_16x16x32_bf16 v[64:67], v[178:181], v[210:213], v[64:67]
	s_setprio 0
	s_barrier
	s_add_i32 s29, s29, s97
	v_lshl_add_u64 v[214:215], s[10:11], 0, v[136:137]
	s_mov_b32 m0, s29
	ds_read_b128 v[182:185], v157 offset:16384
	ds_read_b128 v[186:189], v157 offset:17408
	ds_read_b128 v[190:193], v157 offset:18432
	ds_read_b128 v[194:197], v157 offset:19456
	ds_read_b128 v[198:201], v157 offset:20480
	ds_read_b128 v[202:205], v157 offset:21504
	ds_read_b128 v[206:209], v157 offset:22528
	ds_read_b128 v[210:213], v157 offset:23552
	global_load_lds_dwordx4 v[214:215], off
	s_add_i32 m0, s29, 0x2000
	s_add_u32 s30, s10, 0x80000
	v_lshl_add_u64 v[216:217], s[10:11], 0, v[140:141]
	s_addc_u32 s31, s11, 0
	s_add_i32 s14, s14, s97
	global_load_lds_dwordx4 v[216:217], off
	v_lshl_add_u64 v[222:223], s[30:31], 0, v[136:137]
	s_mov_b32 m0, s14
	v_lshl_add_u64 v[224:225], s[16:17], 0, v[138:139]
	global_load_lds_dwordx4 v[222:223], off
	v_lshl_add_u64 v[222:223], s[30:31], 0, v[140:141]
	s_add_i32 m0, s14, 0x2000
	s_nop 0
	global_load_lds_dwordx4 v[222:223], off
	v_lshl_add_u64 v[222:223], s[16:17], 0, v[134:135]
	s_mov_b32 m0, s2
	s_nop 0
	global_load_lds_dwordx4 v[222:223], off
	s_mov_b32 m0, s3
	s_nop 0
	global_load_lds_dwordx4 v[224:225], off
	s_waitcnt vmcnt(8)
	s_waitcnt lgkmcnt(0)
	s_barrier
; #define PG8_STAGE(bufoff, gbase, voff) do { _Pragma("unroll") for (int _i = 0; _i < 2; ++_i) \
;         __builtin_amdgcn_global_load_lds((const unsigned*)((const char*)(gbase) + (voff)[_i]), (LAS unsigned*)(lds + (bufoff) + ldsw + _i * 8192), 16, 0, 0); } while (0)
; #define PG8_LDA(dst, b, h) do { _Pragma("unroll") for (int m = 0; m < 4; ++m) _Pragma("unroll") for (int k = 0; k < 2; ++k) dst[m][k] = *(const LAS bf16x8*)(lds + PG8_SA(b, h) + aoff + m * 2048 + k * 1024); } while (0)
; #define PG8_LDB(dst, b, h) do { _Pragma("unroll") for (int n = 0; n < 2; ++n) _Pragma("unroll") for (int k = 0; k < 2; ++k) dst[n][k] = *(const LAS bf16x8*)(lds + PG8_SB(b, h) + boff + n * 2048 + k * 1024); } while (0)
; #define PG8_MMA(ai, bj, At, Bt) do { __builtin_amdgcn_s_setprio(1); _Pragma("unroll") for (int m = 0; m < 4; ++m) _Pragma("unroll") for (int n = 0; n < 2; ++n) _Pragma("unroll") for (int k = 0; k < 2; ++k) \
;         acc[ai][bj][m][n] = __builtin_amdgcn_mfma_f32_16x16x32_bf16(Bt[n][k], At[m][k], acc[ai][bj][m][n], 0, 0, 0); __builtin_amdgcn_s_setprio(0); } while (0)
; #define PG8_WAIT_V(n) asm volatile("s_waitcnt vmcnt(" #n ")" ::: "memory")
; #define PG8_WAIT_L(n) asm volatile("s_waitcnt lgkmcnt(" #n ")" ::: "memory")
; #define PG8_BAR __builtin_amdgcn_s_barrier()
; #define PG8_SCHED __builtin_amdgcn_sched_barrier(0)
; template <class Epi, class Sched>
; DI void gemm_phase(LAS unsigned char* lds, const int tid, const int K, const int lda, const int ldb, const Sched& S_, const Epi& E) {
;     ...
;             PG8_WAIT_V(8); PG8_WAIT_L(0); PG8_BAR; PG8_MMA(1, 0, At, B0); PG8_MMA(1, 1, At, B1); PG8_BAR; PG8_SCHED;
;             PG8_LDB(B0, 1, 0); PG8_LDB(B1, 1, 1); PG8_SCHED; PG8_LDA(At, 1, 0); PG8_STAGE(PG8_SA(0, 1), a2 + hstepA, voffA);
;             PG8_WAIT_V(8); PG8_WAIT_L(0); PG8_BAR; PG8_MMA(0, 0, At, B0); PG8_MMA(0, 1, At, B1); PG8_BAR; PG8_SCHED;
	s_setprio 1
	s_waitcnt lgkmcnt(0)
	v_mfma_f32_16x16x32_bf16 v[60:63], v[130:133], v[182:185], v[60:63]
	v_mfma_f32_16x16x32_bf16 v[56:59], v[158:161], v[182:185], v[56:59]
	v_mfma_f32_16x16x32_bf16 v[44:47], v[130:133], v[190:193], v[44:47]
	v_mfma_f32_16x16x32_bf16 v[40:43], v[158:161], v[190:193], v[40:43]
	v_mfma_f32_16x16x32_bf16 v[28:31], v[130:133], v[198:201], v[28:31]
	v_mfma_f32_16x16x32_bf16 v[24:27], v[158:161], v[198:201], v[24:27]
	v_mfma_f32_16x16x32_bf16 v[12:15], v[130:133], v[206:209], v[12:15]
	v_mfma_f32_16x16x32_bf16 v[8:11], v[158:161], v[206:209], v[8:11]
	v_mfma_f32_16x16x32_bf16 v[60:63], v[150:153], v[186:189], v[60:63]
	v_mfma_f32_16x16x32_bf16 v[56:59], v[162:165], v[186:189], v[56:59]
	v_mfma_f32_16x16x32_bf16 v[44:47], v[150:153], v[194:197], v[44:47]
	v_mfma_f32_16x16x32_bf16 v[40:43], v[162:165], v[194:197], v[40:43]
	v_mfma_f32_16x16x32_bf16 v[28:31], v[150:153], v[202:205], v[28:31]
	v_mfma_f32_16x16x32_bf16 v[24:27], v[162:165], v[202:205], v[24:27]
	v_mfma_f32_16x16x32_bf16 v[12:15], v[150:153], v[210:213], v[12:15]
	v_mfma_f32_16x16x32_bf16 v[8:11], v[162:165], v[210:213], v[8:11]
	v_mfma_f32_16x16x32_bf16 v[52:55], v[166:169], v[182:185], v[52:55]
	v_mfma_f32_16x16x32_bf16 v[48:51], v[174:177], v[182:185], v[48:51]
	v_mfma_f32_16x16x32_bf16 v[36:39], v[166:169], v[190:193], v[36:39]
	v_mfma_f32_16x16x32_bf16 v[32:35], v[174:177], v[190:193], v[32:35]
	v_mfma_f32_16x16x32_bf16 v[20:23], v[166:169], v[198:201], v[20:23]
	v_mfma_f32_16x16x32_bf16 v[16:19], v[174:177], v[198:201], v[16:19]
	v_mfma_f32_16x16x32_bf16 v[4:7], v[166:169], v[206:209], v[4:7]
	v_mfma_f32_16x16x32_bf16 v[0:3], v[174:177], v[206:209], v[0:3]
	v_mfma_f32_16x16x32_bf16 v[52:55], v[170:173], v[186:189], v[52:55]
	v_mfma_f32_16x16x32_bf16 v[48:51], v[178:181], v[186:189], v[48:51]
	v_mfma_f32_16x16x32_bf16 v[36:39], v[170:173], v[194:197], v[36:39]
	v_mfma_f32_16x16x32_bf16 v[32:35], v[178:181], v[194:197], v[32:35]
	v_mfma_f32_16x16x32_bf16 v[20:23], v[170:173], v[202:205], v[20:23]
	v_mfma_f32_16x16x32_bf16 v[16:19], v[178:181], v[202:205], v[16:19]
	v_mfma_f32_16x16x32_bf16 v[4:7], v[170:173], v[210:213], v[4:7]
	v_mfma_f32_16x16x32_bf16 v[0:3], v[178:181], v[210:213], v[0:3]
	s_setprio 0
	s_barrier
	s_add_i32 s14, 0, 0x18000
	v_add_u32_e32 v128, s14, v155
	s_add_i32 s29, 0, 0x1c000
	ds_read_b128 v[130:133], v128
	ds_read_b128 v[150:153], v128 offset:1024
	ds_read_b128 v[158:161], v128 offset:2048
	ds_read_b128 v[162:165], v128 offset:3072
	v_add_u32_e32 v128, s29, v155
	ds_read_b128 v[166:169], v128
	ds_read_b128 v[170:173], v128 offset:1024
	ds_read_b128 v[174:177], v128 offset:2048
	ds_read_b128 v[178:181], v128 offset:3072
	s_add_u32 s16, s16, 0x80000
	s_addc_u32 s17, s17, 0
	s_mov_b32 m0, s78
	v_lshl_add_u64 v[226:227], s[16:17], 0, v[134:135]
	ds_read_b128 v[182:185], v157 offset:32768
	ds_read_b128 v[186:189], v157 offset:33792
	ds_read_b128 v[190:193], v157 offset:34816
	ds_read_b128 v[194:197], v157 offset:35840
	ds_read_b128 v[198:201], v157 offset:36864
	ds_read_b128 v[202:205], v157 offset:37888
	ds_read_b128 v[206:209], v157 offset:38912
	ds_read_b128 v[210:213], v157 offset:39936
	global_load_lds_dwordx4 v[226:227], off
	v_lshl_add_u64 v[226:227], s[16:17], 0, v[138:139]
	s_mov_b32 m0, s79
	s_nop 0
	global_load_lds_dwordx4 v[226:227], off
	s_waitcnt vmcnt(8)
	s_waitcnt lgkmcnt(0)
	s_barrier
	s_setprio 1
	s_waitcnt lgkmcnt(0)
	v_mfma_f32_16x16x32_bf16 v[124:127], v[130:133], v[182:185], v[124:127]
	v_mfma_f32_16x16x32_bf16 v[120:123], v[158:161], v[182:185], v[120:123]
	v_mfma_f32_16x16x32_bf16 v[108:111], v[130:133], v[190:193], v[108:111]
	v_mfma_f32_16x16x32_bf16 v[104:107], v[158:161], v[190:193], v[104:107]
	v_mfma_f32_16x16x32_bf16 v[92:95], v[130:133], v[198:201], v[92:95]
	v_mfma_f32_16x16x32_bf16 v[88:91], v[158:161], v[198:201], v[88:91]
	v_mfma_f32_16x16x32_bf16 v[76:79], v[130:133], v[206:209], v[76:79]
	v_mfma_f32_16x16x32_bf16 v[72:75], v[158:161], v[206:209], v[72:75]
	v_mfma_f32_16x16x32_bf16 v[124:127], v[150:153], v[186:189], v[124:127]
	v_mfma_f32_16x16x32_bf16 v[120:123], v[162:165], v[186:189], v[120:123]
	v_mfma_f32_16x16x32_bf16 v[108:111], v[150:153], v[194:197], v[108:111]
	v_mfma_f32_16x16x32_bf16 v[104:107], v[162:165], v[194:197], v[104:107]
	v_mfma_f32_16x16x32_bf16 v[92:95], v[150:153], v[202:205], v[92:95]
	v_mfma_f32_16x16x32_bf16 v[88:91], v[162:165], v[202:205], v[88:91]
	v_mfma_f32_16x16x32_bf16 v[76:79], v[150:153], v[210:213], v[76:79]
	v_mfma_f32_16x16x32_bf16 v[72:75], v[162:165], v[210:213], v[72:75]
	v_mfma_f32_16x16x32_bf16 v[116:119], v[166:169], v[182:185], v[116:119]
	v_mfma_f32_16x16x32_bf16 v[112:115], v[174:177], v[182:185], v[112:115]
	v_mfma_f32_16x16x32_bf16 v[100:103], v[166:169], v[190:193], v[100:103]
	v_mfma_f32_16x16x32_bf16 v[96:99], v[174:177], v[190:193], v[96:99]
	v_mfma_f32_16x16x32_bf16 v[84:87], v[166:169], v[198:201], v[84:87]
	v_mfma_f32_16x16x32_bf16 v[80:83], v[174:177], v[198:201], v[80:83]
	v_mfma_f32_16x16x32_bf16 v[68:71], v[166:169], v[206:209], v[68:71]
	v_mfma_f32_16x16x32_bf16 v[64:67], v[174:177], v[206:209], v[64:67]
	v_mfma_f32_16x16x32_bf16 v[116:119], v[170:173], v[186:189], v[116:119]
	v_mfma_f32_16x16x32_bf16 v[112:115], v[178:181], v[186:189], v[112:115]
	v_mfma_f32_16x16x32_bf16 v[100:103], v[170:173], v[194:197], v[100:103]
	v_mfma_f32_16x16x32_bf16 v[96:99], v[178:181], v[194:197], v[96:99]
	v_mfma_f32_16x16x32_bf16 v[84:87], v[170:173], v[202:205], v[84:87]
	v_mfma_f32_16x16x32_bf16 v[80:83], v[178:181], v[202:205], v[80:83]
	v_mfma_f32_16x16x32_bf16 v[68:71], v[170:173], v[210:213], v[68:71]
	v_mfma_f32_16x16x32_bf16 v[64:67], v[178:181], v[210:213], v[64:67]
	s_setprio 0
	s_barrier
; DI void unpack8(const u32x4 v, float* x) { x[0] = bflo(v.x); x[1] = bfhi(v.x); x[2] = bflo(v.y); x[3] = bfhi(v.y); x[4] = bflo(v.z); x[5] = bfhi(v.z); x[6] = bflo(v.w); x[7] = bfhi(v.w); }
; #define PG8_STAGE(bufoff, gbase, voff) do { _Pragma("unroll") for (int _i = 0; _i < 2; ++_i) \
;         __builtin_amdgcn_global_load_lds((const unsigned*)((const char*)(gbase) + (voff)[_i]), (LAS unsigned*)(lds + (bufoff) + ldsw + _i * 8192), 16, 0, 0); } while (0)
; #define PG8_LDA(dst, b, h) do { _Pragma("unroll") for (int m = 0; m < 4; ++m) _Pragma("unroll") for (int k = 0; k < 2; ++k) dst[m][k] = *(const LAS bf16x8*)(lds + PG8_SA(b, h) + aoff + m * 2048 + k * 1024); } while (0)
; #define PG8_MMA(ai, bj, At, Bt) do { __builtin_amdgcn_s_setprio(1); _Pragma("unroll") for (int m = 0; m < 4; ++m) _Pragma("unroll") for (int n = 0; n < 2; ++n) _Pragma("unroll") for (int k = 0; k < 2; ++k) \
;         acc[ai][bj][m][n] = __builtin_amdgcn_mfma_f32_16x16x32_bf16(Bt[n][k], At[m][k], acc[ai][bj][m][n], 0, 0, 0); __builtin_amdgcn_s_setprio(0); } while (0)
; #define PG8_BAR __builtin_amdgcn_s_barrier()
;     DI void hook(f32x4 (&acc)[2][2][4][2], const Unit& u, int n, int wr, int wc, int fr, int fq) const {
;         int row0 = u.pm * BM + wr * 64 + fr, col0 = u.pn * BM + wc * 32 + 8 * fq;
;         asm volatile("" : "+v"(row0), "+v"(col0));
; #pragma unroll
;         for (int ai = 0; ai < 2; ++ai) {
; #pragma unroll
;             for (int m = 0; m < 4; ++m) { const size_t row = (size_t)(row0 + ai * HALF + m * 16);
; #pragma unroll
;                 for (int bj = 0; bj < 2; ++bj) { const int col = col0 + bj * HALF;
;                     float gp[8], gc[8]; unpack8(*(const u32x4*)(G + row * LDP + (size_t)(n - 1) * DM + col), gp); unpack8(*(const u32x4*)(G + row * LDP + (size_t)n * DM + col), gc);
; template <class Epi, class Sched>
; DI void gemm_phase(LAS unsigned char* lds, const int tid, const int K, const int lda, const int ldb, const Sched& S_, const Epi& E) {
;     ...
;             PG8_LDA(At, 1, 1); PG8_STAGE(PG8_SB(1, 0), b3, voffB); PG8_STAGE(PG8_SB(1, 1), b3 + hstepB, voffB); PG8_STAGE(PG8_SA(1, 0), a3, voffA);
;             PG8_WAIT_V(8); PG8_WAIT_L(0); PG8_BAR; PG8_MMA(1, 0, At, B0); PG8_MMA(1, 1, At, B1); PG8_BAR; PG8_SCHED;
;             if constexpr (Epi::HOOK) { if (((t + 2) & 7) == 0 && !last) { E.hook(acc, cur, (t + 2) >> 3, wr, wc, fr, fq); PG8_SCHED; } }
;         }
	s_add_i32 s14, s14, s97
	v_lshl_add_u64 v[214:215], v[214:215], 0, s[94:95]
	s_mov_b32 m0, s14
	ds_read_b128 v[182:185], v157 offset:49152
	ds_read_b128 v[186:189], v157 offset:50176
	ds_read_b128 v[190:193], v157 offset:51200
	ds_read_b128 v[194:197], v157 offset:52224
	ds_read_b128 v[198:201], v157 offset:53248
	ds_read_b128 v[202:205], v157 offset:54272
	ds_read_b128 v[206:209], v157 offset:55296
	ds_read_b128 v[210:213], v157 offset:56320
	global_load_lds_dwordx4 v[214:215], off
	s_add_i32 m0, s14, 0x2000
	s_add_u32 s10, s10, 0x80080
	v_lshl_add_u64 v[214:215], v[216:217], 0, s[94:95]
	s_addc_u32 s11, s11, 0
	s_add_i32 s14, s29, s97
	global_load_lds_dwordx4 v[214:215], off
	v_lshl_add_u64 v[214:215], s[10:11], 0, v[136:137]
	s_mov_b32 m0, s14
	s_nop 0
	global_load_lds_dwordx4 v[214:215], off
	v_lshl_add_u64 v[214:215], s[10:11], 0, v[140:141]
	s_add_i32 m0, s14, 0x2000
	s_nop 0
	global_load_lds_dwordx4 v[214:215], off
	v_lshl_add_u64 v[214:215], v[222:223], 0, s[94:95]
	s_mov_b32 m0, s80
	s_nop 0
	global_load_lds_dwordx4 v[214:215], off
	v_lshl_add_u64 v[214:215], v[224:225], 0, s[94:95]
	s_mov_b32 m0, s81
	s_nop 0
	global_load_lds_dwordx4 v[214:215], off
	s_waitcnt vmcnt(8)
	s_waitcnt lgkmcnt(0)
	s_barrier
	s_setprio 1
	s_waitcnt lgkmcnt(0)
	v_mfma_f32_16x16x32_bf16 v[60:63], v[130:133], v[182:185], v[60:63]
	v_mfma_f32_16x16x32_bf16 v[56:59], v[158:161], v[182:185], v[56:59]
	v_mfma_f32_16x16x32_bf16 v[44:47], v[130:133], v[190:193], v[44:47]
	v_mfma_f32_16x16x32_bf16 v[40:43], v[158:161], v[190:193], v[40:43]
	v_mfma_f32_16x16x32_bf16 v[28:31], v[130:133], v[198:201], v[28:31]
	v_mfma_f32_16x16x32_bf16 v[24:27], v[158:161], v[198:201], v[24:27]
	v_mfma_f32_16x16x32_bf16 v[12:15], v[130:133], v[206:209], v[12:15]
	v_mfma_f32_16x16x32_bf16 v[8:11], v[158:161], v[206:209], v[8:11]
	v_mfma_f32_16x16x32_bf16 v[60:63], v[150:153], v[186:189], v[60:63]
	v_mfma_f32_16x16x32_bf16 v[56:59], v[162:165], v[186:189], v[56:59]
	v_mfma_f32_16x16x32_bf16 v[44:47], v[150:153], v[194:197], v[44:47]
	v_mfma_f32_16x16x32_bf16 v[40:43], v[162:165], v[194:197], v[40:43]
	v_mfma_f32_16x16x32_bf16 v[28:31], v[150:153], v[202:205], v[28:31]
	v_mfma_f32_16x16x32_bf16 v[24:27], v[162:165], v[202:205], v[24:27]
	v_mfma_f32_16x16x32_bf16 v[12:15], v[150:153], v[210:213], v[12:15]
	v_mfma_f32_16x16x32_bf16 v[8:11], v[162:165], v[210:213], v[8:11]
	v_mfma_f32_16x16x32_bf16 v[52:55], v[166:169], v[182:185], v[52:55]
	v_mfma_f32_16x16x32_bf16 v[48:51], v[174:177], v[182:185], v[48:51]
	v_mfma_f32_16x16x32_bf16 v[36:39], v[166:169], v[190:193], v[36:39]
	v_mfma_f32_16x16x32_bf16 v[32:35], v[174:177], v[190:193], v[32:35]
	v_mfma_f32_16x16x32_bf16 v[20:23], v[166:169], v[198:201], v[20:23]
	v_mfma_f32_16x16x32_bf16 v[16:19], v[174:177], v[198:201], v[16:19]
	v_mfma_f32_16x16x32_bf16 v[4:7], v[166:169], v[206:209], v[4:7]
	v_mfma_f32_16x16x32_bf16 v[0:3], v[174:177], v[206:209], v[0:3]
	v_mfma_f32_16x16x32_bf16 v[52:55], v[170:173], v[186:189], v[52:55]
	v_mfma_f32_16x16x32_bf16 v[48:51], v[178:181], v[186:189], v[48:51]
	v_mfma_f32_16x16x32_bf16 v[36:39], v[170:173], v[194:197], v[36:39]
	v_mfma_f32_16x16x32_bf16 v[32:35], v[178:181], v[194:197], v[32:35]
	v_mfma_f32_16x16x32_bf16 v[20:23], v[170:173], v[202:205], v[20:23]
	v_mfma_f32_16x16x32_bf16 v[16:19], v[178:181], v[202:205], v[16:19]
	v_mfma_f32_16x16x32_bf16 v[4:7], v[170:173], v[210:213], v[4:7]
	v_mfma_f32_16x16x32_bf16 v[0:3], v[178:181], v[210:213], v[0:3]
	s_setprio 0
	s_barrier
	s_add_i32 s10, s51, 4
	s_and_b32 s11, s10, 6
	s_cmp_lg_u32 s11, 0
	s_cselect_b64 s[16:17], -1, 0
	s_or_b64 s[8:9], s[8:9], s[16:17]
	s_and_b64 vcc, exec, s[8:9]
	s_cbranch_vccnz .LBB0_712
	s_lshr_b32 s14, s10, 3
	s_lshl_b32 s14, s14, 12
	s_add_u32 s8, s18, s14
	s_addc_u32 s9, s19, 0
	s_add_u32 s8, s8, 0xfffff800
	s_addc_u32 s9, s9, -1
	s_mov_b32 s62, 0xda24260
	s_mov_b32 s63, 0xffff0000
	s_mov_b32 s30, 0x8c000
	s_mov_b32 s31, 0
	s_mov_b32 s16, 0x2bc000
	s_mov_b32 s17, 0
	v_mov_b64_e32 v[132:133], s[8:9]
	v_mad_i64_i32 v[130:131], vcc, v146, s68, v[132:133]
	v_lshlrev_b32_e32 v132, 1, v148
	v_mov_b32_e32 v133, 0
	v_lshl_add_u64 v[130:131], v[130:131], 0, v[132:133]
	global_load_dwordx4 v[158:161], v[130:131], off offset:-2048
	global_load_dwordx4 v[162:165], v[130:131], off offset:2048
	global_load_dwordx4 v[166:169], v[130:131], off offset:-1792
	global_load_dwordx4 v[170:173], v[130:131], off offset:2304
	v_lshl_add_u64 v[130:131], v[130:131], 0, s[30:31]
	global_load_dwordx4 v[174:177], v[130:131], off offset:-2048
	global_load_dwordx4 v[178:181], v[130:131], off offset:2048
	global_load_dwordx4 v[182:185], v[130:131], off offset:-1792
	global_load_dwordx4 v[186:189], v[130:131], off offset:2304
	v_lshl_add_u64 v[130:131], v[130:131], 0, s[30:31]
	global_load_dwordx4 v[190:193], v[130:131], off offset:-2048
	global_load_dwordx4 v[194:197], v[130:131], off offset:2048
	global_load_dwordx4 v[198:201], v[130:131], off offset:-1792
	global_load_dwordx4 v[202:205], v[130:131], off offset:2304
	v_lshl_add_u64 v[130:131], v[130:131], 0, s[30:31]
	s_waitcnt vmcnt(10)
; DI void unpack8(const u32x4 v, float* x) { x[0] = bflo(v.x); x[1] = bfhi(v.x); x[2] = bflo(v.y); x[3] = bfhi(v.y); x[4] = bflo(v.z); x[5] = bfhi(v.z); x[6] = bflo(v.w); x[7] = bfhi(v.w); }
;     DI void hook(f32x4 (&acc)[2][2][4][2], const Unit& u, int n, int wr, int wc, int fr, int fq) const {
;     ...
;                     float gp[8], gc[8]; unpack8(*(const u32x4*)(G + row * LDP + (size_t)(n - 1) * DM + col), gp); unpack8(*(const u32x4*)(G + row * LDP + (size_t)n * DM + col), gc);
; #pragma unroll
;                     for (int j = 0; j < 4; ++j) { acc[ai][bj][m][0][j] *= fmaxf(gp[j], 1e-30f) * __builtin_amdgcn_rcpf(fmaxf(gc[j], 1e-30f));
;                                                   acc[ai][bj][m][1][j] *= fmaxf(gp[4 + j], 1e-30f) * __builtin_amdgcn_rcpf(fmaxf(gc[4 + j], 1e-30f)); } }
	v_lshlrev_b32_e32 v206, 16, v158
	v_and_b32_e32 v207, s63, v158
	v_lshlrev_b32_e32 v214, 16, v162
	v_and_b32_e32 v215, s63, v162
	v_lshlrev_b32_e32 v208, 16, v159
	v_and_b32_e32 v209, s63, v159
	v_lshlrev_b32_e32 v216, 16, v163
	v_and_b32_e32 v217, s63, v163
	v_lshlrev_b32_e32 v210, 16, v160
	v_and_b32_e32 v211, s63, v160
	v_lshlrev_b32_e32 v222, 16, v164
	v_and_b32_e32 v223, s63, v164
	v_lshlrev_b32_e32 v212, 16, v161
	v_and_b32_e32 v213, s63, v161
	v_lshlrev_b32_e32 v224, 16, v165
	v_and_b32_e32 v225, s63, v165
	v_max_f32_e32 v214, s62, v214
	v_max_f32_e32 v215, s62, v215
	v_max_f32_e32 v216, s62, v216
	v_max_f32_e32 v217, s62, v217
	v_max_f32_e32 v222, s62, v222
	v_max_f32_e32 v223, s62, v223
	v_max_f32_e32 v224, s62, v224
	v_max_f32_e32 v225, s62, v225
	v_rcp_f32_e32 v214, v214
	v_rcp_f32_e32 v215, v215
	v_rcp_f32_e32 v216, v216
	v_rcp_f32_e32 v217, v217
	v_rcp_f32_e32 v222, v222
	v_rcp_f32_e32 v223, v223
	v_rcp_f32_e32 v224, v224
	v_rcp_f32_e32 v225, v225
	v_max_f32_e32 v206, s62, v206
	v_max_f32_e32 v207, s62, v207
	v_max_f32_e32 v208, s62, v208
	v_max_f32_e32 v209, s62, v209
	v_max_f32_e32 v210, s62, v210
	v_max_f32_e32 v211, s62, v211
	v_max_f32_e32 v212, s62, v212
	v_max_f32_e32 v213, s62, v213
	v_pk_mul_f32 v[206:207], v[206:207], v[214:215]
	v_pk_mul_f32 v[208:209], v[208:209], v[216:217]
	v_pk_mul_f32 v[210:211], v[210:211], v[222:223]
	v_pk_mul_f32 v[212:213], v[212:213], v[224:225]
	v_pk_mul_f32 v[124:125], v[124:125], v[206:207]
	v_pk_mul_f32 v[126:127], v[126:127], v[208:209]
	v_pk_mul_f32 v[120:121], v[120:121], v[210:211]
	v_pk_mul_f32 v[122:123], v[122:123], v[212:213]
	s_waitcnt vmcnt(8)
	v_lshlrev_b32_e32 v206, 16, v166
	v_and_b32_e32 v207, s63, v166
	v_lshlrev_b32_e32 v214, 16, v170
	v_and_b32_e32 v215, s63, v170
	v_lshlrev_b32_e32 v208, 16, v167
	v_and_b32_e32 v209, s63, v167
	v_lshlrev_b32_e32 v216, 16, v171
	v_and_b32_e32 v217, s63, v171
	v_lshlrev_b32_e32 v210, 16, v168
	v_and_b32_e32 v211, s63, v168
	v_lshlrev_b32_e32 v222, 16, v172
	v_and_b32_e32 v223, s63, v172
	v_lshlrev_b32_e32 v212, 16, v169
	v_and_b32_e32 v213, s63, v169
	v_lshlrev_b32_e32 v224, 16, v173
	v_and_b32_e32 v225, s63, v173
	v_max_f32_e32 v214, s62, v214
	v_max_f32_e32 v215, s62, v215
	v_max_f32_e32 v216, s62, v216
	v_max_f32_e32 v217, s62, v217
	v_max_f32_e32 v222, s62, v222
	v_max_f32_e32 v223, s62, v223
	v_max_f32_e32 v224, s62, v224
	v_max_f32_e32 v225, s62, v225
	v_rcp_f32_e32 v214, v214
	v_rcp_f32_e32 v215, v215
	v_rcp_f32_e32 v216, v216
	v_rcp_f32_e32 v217, v217
	v_rcp_f32_e32 v222, v222
	v_rcp_f32_e32 v223, v223
	v_rcp_f32_e32 v224, v224
	v_rcp_f32_e32 v225, v225
	v_max_f32_e32 v206, s62, v206
	v_max_f32_e32 v207, s62, v207
	v_max_f32_e32 v208, s62, v208
	v_max_f32_e32 v209, s62, v209
	v_max_f32_e32 v210, s62, v210
	v_max_f32_e32 v211, s62, v211
	v_max_f32_e32 v212, s62, v212
	v_max_f32_e32 v213, s62, v213
	v_pk_mul_f32 v[206:207], v[206:207], v[214:215]
	v_pk_mul_f32 v[208:209], v[208:209], v[216:217]
	v_pk_mul_f32 v[210:211], v[210:211], v[222:223]
	v_pk_mul_f32 v[212:213], v[212:213], v[224:225]
	v_pk_mul_f32 v[116:117], v[116:117], v[206:207]
	v_pk_mul_f32 v[118:119], v[118:119], v[208:209]
	v_pk_mul_f32 v[112:113], v[112:113], v[210:211]
	v_pk_mul_f32 v[114:115], v[114:115], v[212:213]
	global_load_dwordx4 v[158:161], v[130:131], off offset:-2048
	global_load_dwordx4 v[162:165], v[130:131], off offset:2048
	global_load_dwordx4 v[166:169], v[130:131], off offset:-1792
	global_load_dwordx4 v[170:173], v[130:131], off offset:2304
	v_lshl_add_u64 v[130:131], v[130:131], 0, s[16:17]
	s_waitcnt vmcnt(10)
	v_lshlrev_b32_e32 v206, 16, v174
	v_and_b32_e32 v207, s63, v174
	v_lshlrev_b32_e32 v214, 16, v178
	v_and_b32_e32 v215, s63, v178
	v_lshlrev_b32_e32 v208, 16, v175
	v_and_b32_e32 v209, s63, v175
	v_lshlrev_b32_e32 v216, 16, v179
	v_and_b32_e32 v217, s63, v179
	v_lshlrev_b32_e32 v210, 16, v176
	v_and_b32_e32 v211, s63, v176
	v_lshlrev_b32_e32 v222, 16, v180
	v_and_b32_e32 v223, s63, v180
	v_lshlrev_b32_e32 v212, 16, v177
	v_and_b32_e32 v213, s63, v177
	v_lshlrev_b32_e32 v224, 16, v181
	v_and_b32_e32 v225, s63, v181
	v_max_f32_e32 v214, s62, v214
	v_max_f32_e32 v215, s62, v215
	v_max_f32_e32 v216, s62, v216
	v_max_f32_e32 v217, s62, v217
	v_max_f32_e32 v222, s62, v222
	v_max_f32_e32 v223, s62, v223
	v_max_f32_e32 v224, s62, v224
	v_max_f32_e32 v225, s62, v225
	v_rcp_f32_e32 v214, v214
	v_rcp_f32_e32 v215, v215
	v_rcp_f32_e32 v216, v216
	v_rcp_f32_e32 v217, v217
	v_rcp_f32_e32 v222, v222
	v_rcp_f32_e32 v223, v223
	v_rcp_f32_e32 v224, v224
	v_rcp_f32_e32 v225, v225
	v_max_f32_e32 v206, s62, v206
	v_max_f32_e32 v207, s62, v207
	v_max_f32_e32 v208, s62, v208
	v_max_f32_e32 v209, s62, v209
	v_max_f32_e32 v210, s62, v210
	v_max_f32_e32 v211, s62, v211
	v_max_f32_e32 v212, s62, v212
	v_max_f32_e32 v213, s62, v213
	v_pk_mul_f32 v[206:207], v[206:207], v[214:215]
	v_pk_mul_f32 v[208:209], v[208:209], v[216:217]
	v_pk_mul_f32 v[210:211], v[210:211], v[222:223]
	v_pk_mul_f32 v[212:213], v[212:213], v[224:225]
	v_pk_mul_f32 v[108:109], v[108:109], v[206:207]
	v_pk_mul_f32 v[110:111], v[110:111], v[208:209]
	v_pk_mul_f32 v[104:105], v[104:105], v[210:211]
	v_pk_mul_f32 v[106:107], v[106:107], v[212:213]
	s_waitcnt vmcnt(8)
; DI void unpack8(const u32x4 v, float* x) { x[0] = bflo(v.x); x[1] = bfhi(v.x); x[2] = bflo(v.y); x[3] = bfhi(v.y); x[4] = bflo(v.z); x[5] = bfhi(v.z); x[6] = bflo(v.w); x[7] = bfhi(v.w); }
;     DI void hook(f32x4 (&acc)[2][2][4][2], const Unit& u, int n, int wr, int wc, int fr, int fq) const {
;     ...
;                     float gp[8], gc[8]; unpack8(*(const u32x4*)(G + row * LDP + (size_t)(n - 1) * DM + col), gp); unpack8(*(const u32x4*)(G + row * LDP + (size_t)n * DM + col), gc);
; #pragma unroll
;                     for (int j = 0; j < 4; ++j) { acc[ai][bj][m][0][j] *= fmaxf(gp[j], 1e-30f) * __builtin_amdgcn_rcpf(fmaxf(gc[j], 1e-30f));
;                                                   acc[ai][bj][m][1][j] *= fmaxf(gp[4 + j], 1e-30f) * __builtin_amdgcn_rcpf(fmaxf(gc[4 + j], 1e-30f)); } }
	v_lshlrev_b32_e32 v206, 16, v182
	v_and_b32_e32 v207, s63, v182
	v_lshlrev_b32_e32 v214, 16, v186
	v_and_b32_e32 v215, s63, v186
	v_lshlrev_b32_e32 v208, 16, v183
	v_and_b32_e32 v209, s63, v183
	v_lshlrev_b32_e32 v216, 16, v187
	v_and_b32_e32 v217, s63, v187
	v_lshlrev_b32_e32 v210, 16, v184
	v_and_b32_e32 v211, s63, v184
	v_lshlrev_b32_e32 v222, 16, v188
	v_and_b32_e32 v223, s63, v188
	v_lshlrev_b32_e32 v212, 16, v185
	v_and_b32_e32 v213, s63, v185
	v_lshlrev_b32_e32 v224, 16, v189
	v_and_b32_e32 v225, s63, v189
	v_max_f32_e32 v214, s62, v214
	v_max_f32_e32 v215, s62, v215
	v_max_f32_e32 v216, s62, v216
	v_max_f32_e32 v217, s62, v217
	v_max_f32_e32 v222, s62, v222
	v_max_f32_e32 v223, s62, v223
	v_max_f32_e32 v224, s62, v224
	v_max_f32_e32 v225, s62, v225
	v_rcp_f32_e32 v214, v214
	v_rcp_f32_e32 v215, v215
	v_rcp_f32_e32 v216, v216
	v_rcp_f32_e32 v217, v217
	v_rcp_f32_e32 v222, v222
	v_rcp_f32_e32 v223, v223
	v_rcp_f32_e32 v224, v224
	v_rcp_f32_e32 v225, v225
	v_max_f32_e32 v206, s62, v206
	v_max_f32_e32 v207, s62, v207
	v_max_f32_e32 v208, s62, v208
	v_max_f32_e32 v209, s62, v209
	v_max_f32_e32 v210, s62, v210
	v_max_f32_e32 v211, s62, v211
	v_max_f32_e32 v212, s62, v212
	v_max_f32_e32 v213, s62, v213
	v_pk_mul_f32 v[206:207], v[206:207], v[214:215]
	v_pk_mul_f32 v[208:209], v[208:209], v[216:217]
	v_pk_mul_f32 v[210:211], v[210:211], v[222:223]
	v_pk_mul_f32 v[212:213], v[212:213], v[224:225]
	v_pk_mul_f32 v[100:101], v[100:101], v[206:207]
	v_pk_mul_f32 v[102:103], v[102:103], v[208:209]
	v_pk_mul_f32 v[96:97], v[96:97], v[210:211]
	v_pk_mul_f32 v[98:99], v[98:99], v[212:213]
	global_load_dwordx4 v[174:177], v[130:131], off offset:-2048
	global_load_dwordx4 v[178:181], v[130:131], off offset:2048
	global_load_dwordx4 v[182:185], v[130:131], off offset:-1792
	global_load_dwordx4 v[186:189], v[130:131], off offset:2304
	v_lshl_add_u64 v[130:131], v[130:131], 0, s[30:31]
	s_waitcnt vmcnt(10)
	v_lshlrev_b32_e32 v206, 16, v190
	v_and_b32_e32 v207, s63, v190
	v_lshlrev_b32_e32 v214, 16, v194
	v_and_b32_e32 v215, s63, v194
	v_lshlrev_b32_e32 v208, 16, v191
	v_and_b32_e32 v209, s63, v191
	v_lshlrev_b32_e32 v216, 16, v195
	v_and_b32_e32 v217, s63, v195
	v_lshlrev_b32_e32 v210, 16, v192
	v_and_b32_e32 v211, s63, v192
	v_lshlrev_b32_e32 v222, 16, v196
	v_and_b32_e32 v223, s63, v196
	v_lshlrev_b32_e32 v212, 16, v193
	v_and_b32_e32 v213, s63, v193
	v_lshlrev_b32_e32 v224, 16, v197
	v_and_b32_e32 v225, s63, v197
	v_max_f32_e32 v214, s62, v214
	v_max_f32_e32 v215, s62, v215
	v_max_f32_e32 v216, s62, v216
	v_max_f32_e32 v217, s62, v217
	v_max_f32_e32 v222, s62, v222
	v_max_f32_e32 v223, s62, v223
	v_max_f32_e32 v224, s62, v224
	v_max_f32_e32 v225, s62, v225
	v_rcp_f32_e32 v214, v214
	v_rcp_f32_e32 v215, v215
	v_rcp_f32_e32 v216, v216
	v_rcp_f32_e32 v217, v217
	v_rcp_f32_e32 v222, v222
	v_rcp_f32_e32 v223, v223
	v_rcp_f32_e32 v224, v224
	v_rcp_f32_e32 v225, v225
	v_max_f32_e32 v206, s62, v206
	v_max_f32_e32 v207, s62, v207
	v_max_f32_e32 v208, s62, v208
	v_max_f32_e32 v209, s62, v209
	v_max_f32_e32 v210, s62, v210
	v_max_f32_e32 v211, s62, v211
	v_max_f32_e32 v212, s62, v212
	v_max_f32_e32 v213, s62, v213
	v_pk_mul_f32 v[206:207], v[206:207], v[214:215]
	v_pk_mul_f32 v[208:209], v[208:209], v[216:217]
	v_pk_mul_f32 v[210:211], v[210:211], v[222:223]
	v_pk_mul_f32 v[212:213], v[212:213], v[224:225]
	v_pk_mul_f32 v[92:93], v[92:93], v[206:207]
	v_pk_mul_f32 v[94:95], v[94:95], v[208:209]
	v_pk_mul_f32 v[88:89], v[88:89], v[210:211]
	v_pk_mul_f32 v[90:91], v[90:91], v[212:213]
	s_waitcnt vmcnt(8)
	v_lshlrev_b32_e32 v206, 16, v198
	v_and_b32_e32 v207, s63, v198
	v_lshlrev_b32_e32 v214, 16, v202
	v_and_b32_e32 v215, s63, v202
	v_lshlrev_b32_e32 v208, 16, v199
	v_and_b32_e32 v209, s63, v199
	v_lshlrev_b32_e32 v216, 16, v203
	v_and_b32_e32 v217, s63, v203
	v_lshlrev_b32_e32 v210, 16, v200
	v_and_b32_e32 v211, s63, v200
	v_lshlrev_b32_e32 v222, 16, v204
	v_and_b32_e32 v223, s63, v204
	v_lshlrev_b32_e32 v212, 16, v201
	v_and_b32_e32 v213, s63, v201
	v_lshlrev_b32_e32 v224, 16, v205
	v_and_b32_e32 v225, s63, v205
	v_max_f32_e32 v214, s62, v214
	v_max_f32_e32 v215, s62, v215
	v_max_f32_e32 v216, s62, v216
	v_max_f32_e32 v217, s62, v217
	v_max_f32_e32 v222, s62, v222
	v_max_f32_e32 v223, s62, v223
	v_max_f32_e32 v224, s62, v224
	v_max_f32_e32 v225, s62, v225
	v_rcp_f32_e32 v214, v214
	v_rcp_f32_e32 v215, v215
	v_rcp_f32_e32 v216, v216
	v_rcp_f32_e32 v217, v217
	v_rcp_f32_e32 v222, v222
	v_rcp_f32_e32 v223, v223
	v_rcp_f32_e32 v224, v224
	v_rcp_f32_e32 v225, v225
	v_max_f32_e32 v206, s62, v206
	v_max_f32_e32 v207, s62, v207
	v_max_f32_e32 v208, s62, v208
	v_max_f32_e32 v209, s62, v209
	v_max_f32_e32 v210, s62, v210
	v_max_f32_e32 v211, s62, v211
	v_max_f32_e32 v212, s62, v212
	v_max_f32_e32 v213, s62, v213
	v_pk_mul_f32 v[206:207], v[206:207], v[214:215]
	v_pk_mul_f32 v[208:209], v[208:209], v[216:217]
	v_pk_mul_f32 v[210:211], v[210:211], v[222:223]
	v_pk_mul_f32 v[212:213], v[212:213], v[224:225]
	v_pk_mul_f32 v[84:85], v[84:85], v[206:207]
	v_pk_mul_f32 v[86:87], v[86:87], v[208:209]
	v_pk_mul_f32 v[80:81], v[80:81], v[210:211]
	v_pk_mul_f32 v[82:83], v[82:83], v[212:213]
	global_load_dwordx4 v[190:193], v[130:131], off offset:-2048
	global_load_dwordx4 v[194:197], v[130:131], off offset:2048
	global_load_dwordx4 v[198:201], v[130:131], off offset:-1792
	global_load_dwordx4 v[202:205], v[130:131], off offset:2304
	v_lshl_add_u64 v[130:131], v[130:131], 0, s[30:31]
	s_waitcnt vmcnt(10)
; DI void unpack8(const u32x4 v, float* x) { x[0] = bflo(v.x); x[1] = bfhi(v.x); x[2] = bflo(v.y); x[3] = bfhi(v.y); x[4] = bflo(v.z); x[5] = bfhi(v.z); x[6] = bflo(v.w); x[7] = bfhi(v.w); }
;     DI void hook(f32x4 (&acc)[2][2][4][2], const Unit& u, int n, int wr, int wc, int fr, int fq) const {
;     ...
;                     float gp[8], gc[8]; unpack8(*(const u32x4*)(G + row * LDP + (size_t)(n - 1) * DM + col), gp); unpack8(*(const u32x4*)(G + row * LDP + (size_t)n * DM + col), gc);
; #pragma unroll
;                     for (int j = 0; j < 4; ++j) { acc[ai][bj][m][0][j] *= fmaxf(gp[j], 1e-30f) * __builtin_amdgcn_rcpf(fmaxf(gc[j], 1e-30f));
;                                                   acc[ai][bj][m][1][j] *= fmaxf(gp[4 + j], 1e-30f) * __builtin_amdgcn_rcpf(fmaxf(gc[4 + j], 1e-30f)); } }
	v_lshlrev_b32_e32 v206, 16, v158
	v_and_b32_e32 v207, s63, v158
	v_lshlrev_b32_e32 v214, 16, v162
	v_and_b32_e32 v215, s63, v162
	v_lshlrev_b32_e32 v208, 16, v159
	v_and_b32_e32 v209, s63, v159
	v_lshlrev_b32_e32 v216, 16, v163
	v_and_b32_e32 v217, s63, v163
	v_lshlrev_b32_e32 v210, 16, v160
	v_and_b32_e32 v211, s63, v160
	v_lshlrev_b32_e32 v222, 16, v164
	v_and_b32_e32 v223, s63, v164
	v_lshlrev_b32_e32 v212, 16, v161
	v_and_b32_e32 v213, s63, v161
	v_lshlrev_b32_e32 v224, 16, v165
	v_and_b32_e32 v225, s63, v165
	v_max_f32_e32 v214, s62, v214
	v_max_f32_e32 v215, s62, v215
	v_max_f32_e32 v216, s62, v216
	v_max_f32_e32 v217, s62, v217
	v_max_f32_e32 v222, s62, v222
	v_max_f32_e32 v223, s62, v223
	v_max_f32_e32 v224, s62, v224
	v_max_f32_e32 v225, s62, v225
	v_rcp_f32_e32 v214, v214
	v_rcp_f32_e32 v215, v215
	v_rcp_f32_e32 v216, v216
	v_rcp_f32_e32 v217, v217
	v_rcp_f32_e32 v222, v222
	v_rcp_f32_e32 v223, v223
	v_rcp_f32_e32 v224, v224
	v_rcp_f32_e32 v225, v225
	v_max_f32_e32 v206, s62, v206
	v_max_f32_e32 v207, s62, v207
	v_max_f32_e32 v208, s62, v208
	v_max_f32_e32 v209, s62, v209
	v_max_f32_e32 v210, s62, v210
	v_max_f32_e32 v211, s62, v211
	v_max_f32_e32 v212, s62, v212
	v_max_f32_e32 v213, s62, v213
	v_pk_mul_f32 v[206:207], v[206:207], v[214:215]
	v_pk_mul_f32 v[208:209], v[208:209], v[216:217]
	v_pk_mul_f32 v[210:211], v[210:211], v[222:223]
	v_pk_mul_f32 v[212:213], v[212:213], v[224:225]
	v_pk_mul_f32 v[76:77], v[76:77], v[206:207]
	v_pk_mul_f32 v[78:79], v[78:79], v[208:209]
	v_pk_mul_f32 v[72:73], v[72:73], v[210:211]
	v_pk_mul_f32 v[74:75], v[74:75], v[212:213]
	s_waitcnt vmcnt(8)
	v_lshlrev_b32_e32 v206, 16, v166
	v_and_b32_e32 v207, s63, v166
	v_lshlrev_b32_e32 v214, 16, v170
	v_and_b32_e32 v215, s63, v170
	v_lshlrev_b32_e32 v208, 16, v167
	v_and_b32_e32 v209, s63, v167
	v_lshlrev_b32_e32 v216, 16, v171
	v_and_b32_e32 v217, s63, v171
	v_lshlrev_b32_e32 v210, 16, v168
	v_and_b32_e32 v211, s63, v168
	v_lshlrev_b32_e32 v222, 16, v172
	v_and_b32_e32 v223, s63, v172
	v_lshlrev_b32_e32 v212, 16, v169
	v_and_b32_e32 v213, s63, v169
	v_lshlrev_b32_e32 v224, 16, v173
	v_and_b32_e32 v225, s63, v173
	v_max_f32_e32 v214, s62, v214
	v_max_f32_e32 v215, s62, v215
	v_max_f32_e32 v216, s62, v216
	v_max_f32_e32 v217, s62, v217
	v_max_f32_e32 v222, s62, v222
	v_max_f32_e32 v223, s62, v223
	v_max_f32_e32 v224, s62, v224
	v_max_f32_e32 v225, s62, v225
	v_rcp_f32_e32 v214, v214
	v_rcp_f32_e32 v215, v215
	v_rcp_f32_e32 v216, v216
	v_rcp_f32_e32 v217, v217
	v_rcp_f32_e32 v222, v222
	v_rcp_f32_e32 v223, v223
	v_rcp_f32_e32 v224, v224
	v_rcp_f32_e32 v225, v225
	v_max_f32_e32 v206, s62, v206
	v_max_f32_e32 v207, s62, v207
	v_max_f32_e32 v208, s62, v208
	v_max_f32_e32 v209, s62, v209
	v_max_f32_e32 v210, s62, v210
	v_max_f32_e32 v211, s62, v211
	v_max_f32_e32 v212, s62, v212
	v_max_f32_e32 v213, s62, v213
	v_pk_mul_f32 v[206:207], v[206:207], v[214:215]
	v_pk_mul_f32 v[208:209], v[208:209], v[216:217]
	v_pk_mul_f32 v[210:211], v[210:211], v[222:223]
	v_pk_mul_f32 v[212:213], v[212:213], v[224:225]
	v_pk_mul_f32 v[68:69], v[68:69], v[206:207]
	v_pk_mul_f32 v[70:71], v[70:71], v[208:209]
	v_pk_mul_f32 v[64:65], v[64:65], v[210:211]
	v_pk_mul_f32 v[66:67], v[66:67], v[212:213]
	global_load_dwordx4 v[158:161], v[130:131], off offset:-2048
	global_load_dwordx4 v[162:165], v[130:131], off offset:2048
	global_load_dwordx4 v[166:169], v[130:131], off offset:-1792
	global_load_dwordx4 v[170:173], v[130:131], off offset:2304
	v_lshl_add_u64 v[130:131], v[130:131], 0, s[30:31]
	s_waitcnt vmcnt(10)
	v_lshlrev_b32_e32 v206, 16, v174
	v_and_b32_e32 v207, s63, v174
	v_lshlrev_b32_e32 v214, 16, v178
	v_and_b32_e32 v215, s63, v178
	v_lshlrev_b32_e32 v208, 16, v175
	v_and_b32_e32 v209, s63, v175
	v_lshlrev_b32_e32 v216, 16, v179
	v_and_b32_e32 v217, s63, v179
	v_lshlrev_b32_e32 v210, 16, v176
	v_and_b32_e32 v211, s63, v176
	v_lshlrev_b32_e32 v222, 16, v180
	v_and_b32_e32 v223, s63, v180
	v_lshlrev_b32_e32 v212, 16, v177
	v_and_b32_e32 v213, s63, v177
	v_lshlrev_b32_e32 v224, 16, v181
	v_and_b32_e32 v225, s63, v181
	v_max_f32_e32 v214, s62, v214
	v_max_f32_e32 v215, s62, v215
	v_max_f32_e32 v216, s62, v216
	v_max_f32_e32 v217, s62, v217
	v_max_f32_e32 v222, s62, v222
	v_max_f32_e32 v223, s62, v223
	v_max_f32_e32 v224, s62, v224
	v_max_f32_e32 v225, s62, v225
	v_rcp_f32_e32 v214, v214
	v_rcp_f32_e32 v215, v215
	v_rcp_f32_e32 v216, v216
	v_rcp_f32_e32 v217, v217
	v_rcp_f32_e32 v222, v222
	v_rcp_f32_e32 v223, v223
	v_rcp_f32_e32 v224, v224
	v_rcp_f32_e32 v225, v225
	v_max_f32_e32 v206, s62, v206
	v_max_f32_e32 v207, s62, v207
	v_max_f32_e32 v208, s62, v208
	v_max_f32_e32 v209, s62, v209
	v_max_f32_e32 v210, s62, v210
	v_max_f32_e32 v211, s62, v211
	v_max_f32_e32 v212, s62, v212
	v_max_f32_e32 v213, s62, v213
	v_pk_mul_f32 v[206:207], v[206:207], v[214:215]
	v_pk_mul_f32 v[208:209], v[208:209], v[216:217]
	v_pk_mul_f32 v[210:211], v[210:211], v[222:223]
	v_pk_mul_f32 v[212:213], v[212:213], v[224:225]
	v_pk_mul_f32 v[60:61], v[60:61], v[206:207]
	v_pk_mul_f32 v[62:63], v[62:63], v[208:209]
	v_pk_mul_f32 v[56:57], v[56:57], v[210:211]
	v_pk_mul_f32 v[58:59], v[58:59], v[212:213]
	s_waitcnt vmcnt(8)
; DI void unpack8(const u32x4 v, float* x) { x[0] = bflo(v.x); x[1] = bfhi(v.x); x[2] = bflo(v.y); x[3] = bfhi(v.y); x[4] = bflo(v.z); x[5] = bfhi(v.z); x[6] = bflo(v.w); x[7] = bfhi(v.w); }
;     DI void hook(f32x4 (&acc)[2][2][4][2], const Unit& u, int n, int wr, int wc, int fr, int fq) const {
;     ...
;                     float gp[8], gc[8]; unpack8(*(const u32x4*)(G + row * LDP + (size_t)(n - 1) * DM + col), gp); unpack8(*(const u32x4*)(G + row * LDP + (size_t)n * DM + col), gc);
; #pragma unroll
;                     for (int j = 0; j < 4; ++j) { acc[ai][bj][m][0][j] *= fmaxf(gp[j], 1e-30f) * __builtin_amdgcn_rcpf(fmaxf(gc[j], 1e-30f));
;                                                   acc[ai][bj][m][1][j] *= fmaxf(gp[4 + j], 1e-30f) * __builtin_amdgcn_rcpf(fmaxf(gc[4 + j], 1e-30f)); } }
	v_lshlrev_b32_e32 v206, 16, v182
	v_and_b32_e32 v207, s63, v182
	v_lshlrev_b32_e32 v214, 16, v186
	v_and_b32_e32 v215, s63, v186
	v_lshlrev_b32_e32 v208, 16, v183
	v_and_b32_e32 v209, s63, v183
	v_lshlrev_b32_e32 v216, 16, v187
	v_and_b32_e32 v217, s63, v187
	v_lshlrev_b32_e32 v210, 16, v184
	v_and_b32_e32 v211, s63, v184
	v_lshlrev_b32_e32 v222, 16, v188
	v_and_b32_e32 v223, s63, v188
	v_lshlrev_b32_e32 v212, 16, v185
	v_and_b32_e32 v213, s63, v185
	v_lshlrev_b32_e32 v224, 16, v189
	v_and_b32_e32 v225, s63, v189
	v_max_f32_e32 v214, s62, v214
	v_max_f32_e32 v215, s62, v215
	v_max_f32_e32 v216, s62, v216
	v_max_f32_e32 v217, s62, v217
	v_max_f32_e32 v222, s62, v222
	v_max_f32_e32 v223, s62, v223
	v_max_f32_e32 v224, s62, v224
	v_max_f32_e32 v225, s62, v225
	v_rcp_f32_e32 v214, v214
	v_rcp_f32_e32 v215, v215
	v_rcp_f32_e32 v216, v216
	v_rcp_f32_e32 v217, v217
	v_rcp_f32_e32 v222, v222
	v_rcp_f32_e32 v223, v223
	v_rcp_f32_e32 v224, v224
	v_rcp_f32_e32 v225, v225
	v_max_f32_e32 v206, s62, v206
	v_max_f32_e32 v207, s62, v207
	v_max_f32_e32 v208, s62, v208
	v_max_f32_e32 v209, s62, v209
	v_max_f32_e32 v210, s62, v210
	v_max_f32_e32 v211, s62, v211
	v_max_f32_e32 v212, s62, v212
	v_max_f32_e32 v213, s62, v213
	v_pk_mul_f32 v[206:207], v[206:207], v[214:215]
	v_pk_mul_f32 v[208:209], v[208:209], v[216:217]
	v_pk_mul_f32 v[210:211], v[210:211], v[222:223]
	v_pk_mul_f32 v[212:213], v[212:213], v[224:225]
	v_pk_mul_f32 v[52:53], v[52:53], v[206:207]
	v_pk_mul_f32 v[54:55], v[54:55], v[208:209]
	v_pk_mul_f32 v[48:49], v[48:49], v[210:211]
	v_pk_mul_f32 v[50:51], v[50:51], v[212:213]
	global_load_dwordx4 v[174:177], v[130:131], off offset:-2048
	global_load_dwordx4 v[178:181], v[130:131], off offset:2048
	global_load_dwordx4 v[182:185], v[130:131], off offset:-1792
	global_load_dwordx4 v[186:189], v[130:131], off offset:2304
	s_waitcnt vmcnt(10)
	v_lshlrev_b32_e32 v206, 16, v190
	v_and_b32_e32 v207, s63, v190
	v_lshlrev_b32_e32 v214, 16, v194
	v_and_b32_e32 v215, s63, v194
	v_lshlrev_b32_e32 v208, 16, v191
	v_and_b32_e32 v209, s63, v191
	v_lshlrev_b32_e32 v216, 16, v195
	v_and_b32_e32 v217, s63, v195
	v_lshlrev_b32_e32 v210, 16, v192
	v_and_b32_e32 v211, s63, v192
	v_lshlrev_b32_e32 v222, 16, v196
	v_and_b32_e32 v223, s63, v196
	v_lshlrev_b32_e32 v212, 16, v193
	v_and_b32_e32 v213, s63, v193
	v_lshlrev_b32_e32 v224, 16, v197
	v_and_b32_e32 v225, s63, v197
	v_max_f32_e32 v214, s62, v214
	v_max_f32_e32 v215, s62, v215
	v_max_f32_e32 v216, s62, v216
	v_max_f32_e32 v217, s62, v217
	v_max_f32_e32 v222, s62, v222
	v_max_f32_e32 v223, s62, v223
	v_max_f32_e32 v224, s62, v224
	v_max_f32_e32 v225, s62, v225
	v_rcp_f32_e32 v214, v214
	v_rcp_f32_e32 v215, v215
	v_rcp_f32_e32 v216, v216
	v_rcp_f32_e32 v217, v217
	v_rcp_f32_e32 v222, v222
	v_rcp_f32_e32 v223, v223
	v_rcp_f32_e32 v224, v224
	v_rcp_f32_e32 v225, v225
	v_max_f32_e32 v206, s62, v206
	v_max_f32_e32 v207, s62, v207
	v_max_f32_e32 v208, s62, v208
	v_max_f32_e32 v209, s62, v209
	v_max_f32_e32 v210, s62, v210
	v_max_f32_e32 v211, s62, v211
	v_max_f32_e32 v212, s62, v212
	v_max_f32_e32 v213, s62, v213
	v_pk_mul_f32 v[206:207], v[206:207], v[214:215]
	v_pk_mul_f32 v[208:209], v[208:209], v[216:217]
	v_pk_mul_f32 v[210:211], v[210:211], v[222:223]
	v_pk_mul_f32 v[212:213], v[212:213], v[224:225]
	v_pk_mul_f32 v[44:45], v[44:45], v[206:207]
	v_pk_mul_f32 v[46:47], v[46:47], v[208:209]
	v_pk_mul_f32 v[40:41], v[40:41], v[210:211]
	v_pk_mul_f32 v[42:43], v[42:43], v[212:213]
	s_waitcnt vmcnt(8)
	v_lshlrev_b32_e32 v206, 16, v198
	v_and_b32_e32 v207, s63, v198
	v_lshlrev_b32_e32 v214, 16, v202
	v_and_b32_e32 v215, s63, v202
	v_lshlrev_b32_e32 v208, 16, v199
	v_and_b32_e32 v209, s63, v199
	v_lshlrev_b32_e32 v216, 16, v203
	v_and_b32_e32 v217, s63, v203
	v_lshlrev_b32_e32 v210, 16, v200
	v_and_b32_e32 v211, s63, v200
	v_lshlrev_b32_e32 v222, 16, v204
	v_and_b32_e32 v223, s63, v204
	v_lshlrev_b32_e32 v212, 16, v201
	v_and_b32_e32 v213, s63, v201
	v_lshlrev_b32_e32 v224, 16, v205
	v_and_b32_e32 v225, s63, v205
	v_max_f32_e32 v214, s62, v214
	v_max_f32_e32 v215, s62, v215
	v_max_f32_e32 v216, s62, v216
	v_max_f32_e32 v217, s62, v217
	v_max_f32_e32 v222, s62, v222
	v_max_f32_e32 v223, s62, v223
	v_max_f32_e32 v224, s62, v224
	v_max_f32_e32 v225, s62, v225
	v_rcp_f32_e32 v214, v214
	v_rcp_f32_e32 v215, v215
	v_rcp_f32_e32 v216, v216
	v_rcp_f32_e32 v217, v217
	v_rcp_f32_e32 v222, v222
	v_rcp_f32_e32 v223, v223
	v_rcp_f32_e32 v224, v224
	v_rcp_f32_e32 v225, v225
	v_max_f32_e32 v206, s62, v206
	v_max_f32_e32 v207, s62, v207
	v_max_f32_e32 v208, s62, v208
	v_max_f32_e32 v209, s62, v209
	v_max_f32_e32 v210, s62, v210
	v_max_f32_e32 v211, s62, v211
	v_max_f32_e32 v212, s62, v212
	v_max_f32_e32 v213, s62, v213
	v_pk_mul_f32 v[206:207], v[206:207], v[214:215]
	v_pk_mul_f32 v[208:209], v[208:209], v[216:217]
	v_pk_mul_f32 v[210:211], v[210:211], v[222:223]
	v_pk_mul_f32 v[212:213], v[212:213], v[224:225]
	v_pk_mul_f32 v[36:37], v[36:37], v[206:207]
	v_pk_mul_f32 v[38:39], v[38:39], v[208:209]
	v_pk_mul_f32 v[32:33], v[32:33], v[210:211]
	v_pk_mul_f32 v[34:35], v[34:35], v[212:213]
	s_waitcnt vmcnt(6)
; DI void unpack8(const u32x4 v, float* x) { x[0] = bflo(v.x); x[1] = bfhi(v.x); x[2] = bflo(v.y); x[3] = bfhi(v.y); x[4] = bflo(v.z); x[5] = bfhi(v.z); x[6] = bflo(v.w); x[7] = bfhi(v.w); }
;     DI void hook(f32x4 (&acc)[2][2][4][2], const Unit& u, int n, int wr, int wc, int fr, int fq) const {
;     ...
;                     float gp[8], gc[8]; unpack8(*(const u32x4*)(G + row * LDP + (size_t)(n - 1) * DM + col), gp); unpack8(*(const u32x4*)(G + row * LDP + (size_t)n * DM + col), gc);
; #pragma unroll
;                     for (int j = 0; j < 4; ++j) { acc[ai][bj][m][0][j] *= fmaxf(gp[j], 1e-30f) * __builtin_amdgcn_rcpf(fmaxf(gc[j], 1e-30f));
;                                                   acc[ai][bj][m][1][j] *= fmaxf(gp[4 + j], 1e-30f) * __builtin_amdgcn_rcpf(fmaxf(gc[4 + j], 1e-30f)); } }
;                 if (m & 1) asm volatile("" ::: "memory"); }
;         }
;     }
	v_lshlrev_b32_e32 v206, 16, v158
	v_and_b32_e32 v207, s63, v158
	v_lshlrev_b32_e32 v214, 16, v162
	v_and_b32_e32 v215, s63, v162
	v_lshlrev_b32_e32 v208, 16, v159
	v_and_b32_e32 v209, s63, v159
	v_lshlrev_b32_e32 v216, 16, v163
	v_and_b32_e32 v217, s63, v163
	v_lshlrev_b32_e32 v210, 16, v160
	v_and_b32_e32 v211, s63, v160
	v_lshlrev_b32_e32 v222, 16, v164
	v_and_b32_e32 v223, s63, v164
	v_lshlrev_b32_e32 v212, 16, v161
	v_and_b32_e32 v213, s63, v161
	v_lshlrev_b32_e32 v224, 16, v165
	v_and_b32_e32 v225, s63, v165
	v_max_f32_e32 v214, s62, v214
	v_max_f32_e32 v215, s62, v215
	v_max_f32_e32 v216, s62, v216
	v_max_f32_e32 v217, s62, v217
	v_max_f32_e32 v222, s62, v222
	v_max_f32_e32 v223, s62, v223
	v_max_f32_e32 v224, s62, v224
	v_max_f32_e32 v225, s62, v225
	v_rcp_f32_e32 v214, v214
	v_rcp_f32_e32 v215, v215
	v_rcp_f32_e32 v216, v216
	v_rcp_f32_e32 v217, v217
	v_rcp_f32_e32 v222, v222
	v_rcp_f32_e32 v223, v223
	v_rcp_f32_e32 v224, v224
	v_rcp_f32_e32 v225, v225
	v_max_f32_e32 v206, s62, v206
	v_max_f32_e32 v207, s62, v207
	v_max_f32_e32 v208, s62, v208
	v_max_f32_e32 v209, s62, v209
	v_max_f32_e32 v210, s62, v210
	v_max_f32_e32 v211, s62, v211
	v_max_f32_e32 v212, s62, v212
	v_max_f32_e32 v213, s62, v213
	v_pk_mul_f32 v[206:207], v[206:207], v[214:215]
	v_pk_mul_f32 v[208:209], v[208:209], v[216:217]
	v_pk_mul_f32 v[210:211], v[210:211], v[222:223]
	v_pk_mul_f32 v[212:213], v[212:213], v[224:225]
	v_pk_mul_f32 v[28:29], v[28:29], v[206:207]
	v_pk_mul_f32 v[30:31], v[30:31], v[208:209]
	v_pk_mul_f32 v[24:25], v[24:25], v[210:211]
	v_pk_mul_f32 v[26:27], v[26:27], v[212:213]
	s_waitcnt vmcnt(4)
	v_lshlrev_b32_e32 v206, 16, v166
	v_and_b32_e32 v207, s63, v166
	v_lshlrev_b32_e32 v214, 16, v170
	v_and_b32_e32 v215, s63, v170
	v_lshlrev_b32_e32 v208, 16, v167
	v_and_b32_e32 v209, s63, v167
	v_lshlrev_b32_e32 v216, 16, v171
	v_and_b32_e32 v217, s63, v171
	v_lshlrev_b32_e32 v210, 16, v168
	v_and_b32_e32 v211, s63, v168
	v_lshlrev_b32_e32 v222, 16, v172
	v_and_b32_e32 v223, s63, v172
	v_lshlrev_b32_e32 v212, 16, v169
	v_and_b32_e32 v213, s63, v169
	v_lshlrev_b32_e32 v224, 16, v173
	v_and_b32_e32 v225, s63, v173
	v_max_f32_e32 v214, s62, v214
	v_max_f32_e32 v215, s62, v215
	v_max_f32_e32 v216, s62, v216
	v_max_f32_e32 v217, s62, v217
	v_max_f32_e32 v222, s62, v222
	v_max_f32_e32 v223, s62, v223
	v_max_f32_e32 v224, s62, v224
	v_max_f32_e32 v225, s62, v225
	v_rcp_f32_e32 v214, v214
	v_rcp_f32_e32 v215, v215
	v_rcp_f32_e32 v216, v216
	v_rcp_f32_e32 v217, v217
	v_rcp_f32_e32 v222, v222
	v_rcp_f32_e32 v223, v223
	v_rcp_f32_e32 v224, v224
	v_rcp_f32_e32 v225, v225
	v_max_f32_e32 v206, s62, v206
	v_max_f32_e32 v207, s62, v207
	v_max_f32_e32 v208, s62, v208
	v_max_f32_e32 v209, s62, v209
	v_max_f32_e32 v210, s62, v210
	v_max_f32_e32 v211, s62, v211
	v_max_f32_e32 v212, s62, v212
	v_max_f32_e32 v213, s62, v213
	v_pk_mul_f32 v[206:207], v[206:207], v[214:215]
	v_pk_mul_f32 v[208:209], v[208:209], v[216:217]
	v_pk_mul_f32 v[210:211], v[210:211], v[222:223]
	v_pk_mul_f32 v[212:213], v[212:213], v[224:225]
	v_pk_mul_f32 v[20:21], v[20:21], v[206:207]
	v_pk_mul_f32 v[22:23], v[22:23], v[208:209]
	v_pk_mul_f32 v[16:17], v[16:17], v[210:211]
	v_pk_mul_f32 v[18:19], v[18:19], v[212:213]
	s_waitcnt vmcnt(2)
	v_lshlrev_b32_e32 v206, 16, v174
	v_and_b32_e32 v207, s63, v174
	v_lshlrev_b32_e32 v214, 16, v178
	v_and_b32_e32 v215, s63, v178
	v_lshlrev_b32_e32 v208, 16, v175
	v_and_b32_e32 v209, s63, v175
	v_lshlrev_b32_e32 v216, 16, v179
	v_and_b32_e32 v217, s63, v179
	v_lshlrev_b32_e32 v210, 16, v176
	v_and_b32_e32 v211, s63, v176
	v_lshlrev_b32_e32 v222, 16, v180
	v_and_b32_e32 v223, s63, v180
	v_lshlrev_b32_e32 v212, 16, v177
	v_and_b32_e32 v213, s63, v177
	v_lshlrev_b32_e32 v224, 16, v181
	v_and_b32_e32 v225, s63, v181
	v_max_f32_e32 v214, s62, v214
	v_max_f32_e32 v215, s62, v215
	v_max_f32_e32 v216, s62, v216
	v_max_f32_e32 v217, s62, v217
	v_max_f32_e32 v222, s62, v222
	v_max_f32_e32 v223, s62, v223
	v_max_f32_e32 v224, s62, v224
	v_max_f32_e32 v225, s62, v225
	v_rcp_f32_e32 v214, v214
	v_rcp_f32_e32 v215, v215
	v_rcp_f32_e32 v216, v216
	v_rcp_f32_e32 v217, v217
	v_rcp_f32_e32 v222, v222
	v_rcp_f32_e32 v223, v223
	v_rcp_f32_e32 v224, v224
	v_rcp_f32_e32 v225, v225
	v_max_f32_e32 v206, s62, v206
	v_max_f32_e32 v207, s62, v207
	v_max_f32_e32 v208, s62, v208
	v_max_f32_e32 v209, s62, v209
	v_max_f32_e32 v210, s62, v210
	v_max_f32_e32 v211, s62, v211
	v_max_f32_e32 v212, s62, v212
	v_max_f32_e32 v213, s62, v213
	v_pk_mul_f32 v[206:207], v[206:207], v[214:215]
	v_pk_mul_f32 v[208:209], v[208:209], v[216:217]
	v_pk_mul_f32 v[210:211], v[210:211], v[222:223]
	v_pk_mul_f32 v[212:213], v[212:213], v[224:225]
	v_pk_mul_f32 v[12:13], v[12:13], v[206:207]
	v_pk_mul_f32 v[14:15], v[14:15], v[208:209]
	v_pk_mul_f32 v[8:9], v[8:9], v[210:211]
	v_pk_mul_f32 v[10:11], v[10:11], v[212:213]
	s_waitcnt vmcnt(0)
	v_lshlrev_b32_e32 v206, 16, v182
	v_and_b32_e32 v207, s63, v182
	v_lshlrev_b32_e32 v214, 16, v186
	v_and_b32_e32 v215, s63, v186
	v_lshlrev_b32_e32 v208, 16, v183
	v_and_b32_e32 v209, s63, v183
	v_lshlrev_b32_e32 v216, 16, v187
	v_and_b32_e32 v217, s63, v187
	v_lshlrev_b32_e32 v210, 16, v184
	v_and_b32_e32 v211, s63, v184
	v_lshlrev_b32_e32 v222, 16, v188
	v_and_b32_e32 v223, s63, v188
	v_lshlrev_b32_e32 v212, 16, v185
	v_and_b32_e32 v213, s63, v185
	v_lshlrev_b32_e32 v224, 16, v189
	v_and_b32_e32 v225, s63, v189
	v_max_f32_e32 v214, s62, v214
	v_max_f32_e32 v215, s62, v215
	v_max_f32_e32 v216, s62, v216
	v_max_f32_e32 v217, s62, v217
	v_max_f32_e32 v222, s62, v222
	v_max_f32_e32 v223, s62, v223
	v_max_f32_e32 v224, s62, v224
	v_max_f32_e32 v225, s62, v225
	v_rcp_f32_e32 v214, v214
	v_rcp_f32_e32 v215, v215
	v_rcp_f32_e32 v216, v216
	v_rcp_f32_e32 v217, v217
	v_rcp_f32_e32 v222, v222
	v_rcp_f32_e32 v223, v223
	v_rcp_f32_e32 v224, v224
	v_rcp_f32_e32 v225, v225
	v_max_f32_e32 v206, s62, v206
	v_max_f32_e32 v207, s62, v207
	v_max_f32_e32 v208, s62, v208
	v_max_f32_e32 v209, s62, v209
	v_max_f32_e32 v210, s62, v210
	v_max_f32_e32 v211, s62, v211
	v_max_f32_e32 v212, s62, v212
	v_max_f32_e32 v213, s62, v213
	v_pk_mul_f32 v[206:207], v[206:207], v[214:215]
	v_pk_mul_f32 v[208:209], v[208:209], v[216:217]
	v_pk_mul_f32 v[210:211], v[210:211], v[222:223]
	v_pk_mul_f32 v[212:213], v[212:213], v[224:225]
	v_pk_mul_f32 v[4:5], v[4:5], v[206:207]
	v_pk_mul_f32 v[6:7], v[6:7], v[208:209]
	v_pk_mul_f32 v[0:1], v[0:1], v[210:211]
	v_pk_mul_f32 v[2:3], v[2:3], v[212:213]
	s_branch .LBB0_712

; #define PG8_STAGE(bufoff, gbase, voff) do { _Pragma("unroll") for (int _i = 0; _i < 2; ++_i) \
;         __builtin_amdgcn_global_load_lds((const unsigned*)((const char*)(gbase) + (voff)[_i]), (LAS unsigned*)(lds + (bufoff) + ldsw + _i * 8192), 16, 0, 0); } while (0)
; #define PG8_LDA(dst, b, h) do { _Pragma("unroll") for (int m = 0; m < 4; ++m) _Pragma("unroll") for (int k = 0; k < 2; ++k) dst[m][k] = *(const LAS bf16x8*)(lds + PG8_SA(b, h) + aoff + m * 2048 + k * 1024); } while (0)
; #define PG8_LDB(dst, b, h) do { _Pragma("unroll") for (int n = 0; n < 2; ++n) _Pragma("unroll") for (int k = 0; k < 2; ++k) dst[n][k] = *(const LAS bf16x8*)(lds + PG8_SB(b, h) + boff + n * 2048 + k * 1024); } while (0)
; #define PG8_MMA(ai, bj, At, Bt) do { __builtin_amdgcn_s_setprio(1); _Pragma("unroll") for (int m = 0; m < 4; ++m) _Pragma("unroll") for (int n = 0; n < 2; ++n) _Pragma("unroll") for (int k = 0; k < 2; ++k) \
;         acc[ai][bj][m][n] = __builtin_amdgcn_mfma_f32_16x16x32_bf16(Bt[n][k], At[m][k], acc[ai][bj][m][n], 0, 0, 0); __builtin_amdgcn_s_setprio(0); } while (0)
; #define PG8_WAIT_V(n) asm volatile("s_waitcnt vmcnt(" #n ")" ::: "memory")
; #define PG8_WAIT_L(n) asm volatile("s_waitcnt lgkmcnt(" #n ")" ::: "memory")
; #define PG8_BAR __builtin_amdgcn_s_barrier()
; #define PG8_SCHED __builtin_amdgcn_sched_barrier(0)
; template <class Epi, class Sched>
; DI void gemm_phase(LAS unsigned char* lds, const int tid, const int K, const int lda, const int ldb, const Sched& S_, const Epi& E) {
;     ...
;             const bool last = (t == nt - 2);
;             const char* a1 = cA + (size_t)(t + 1) * kstep;
;             const char* a2 = last ? nA : cA + (size_t)(t + 2) * kstep; const char* b2 = last ? nB : cB + (size_t)(t + 2) * kstep;
;             const char* a3 = a2 + kstep; const char* b3 = b2 + kstep;
;             PG8_LDB(B0, 0, 0); PG8_LDB(B1, 0, 1); PG8_SCHED; PG8_LDA(At, 0, 0); PG8_STAGE(PG8_SA(1, 1), a1 + hstepA, voffA);
;             PG8_WAIT_V(8); PG8_WAIT_L(0); PG8_BAR; PG8_MMA(0, 0, At, B0); PG8_MMA(0, 1, At, B1); PG8_BAR; PG8_SCHED;
;             PG8_LDA(At, 0, 1); PG8_STAGE(PG8_SB(0, 0), b2, voffB); PG8_STAGE(PG8_SB(0, 1), b2 + hstepB, voffB); PG8_STAGE(PG8_SA(0, 0), a2, voffA);
;             PG8_WAIT_V(8); PG8_WAIT_L(0); PG8_BAR; PG8_MMA(1, 0, At, B0); PG8_MMA(1, 1, At, B1); PG8_BAR; PG8_SCHED;
.LBB0_793:
	s_add_u32 s29, s50, 0xfff80080
	s_addc_u32 s36, s51, -1
	s_add_i32 s37, 0, 0x10000
	s_cmp_eq_u32 s49, 28
	s_cselect_b32 s55, s31, s36
	s_cselect_b32 s54, s30, s29
	s_cselect_b32 s53, s35, s21
	s_cselect_b32 s52, s34, s19
	s_add_i32 s29, 0, 0x14000
	v_add_u32_e32 v142, s37, v224
	v_add_u32_e32 v158, s29, v224
	ds_read_b128 v[130:133], v142
	ds_read_b128 v[134:137], v142 offset:1024
	ds_read_b128 v[138:141], v142 offset:2048
	ds_read_b128 v[142:145], v142 offset:3072
	ds_read_b128 v[146:149], v158
	ds_read_b128 v[150:153], v158 offset:1024
	ds_read_b128 v[154:157], v158 offset:2048
	ds_read_b128 v[158:161], v158 offset:3072
	v_lshl_add_u64 v[204:205], s[50:51], 0, v[196:197]
	s_add_i32 m0, s63, 0xc000
	ds_read_b128 v[162:165], v228
	ds_read_b128 v[166:169], v228 offset:1024
	ds_read_b128 v[170:173], v228 offset:2048
	ds_read_b128 v[174:177], v228 offset:3072
	ds_read_b128 v[178:181], v228 offset:4096
	ds_read_b128 v[182:185], v228 offset:5120
	ds_read_b128 v[186:189], v228 offset:6144
	ds_read_b128 v[200:203], v228 offset:7168
	global_load_lds_dwordx4 v[204:205], off
	v_lshl_add_u64 v[204:205], s[50:51], 0, v[198:199]
	s_add_i32 m0, s63, 0xe000
	s_nop 0
	global_load_lds_dwordx4 v[204:205], off
	s_waitcnt vmcnt(8)
	s_waitcnt lgkmcnt(0)
	s_barrier
	s_setprio 1
	s_waitcnt lgkmcnt(0)
	v_mfma_f32_16x16x32_bf16 v[124:127], v[130:133], v[162:165], v[124:127]
	v_mfma_f32_16x16x32_bf16 v[120:123], v[138:141], v[162:165], v[120:123]
	v_mfma_f32_16x16x32_bf16 v[108:111], v[130:133], v[170:173], v[108:111]
	v_mfma_f32_16x16x32_bf16 v[104:107], v[138:141], v[170:173], v[104:107]
	v_mfma_f32_16x16x32_bf16 v[92:95], v[130:133], v[178:181], v[92:95]
	v_mfma_f32_16x16x32_bf16 v[88:91], v[138:141], v[178:181], v[88:91]
	v_mfma_f32_16x16x32_bf16 v[76:79], v[130:133], v[186:189], v[76:79]
	v_mfma_f32_16x16x32_bf16 v[72:75], v[138:141], v[186:189], v[72:75]
	v_mfma_f32_16x16x32_bf16 v[124:127], v[134:137], v[166:169], v[124:127]
	v_mfma_f32_16x16x32_bf16 v[120:123], v[142:145], v[166:169], v[120:123]
	v_mfma_f32_16x16x32_bf16 v[108:111], v[134:137], v[174:177], v[108:111]
	v_mfma_f32_16x16x32_bf16 v[104:107], v[142:145], v[174:177], v[104:107]
	v_mfma_f32_16x16x32_bf16 v[92:95], v[134:137], v[182:185], v[92:95]
	v_mfma_f32_16x16x32_bf16 v[88:91], v[142:145], v[182:185], v[88:91]
	v_mfma_f32_16x16x32_bf16 v[76:79], v[134:137], v[200:203], v[76:79]
	v_mfma_f32_16x16x32_bf16 v[72:75], v[142:145], v[200:203], v[72:75]
	v_mfma_f32_16x16x32_bf16 v[116:119], v[146:149], v[162:165], v[116:119]
	v_mfma_f32_16x16x32_bf16 v[112:115], v[154:157], v[162:165], v[112:115]
	v_mfma_f32_16x16x32_bf16 v[100:103], v[146:149], v[170:173], v[100:103]
	v_mfma_f32_16x16x32_bf16 v[96:99], v[154:157], v[170:173], v[96:99]
	v_mfma_f32_16x16x32_bf16 v[84:87], v[146:149], v[178:181], v[84:87]
	v_mfma_f32_16x16x32_bf16 v[80:83], v[154:157], v[178:181], v[80:83]
	v_mfma_f32_16x16x32_bf16 v[68:71], v[146:149], v[186:189], v[68:71]
	v_mfma_f32_16x16x32_bf16 v[64:67], v[154:157], v[186:189], v[64:67]
	v_mfma_f32_16x16x32_bf16 v[116:119], v[150:153], v[166:169], v[116:119]
	v_mfma_f32_16x16x32_bf16 v[112:115], v[158:161], v[166:169], v[112:115]
	v_mfma_f32_16x16x32_bf16 v[100:103], v[150:153], v[174:177], v[100:103]
	v_mfma_f32_16x16x32_bf16 v[96:99], v[158:161], v[174:177], v[96:99]
	v_mfma_f32_16x16x32_bf16 v[84:87], v[150:153], v[182:185], v[84:87]
	v_mfma_f32_16x16x32_bf16 v[80:83], v[158:161], v[182:185], v[80:83]
	v_mfma_f32_16x16x32_bf16 v[68:71], v[150:153], v[200:203], v[68:71]
	v_mfma_f32_16x16x32_bf16 v[64:67], v[158:161], v[200:203], v[64:67]
	s_setprio 0
	s_barrier
	s_add_i32 s36, s37, s62
	v_lshl_add_u64 v[204:205], s[52:53], 0, v[128:129]
	s_mov_b32 m0, s36
	ds_read_b128 v[162:165], v228 offset:16384
	ds_read_b128 v[166:169], v228 offset:17408
	ds_read_b128 v[170:173], v228 offset:18432
	ds_read_b128 v[174:177], v228 offset:19456
	ds_read_b128 v[178:181], v228 offset:20480
	ds_read_b128 v[182:185], v228 offset:21504
	ds_read_b128 v[186:189], v228 offset:22528
	ds_read_b128 v[200:203], v228 offset:23552
	global_load_lds_dwordx4 v[204:205], off
	s_add_i32 m0, s36, 0x2000
	s_add_u32 s80, s52, 0x80000
	v_lshl_add_u64 v[206:207], s[52:53], 0, v[194:195]
	s_addc_u32 s81, s53, 0
	s_add_i32 s29, s29, s62
	global_load_lds_dwordx4 v[206:207], off
	v_lshl_add_u64 v[208:209], s[80:81], 0, v[128:129]
	s_mov_b32 m0, s29
	v_lshl_add_u64 v[210:211], s[54:55], 0, v[192:193]
	global_load_lds_dwordx4 v[208:209], off
	v_lshl_add_u64 v[208:209], s[80:81], 0, v[194:195]
	s_add_i32 m0, s29, 0x2000
	s_nop 0
	global_load_lds_dwordx4 v[208:209], off
	v_lshl_add_u64 v[208:209], s[54:55], 0, v[190:191]
	s_mov_b32 m0, s63
	s_nop 0
	global_load_lds_dwordx4 v[208:209], off
	s_mov_b32 m0, s64
	s_nop 0
	global_load_lds_dwordx4 v[210:211], off
	s_waitcnt vmcnt(8)
	s_waitcnt lgkmcnt(0)
	s_barrier
; #define PG8_STAGE(bufoff, gbase, voff) do { _Pragma("unroll") for (int _i = 0; _i < 2; ++_i) \
;         __builtin_amdgcn_global_load_lds((const unsigned*)((const char*)(gbase) + (voff)[_i]), (LAS unsigned*)(lds + (bufoff) + ldsw + _i * 8192), 16, 0, 0); } while (0)
; #define PG8_LDA(dst, b, h) do { _Pragma("unroll") for (int m = 0; m < 4; ++m) _Pragma("unroll") for (int k = 0; k < 2; ++k) dst[m][k] = *(const LAS bf16x8*)(lds + PG8_SA(b, h) + aoff + m * 2048 + k * 1024); } while (0)
; #define PG8_LDB(dst, b, h) do { _Pragma("unroll") for (int n = 0; n < 2; ++n) _Pragma("unroll") for (int k = 0; k < 2; ++k) dst[n][k] = *(const LAS bf16x8*)(lds + PG8_SB(b, h) + boff + n * 2048 + k * 1024); } while (0)
; #define PG8_MMA(ai, bj, At, Bt) do { __builtin_amdgcn_s_setprio(1); _Pragma("unroll") for (int m = 0; m < 4; ++m) _Pragma("unroll") for (int n = 0; n < 2; ++n) _Pragma("unroll") for (int k = 0; k < 2; ++k) \
;         acc[ai][bj][m][n] = __builtin_amdgcn_mfma_f32_16x16x32_bf16(Bt[n][k], At[m][k], acc[ai][bj][m][n], 0, 0, 0); __builtin_amdgcn_s_setprio(0); } while (0)
; #define PG8_WAIT_V(n) asm volatile("s_waitcnt vmcnt(" #n ")" ::: "memory")
; #define PG8_WAIT_L(n) asm volatile("s_waitcnt lgkmcnt(" #n ")" ::: "memory")
; #define PG8_BAR __builtin_amdgcn_s_barrier()
; #define PG8_SCHED __builtin_amdgcn_sched_barrier(0)
; template <class Epi, class Sched>
; DI void gemm_phase(LAS unsigned char* lds, const int tid, const int K, const int lda, const int ldb, const Sched& S_, const Epi& E) {
;     ...
;             PG8_WAIT_V(8); PG8_WAIT_L(0); PG8_BAR; PG8_MMA(1, 0, At, B0); PG8_MMA(1, 1, At, B1); PG8_BAR; PG8_SCHED;
;             PG8_LDB(B0, 1, 0); PG8_LDB(B1, 1, 1); PG8_SCHED; PG8_LDA(At, 1, 0); PG8_STAGE(PG8_SA(0, 1), a2 + hstepA, voffA);
;             PG8_WAIT_V(8); PG8_WAIT_L(0); PG8_BAR; PG8_MMA(0, 0, At, B0); PG8_MMA(0, 1, At, B1); PG8_BAR; PG8_SCHED;
	s_setprio 1
	s_waitcnt lgkmcnt(0)
	v_mfma_f32_16x16x32_bf16 v[60:63], v[130:133], v[162:165], v[60:63]
	v_mfma_f32_16x16x32_bf16 v[56:59], v[138:141], v[162:165], v[56:59]
	v_mfma_f32_16x16x32_bf16 v[44:47], v[130:133], v[170:173], v[44:47]
	v_mfma_f32_16x16x32_bf16 v[40:43], v[138:141], v[170:173], v[40:43]
	v_mfma_f32_16x16x32_bf16 v[28:31], v[130:133], v[178:181], v[28:31]
	v_mfma_f32_16x16x32_bf16 v[24:27], v[138:141], v[178:181], v[24:27]
	v_mfma_f32_16x16x32_bf16 v[12:15], v[130:133], v[186:189], v[12:15]
	v_mfma_f32_16x16x32_bf16 v[8:11], v[138:141], v[186:189], v[8:11]
	v_mfma_f32_16x16x32_bf16 v[60:63], v[134:137], v[166:169], v[60:63]
	v_mfma_f32_16x16x32_bf16 v[56:59], v[142:145], v[166:169], v[56:59]
	v_mfma_f32_16x16x32_bf16 v[44:47], v[134:137], v[174:177], v[44:47]
	v_mfma_f32_16x16x32_bf16 v[40:43], v[142:145], v[174:177], v[40:43]
	v_mfma_f32_16x16x32_bf16 v[28:31], v[134:137], v[182:185], v[28:31]
	v_mfma_f32_16x16x32_bf16 v[24:27], v[142:145], v[182:185], v[24:27]
	v_mfma_f32_16x16x32_bf16 v[12:15], v[134:137], v[200:203], v[12:15]
	v_mfma_f32_16x16x32_bf16 v[8:11], v[142:145], v[200:203], v[8:11]
	v_mfma_f32_16x16x32_bf16 v[52:55], v[146:149], v[162:165], v[52:55]
	v_mfma_f32_16x16x32_bf16 v[48:51], v[154:157], v[162:165], v[48:51]
	v_mfma_f32_16x16x32_bf16 v[36:39], v[146:149], v[170:173], v[36:39]
	v_mfma_f32_16x16x32_bf16 v[32:35], v[154:157], v[170:173], v[32:35]
	v_mfma_f32_16x16x32_bf16 v[20:23], v[146:149], v[178:181], v[20:23]
	v_mfma_f32_16x16x32_bf16 v[16:19], v[154:157], v[178:181], v[16:19]
	v_mfma_f32_16x16x32_bf16 v[4:7], v[146:149], v[186:189], v[4:7]
	v_mfma_f32_16x16x32_bf16 v[0:3], v[154:157], v[186:189], v[0:3]
	v_mfma_f32_16x16x32_bf16 v[52:55], v[150:153], v[166:169], v[52:55]
	v_mfma_f32_16x16x32_bf16 v[48:51], v[158:161], v[166:169], v[48:51]
	v_mfma_f32_16x16x32_bf16 v[36:39], v[150:153], v[174:177], v[36:39]
	v_mfma_f32_16x16x32_bf16 v[32:35], v[158:161], v[174:177], v[32:35]
	v_mfma_f32_16x16x32_bf16 v[20:23], v[150:153], v[182:185], v[20:23]
	v_mfma_f32_16x16x32_bf16 v[16:19], v[158:161], v[182:185], v[16:19]
	v_mfma_f32_16x16x32_bf16 v[4:7], v[150:153], v[200:203], v[4:7]
	v_mfma_f32_16x16x32_bf16 v[0:3], v[158:161], v[200:203], v[0:3]
	s_setprio 0
	s_barrier
	s_add_i32 s29, 0, 0x18000
	s_add_i32 s36, 0, 0x1c000
	v_add_u32_e32 v142, s29, v224
	v_add_u32_e32 v158, s36, v224
	ds_read_b128 v[130:133], v142
	ds_read_b128 v[134:137], v142 offset:1024
	ds_read_b128 v[138:141], v142 offset:2048
	ds_read_b128 v[142:145], v142 offset:3072
	ds_read_b128 v[146:149], v158
	ds_read_b128 v[150:153], v158 offset:1024
	ds_read_b128 v[154:157], v158 offset:2048
	ds_read_b128 v[158:161], v158 offset:3072
	s_add_u32 s54, s54, 0x80000
	s_addc_u32 s55, s55, 0
	s_mov_b32 m0, s65
	v_lshl_add_u64 v[212:213], s[54:55], 0, v[190:191]
	ds_read_b128 v[162:165], v228 offset:32768
	ds_read_b128 v[166:169], v228 offset:33792
	ds_read_b128 v[170:173], v228 offset:34816
	ds_read_b128 v[174:177], v228 offset:35840
	ds_read_b128 v[178:181], v228 offset:36864
	ds_read_b128 v[182:185], v228 offset:37888
	ds_read_b128 v[186:189], v228 offset:38912
	ds_read_b128 v[200:203], v228 offset:39936
	global_load_lds_dwordx4 v[212:213], off
	v_lshl_add_u64 v[212:213], s[54:55], 0, v[192:193]
	s_mov_b32 m0, s66
	s_nop 0
	global_load_lds_dwordx4 v[212:213], off
	s_waitcnt vmcnt(8)
	s_waitcnt lgkmcnt(0)
	s_barrier
	s_setprio 1
	s_waitcnt lgkmcnt(0)
	v_mfma_f32_16x16x32_bf16 v[124:127], v[130:133], v[162:165], v[124:127]
	v_mfma_f32_16x16x32_bf16 v[120:123], v[138:141], v[162:165], v[120:123]
	v_mfma_f32_16x16x32_bf16 v[108:111], v[130:133], v[170:173], v[108:111]
	v_mfma_f32_16x16x32_bf16 v[104:107], v[138:141], v[170:173], v[104:107]
	v_mfma_f32_16x16x32_bf16 v[92:95], v[130:133], v[178:181], v[92:95]
	v_mfma_f32_16x16x32_bf16 v[88:91], v[138:141], v[178:181], v[88:91]
	v_mfma_f32_16x16x32_bf16 v[76:79], v[130:133], v[186:189], v[76:79]
	v_mfma_f32_16x16x32_bf16 v[72:75], v[138:141], v[186:189], v[72:75]
	v_mfma_f32_16x16x32_bf16 v[124:127], v[134:137], v[166:169], v[124:127]
	v_mfma_f32_16x16x32_bf16 v[120:123], v[142:145], v[166:169], v[120:123]
	v_mfma_f32_16x16x32_bf16 v[108:111], v[134:137], v[174:177], v[108:111]
	v_mfma_f32_16x16x32_bf16 v[104:107], v[142:145], v[174:177], v[104:107]
	v_mfma_f32_16x16x32_bf16 v[92:95], v[134:137], v[182:185], v[92:95]
	v_mfma_f32_16x16x32_bf16 v[88:91], v[142:145], v[182:185], v[88:91]
	v_mfma_f32_16x16x32_bf16 v[76:79], v[134:137], v[200:203], v[76:79]
	v_mfma_f32_16x16x32_bf16 v[72:75], v[142:145], v[200:203], v[72:75]
	v_mfma_f32_16x16x32_bf16 v[116:119], v[146:149], v[162:165], v[116:119]
	v_mfma_f32_16x16x32_bf16 v[112:115], v[154:157], v[162:165], v[112:115]
	v_mfma_f32_16x16x32_bf16 v[100:103], v[146:149], v[170:173], v[100:103]
	v_mfma_f32_16x16x32_bf16 v[96:99], v[154:157], v[170:173], v[96:99]
	v_mfma_f32_16x16x32_bf16 v[84:87], v[146:149], v[178:181], v[84:87]
	v_mfma_f32_16x16x32_bf16 v[80:83], v[154:157], v[178:181], v[80:83]
	v_mfma_f32_16x16x32_bf16 v[68:71], v[146:149], v[186:189], v[68:71]
	v_mfma_f32_16x16x32_bf16 v[64:67], v[154:157], v[186:189], v[64:67]
	v_mfma_f32_16x16x32_bf16 v[116:119], v[150:153], v[166:169], v[116:119]
	v_mfma_f32_16x16x32_bf16 v[112:115], v[158:161], v[166:169], v[112:115]
	v_mfma_f32_16x16x32_bf16 v[100:103], v[150:153], v[174:177], v[100:103]
	v_mfma_f32_16x16x32_bf16 v[96:99], v[158:161], v[174:177], v[96:99]
	v_mfma_f32_16x16x32_bf16 v[84:87], v[150:153], v[182:185], v[84:87]
	v_mfma_f32_16x16x32_bf16 v[80:83], v[158:161], v[182:185], v[80:83]
	v_mfma_f32_16x16x32_bf16 v[68:71], v[150:153], v[200:203], v[68:71]
	v_mfma_f32_16x16x32_bf16 v[64:67], v[158:161], v[200:203], v[64:67]
	s_setprio 0
	s_barrier
; #define PG8_STAGE(bufoff, gbase, voff) do { _Pragma("unroll") for (int _i = 0; _i < 2; ++_i) \
;         __builtin_amdgcn_global_load_lds((const unsigned*)((const char*)(gbase) + (voff)[_i]), (LAS unsigned*)(lds + (bufoff) + ldsw + _i * 8192), 16, 0, 0); } while (0)
; #define PG8_LDA(dst, b, h) do { _Pragma("unroll") for (int m = 0; m < 4; ++m) _Pragma("unroll") for (int k = 0; k < 2; ++k) dst[m][k] = *(const LAS bf16x8*)(lds + PG8_SA(b, h) + aoff + m * 2048 + k * 1024); } while (0)
; #define PG8_MMA(ai, bj, At, Bt) do { __builtin_amdgcn_s_setprio(1); _Pragma("unroll") for (int m = 0; m < 4; ++m) _Pragma("unroll") for (int n = 0; n < 2; ++n) _Pragma("unroll") for (int k = 0; k < 2; ++k) \
;         acc[ai][bj][m][n] = __builtin_amdgcn_mfma_f32_16x16x32_bf16(Bt[n][k], At[m][k], acc[ai][bj][m][n], 0, 0, 0); __builtin_amdgcn_s_setprio(0); } while (0)
; #define PG8_WAIT_V(n) asm volatile("s_waitcnt vmcnt(" #n ")" ::: "memory")
; #define PG8_WAIT_L(n) asm volatile("s_waitcnt lgkmcnt(" #n ")" ::: "memory")
; #define PG8_BAR __builtin_amdgcn_s_barrier()
; #define PG8_SCHED __builtin_amdgcn_sched_barrier(0)
; template <class Epi, class Sched>
; DI void gemm_phase(LAS unsigned char* lds, const int tid, const int K, const int lda, const int ldb, const Sched& S_, const Epi& E) {
;     ...
;             PG8_LDA(At, 1, 1); PG8_STAGE(PG8_SB(1, 0), b3, voffB); PG8_STAGE(PG8_SB(1, 1), b3 + hstepB, voffB); PG8_STAGE(PG8_SA(1, 0), a3, voffA);
;             PG8_WAIT_V(8); PG8_WAIT_L(0); PG8_BAR; PG8_MMA(1, 0, At, B0); PG8_MMA(1, 1, At, B1); PG8_BAR; PG8_SCHED;
;             if constexpr (Epi::HOOK) { if (((t + 2) & 7) == 0 && !last) { E.hook(acc, cur, (t + 2) >> 3, wr, wc, fr, fq); PG8_SCHED; } }
;         }
;         if (wr == 0) PG8_BAR;
	s_add_i32 s29, s29, s62
	v_lshl_add_u64 v[204:205], v[204:205], 0, s[94:95]
	s_mov_b32 m0, s29
	ds_read_b128 v[162:165], v228 offset:49152
	ds_read_b128 v[166:169], v228 offset:50176
	ds_read_b128 v[170:173], v228 offset:51200
	ds_read_b128 v[174:177], v228 offset:52224
	ds_read_b128 v[178:181], v228 offset:53248
	ds_read_b128 v[182:185], v228 offset:54272
	ds_read_b128 v[186:189], v228 offset:55296
	ds_read_b128 v[200:203], v228 offset:56320
	global_load_lds_dwordx4 v[204:205], off
	s_add_i32 m0, s29, 0x2000
	s_add_u32 s52, s52, 0x80080
	v_lshl_add_u64 v[204:205], v[206:207], 0, s[94:95]
	s_addc_u32 s53, s53, 0
	s_add_i32 s29, s36, s62
	global_load_lds_dwordx4 v[204:205], off
	v_lshl_add_u64 v[204:205], s[52:53], 0, v[128:129]
	s_mov_b32 m0, s29
	s_nop 0
	global_load_lds_dwordx4 v[204:205], off
	v_lshl_add_u64 v[204:205], s[52:53], 0, v[194:195]
	s_add_i32 m0, s29, 0x2000
	s_nop 0
	global_load_lds_dwordx4 v[204:205], off
	v_lshl_add_u64 v[204:205], v[208:209], 0, s[94:95]
	s_mov_b32 m0, s67
	s_nop 0
	global_load_lds_dwordx4 v[204:205], off
	v_lshl_add_u64 v[204:205], v[210:211], 0, s[94:95]
	s_mov_b32 m0, s77
	s_nop 0
	global_load_lds_dwordx4 v[204:205], off
	s_waitcnt vmcnt(8)
	s_waitcnt lgkmcnt(0)
	s_barrier
	s_setprio 1
	s_waitcnt lgkmcnt(0)
	v_mfma_f32_16x16x32_bf16 v[60:63], v[130:133], v[162:165], v[60:63]
	v_mfma_f32_16x16x32_bf16 v[56:59], v[138:141], v[162:165], v[56:59]
	v_mfma_f32_16x16x32_bf16 v[44:47], v[130:133], v[170:173], v[44:47]
	v_mfma_f32_16x16x32_bf16 v[40:43], v[138:141], v[170:173], v[40:43]
	v_mfma_f32_16x16x32_bf16 v[28:31], v[130:133], v[178:181], v[28:31]
	v_mfma_f32_16x16x32_bf16 v[24:27], v[138:141], v[178:181], v[24:27]
	v_mfma_f32_16x16x32_bf16 v[12:15], v[130:133], v[186:189], v[12:15]
	v_mfma_f32_16x16x32_bf16 v[8:11], v[138:141], v[186:189], v[8:11]
	v_mfma_f32_16x16x32_bf16 v[60:63], v[134:137], v[166:169], v[60:63]
	v_mfma_f32_16x16x32_bf16 v[56:59], v[142:145], v[166:169], v[56:59]
	v_mfma_f32_16x16x32_bf16 v[44:47], v[134:137], v[174:177], v[44:47]
	v_mfma_f32_16x16x32_bf16 v[40:43], v[142:145], v[174:177], v[40:43]
	v_mfma_f32_16x16x32_bf16 v[28:31], v[134:137], v[182:185], v[28:31]
	v_mfma_f32_16x16x32_bf16 v[24:27], v[142:145], v[182:185], v[24:27]
	v_mfma_f32_16x16x32_bf16 v[12:15], v[134:137], v[200:203], v[12:15]
	v_mfma_f32_16x16x32_bf16 v[8:11], v[142:145], v[200:203], v[8:11]
	v_mfma_f32_16x16x32_bf16 v[52:55], v[146:149], v[162:165], v[52:55]
	v_mfma_f32_16x16x32_bf16 v[48:51], v[154:157], v[162:165], v[48:51]
	v_mfma_f32_16x16x32_bf16 v[36:39], v[146:149], v[170:173], v[36:39]
	v_mfma_f32_16x16x32_bf16 v[32:35], v[154:157], v[170:173], v[32:35]
	v_mfma_f32_16x16x32_bf16 v[20:23], v[146:149], v[178:181], v[20:23]
	v_mfma_f32_16x16x32_bf16 v[16:19], v[154:157], v[178:181], v[16:19]
	v_mfma_f32_16x16x32_bf16 v[4:7], v[146:149], v[186:189], v[4:7]
	v_mfma_f32_16x16x32_bf16 v[0:3], v[154:157], v[186:189], v[0:3]
	v_mfma_f32_16x16x32_bf16 v[52:55], v[150:153], v[166:169], v[52:55]
	v_mfma_f32_16x16x32_bf16 v[48:51], v[158:161], v[166:169], v[48:51]
	v_mfma_f32_16x16x32_bf16 v[36:39], v[150:153], v[174:177], v[36:39]
	v_mfma_f32_16x16x32_bf16 v[32:35], v[158:161], v[174:177], v[32:35]
	v_mfma_f32_16x16x32_bf16 v[20:23], v[150:153], v[182:185], v[20:23]
	v_mfma_f32_16x16x32_bf16 v[16:19], v[158:161], v[182:185], v[16:19]
	v_mfma_f32_16x16x32_bf16 v[4:7], v[150:153], v[200:203], v[4:7]
	v_mfma_f32_16x16x32_bf16 v[0:3], v[158:161], v[200:203], v[0:3]
	s_setprio 0
	s_barrier
	s_add_i32 s49, s49, 2
	s_add_u32 s50, s50, 0x100
	s_addc_u32 s51, s51, 0
	s_add_u32 s19, s19, 0x100
	s_addc_u32 s21, s21, 0
	s_cmp_gt_u32 s49, 29
	s_cbranch_scc0 .LBB0_793
	s_and_b64 vcc, exec, s[16:17]
	s_cbranch_vccz .LBB0_796
	s_barrier

; #define PG8_STAGE(bufoff, gbase, voff) do { _Pragma("unroll") for (int _i = 0; _i < 2; ++_i) \
;         __builtin_amdgcn_global_load_lds((const unsigned*)((const char*)(gbase) + (voff)[_i]), (LAS unsigned*)(lds + (bufoff) + ldsw + _i * 8192), 16, 0, 0); } while (0)
; #define PG8_LDA(dst, b, h) do { _Pragma("unroll") for (int m = 0; m < 4; ++m) _Pragma("unroll") for (int k = 0; k < 2; ++k) dst[m][k] = *(const LAS bf16x8*)(lds + PG8_SA(b, h) + aoff + m * 2048 + k * 1024); } while (0)
; #define PG8_LDB(dst, b, h) do { _Pragma("unroll") for (int n = 0; n < 2; ++n) _Pragma("unroll") for (int k = 0; k < 2; ++k) dst[n][k] = *(const LAS bf16x8*)(lds + PG8_SB(b, h) + boff + n * 2048 + k * 1024); } while (0)
; #define PG8_MMA(ai, bj, At, Bt) do { __builtin_amdgcn_s_setprio(1); _Pragma("unroll") for (int m = 0; m < 4; ++m) _Pragma("unroll") for (int n = 0; n < 2; ++n) _Pragma("unroll") for (int k = 0; k < 2; ++k) \
;         acc[ai][bj][m][n] = __builtin_amdgcn_mfma_f32_16x16x32_bf16(Bt[n][k], At[m][k], acc[ai][bj][m][n], 0, 0, 0); __builtin_amdgcn_s_setprio(0); } while (0)
; #define PG8_WAIT_V(n) asm volatile("s_waitcnt vmcnt(" #n ")" ::: "memory")
; #define PG8_WAIT_L(n) asm volatile("s_waitcnt lgkmcnt(" #n ")" ::: "memory")
; #define PG8_BAR __builtin_amdgcn_s_barrier()
; #define PG8_SCHED __builtin_amdgcn_sched_barrier(0)
; template <class Epi, class Sched>
; DI void gemm_phase(LAS unsigned char* lds, const int tid, const int K, const int lda, const int ldb, const Sched& S_, const Epi& E) {
;     ...
;             const bool last = (t == nt - 2);
;             const char* a1 = cA + (size_t)(t + 1) * kstep;
;             const char* a2 = last ? nA : cA + (size_t)(t + 2) * kstep; const char* b2 = last ? nB : cB + (size_t)(t + 2) * kstep;
;             const char* a3 = a2 + kstep; const char* b3 = b2 + kstep;
;             PG8_LDB(B0, 0, 0); PG8_LDB(B1, 0, 1); PG8_SCHED; PG8_LDA(At, 0, 0); PG8_STAGE(PG8_SA(1, 1), a1 + hstepA, voffA);
;             PG8_WAIT_V(8); PG8_WAIT_L(0); PG8_BAR; PG8_MMA(0, 0, At, B0); PG8_MMA(0, 1, At, B1); PG8_BAR; PG8_SCHED;
;             PG8_LDA(At, 0, 1); PG8_STAGE(PG8_SB(0, 0), b2, voffB); PG8_STAGE(PG8_SB(0, 1), b2 + hstepB, voffB); PG8_STAGE(PG8_SA(0, 0), a2, voffA);
;             PG8_WAIT_V(8); PG8_WAIT_L(0); PG8_BAR; PG8_MMA(1, 0, At, B0); PG8_MMA(1, 1, At, B1); PG8_BAR; PG8_SCHED;
.LBB0_835:
	s_add_u32 s29, s30, 0xfff80080
	s_addc_u32 s34, s31, -1
	s_add_i32 s36, 0, 0x10000
	s_cmp_eq_u32 s64, 28
	s_cselect_b32 s49, s17, s34
	s_cselect_b32 s48, s16, s29
	v_add_u32_e32 v144, s36, v147
	s_cselect_b32 s35, s19, s11
	s_cselect_b32 s34, s18, s9
	s_add_i32 s29, 0, 0x14000
	ds_read_b128 v[140:143], v144
	ds_read_b128 v[150:153], v144 offset:1024
	ds_read_b128 v[154:157], v144 offset:2048
	ds_read_b128 v[158:161], v144 offset:3072
	v_add_u32_e32 v144, s29, v147
	ds_read_b128 v[162:165], v144
	ds_read_b128 v[166:169], v144 offset:1024
	ds_read_b128 v[170:173], v144 offset:2048
	ds_read_b128 v[174:177], v144 offset:3072
	v_lshl_add_u64 v[144:145], s[30:31], 0, v[136:137]
	s_add_i32 m0, s51, 0xc000
	ds_read_b128 v[178:181], v149
	ds_read_b128 v[182:185], v149 offset:1024
	ds_read_b128 v[186:189], v149 offset:2048
	ds_read_b128 v[190:193], v149 offset:3072
	ds_read_b128 v[194:197], v149 offset:4096
	ds_read_b128 v[198:201], v149 offset:5120
	ds_read_b128 v[202:205], v149 offset:6144
	ds_read_b128 v[206:209], v149 offset:7168
	global_load_lds_dwordx4 v[144:145], off
	v_lshl_add_u64 v[144:145], s[30:31], 0, v[138:139]
	s_add_i32 m0, s51, 0xe000
	s_nop 0
	global_load_lds_dwordx4 v[144:145], off
	s_waitcnt vmcnt(8)
	s_waitcnt lgkmcnt(0)
	s_barrier
	s_setprio 1
	s_waitcnt lgkmcnt(0)
	v_mfma_f32_16x16x32_bf16 v[124:127], v[140:143], v[178:181], v[124:127]
	v_mfma_f32_16x16x32_bf16 v[120:123], v[154:157], v[178:181], v[120:123]
	v_mfma_f32_16x16x32_bf16 v[116:119], v[140:143], v[186:189], v[116:119]
	v_mfma_f32_16x16x32_bf16 v[112:115], v[154:157], v[186:189], v[112:115]
	v_mfma_f32_16x16x32_bf16 v[100:103], v[140:143], v[194:197], v[100:103]
	v_mfma_f32_16x16x32_bf16 v[96:99], v[154:157], v[194:197], v[96:99]
	v_mfma_f32_16x16x32_bf16 v[84:87], v[140:143], v[202:205], v[84:87]
	v_mfma_f32_16x16x32_bf16 v[80:83], v[154:157], v[202:205], v[80:83]
	v_mfma_f32_16x16x32_bf16 v[124:127], v[150:153], v[182:185], v[124:127]
	v_mfma_f32_16x16x32_bf16 v[120:123], v[158:161], v[182:185], v[120:123]
	v_mfma_f32_16x16x32_bf16 v[116:119], v[150:153], v[190:193], v[116:119]
	v_mfma_f32_16x16x32_bf16 v[112:115], v[158:161], v[190:193], v[112:115]
	v_mfma_f32_16x16x32_bf16 v[100:103], v[150:153], v[198:201], v[100:103]
	v_mfma_f32_16x16x32_bf16 v[96:99], v[158:161], v[198:201], v[96:99]
	v_mfma_f32_16x16x32_bf16 v[84:87], v[150:153], v[206:209], v[84:87]
	v_mfma_f32_16x16x32_bf16 v[80:83], v[158:161], v[206:209], v[80:83]
	v_mfma_f32_16x16x32_bf16 v[108:111], v[162:165], v[178:181], v[108:111]
	v_mfma_f32_16x16x32_bf16 v[104:107], v[170:173], v[178:181], v[104:107]
	v_mfma_f32_16x16x32_bf16 v[92:95], v[162:165], v[186:189], v[92:95]
	v_mfma_f32_16x16x32_bf16 v[88:91], v[170:173], v[186:189], v[88:91]
	v_mfma_f32_16x16x32_bf16 v[76:79], v[162:165], v[194:197], v[76:79]
	v_mfma_f32_16x16x32_bf16 v[72:75], v[170:173], v[194:197], v[72:75]
	v_mfma_f32_16x16x32_bf16 v[68:71], v[162:165], v[202:205], v[68:71]
	v_mfma_f32_16x16x32_bf16 v[64:67], v[170:173], v[202:205], v[64:67]
	v_mfma_f32_16x16x32_bf16 v[108:111], v[166:169], v[182:185], v[108:111]
	v_mfma_f32_16x16x32_bf16 v[104:107], v[174:177], v[182:185], v[104:107]
	v_mfma_f32_16x16x32_bf16 v[92:95], v[166:169], v[190:193], v[92:95]
	v_mfma_f32_16x16x32_bf16 v[88:91], v[174:177], v[190:193], v[88:91]
	v_mfma_f32_16x16x32_bf16 v[76:79], v[166:169], v[198:201], v[76:79]
	v_mfma_f32_16x16x32_bf16 v[72:75], v[174:177], v[198:201], v[72:75]
	v_mfma_f32_16x16x32_bf16 v[68:71], v[166:169], v[206:209], v[68:71]
	v_mfma_f32_16x16x32_bf16 v[64:67], v[174:177], v[206:209], v[64:67]
	s_setprio 0
	s_barrier
	s_add_i32 s36, s36, s50
	v_lshl_add_u64 v[144:145], s[34:35], 0, v[128:129]
	s_mov_b32 m0, s36
	ds_read_b128 v[178:181], v149 offset:16384
	ds_read_b128 v[182:185], v149 offset:17408
	ds_read_b128 v[186:189], v149 offset:18432
	ds_read_b128 v[190:193], v149 offset:19456
	ds_read_b128 v[194:197], v149 offset:20480
	ds_read_b128 v[198:201], v149 offset:21504
	ds_read_b128 v[202:205], v149 offset:22528
	ds_read_b128 v[206:209], v149 offset:23552
	global_load_lds_dwordx4 v[144:145], off
	s_add_i32 m0, s36, 0x2000
	s_add_u32 s66, s34, 0x80000
	v_lshl_add_u64 v[210:211], s[34:35], 0, v[134:135]
	s_addc_u32 s67, s35, 0
	s_add_i32 s29, s29, s50
	global_load_lds_dwordx4 v[210:211], off
	v_lshl_add_u64 v[212:213], s[66:67], 0, v[128:129]
	s_mov_b32 m0, s29
	v_lshl_add_u64 v[214:215], s[48:49], 0, v[132:133]
	global_load_lds_dwordx4 v[212:213], off
	v_lshl_add_u64 v[212:213], s[66:67], 0, v[134:135]
	s_add_i32 m0, s29, 0x2000
	s_nop 0
	global_load_lds_dwordx4 v[212:213], off
	v_lshl_add_u64 v[212:213], s[48:49], 0, v[130:131]
	s_mov_b32 m0, s51
	s_nop 0
	global_load_lds_dwordx4 v[212:213], off
	s_mov_b32 m0, s52
	s_nop 0
	global_load_lds_dwordx4 v[214:215], off
	s_waitcnt vmcnt(8)
	s_waitcnt lgkmcnt(0)
	s_barrier
; #define PG8_STAGE(bufoff, gbase, voff) do { _Pragma("unroll") for (int _i = 0; _i < 2; ++_i) \
;         __builtin_amdgcn_global_load_lds((const unsigned*)((const char*)(gbase) + (voff)[_i]), (LAS unsigned*)(lds + (bufoff) + ldsw + _i * 8192), 16, 0, 0); } while (0)
; #define PG8_LDA(dst, b, h) do { _Pragma("unroll") for (int m = 0; m < 4; ++m) _Pragma("unroll") for (int k = 0; k < 2; ++k) dst[m][k] = *(const LAS bf16x8*)(lds + PG8_SA(b, h) + aoff + m * 2048 + k * 1024); } while (0)
; #define PG8_LDB(dst, b, h) do { _Pragma("unroll") for (int n = 0; n < 2; ++n) _Pragma("unroll") for (int k = 0; k < 2; ++k) dst[n][k] = *(const LAS bf16x8*)(lds + PG8_SB(b, h) + boff + n * 2048 + k * 1024); } while (0)
; #define PG8_MMA(ai, bj, At, Bt) do { __builtin_amdgcn_s_setprio(1); _Pragma("unroll") for (int m = 0; m < 4; ++m) _Pragma("unroll") for (int n = 0; n < 2; ++n) _Pragma("unroll") for (int k = 0; k < 2; ++k) \
;         acc[ai][bj][m][n] = __builtin_amdgcn_mfma_f32_16x16x32_bf16(Bt[n][k], At[m][k], acc[ai][bj][m][n], 0, 0, 0); __builtin_amdgcn_s_setprio(0); } while (0)
; #define PG8_WAIT_V(n) asm volatile("s_waitcnt vmcnt(" #n ")" ::: "memory")
; #define PG8_WAIT_L(n) asm volatile("s_waitcnt lgkmcnt(" #n ")" ::: "memory")
; #define PG8_BAR __builtin_amdgcn_s_barrier()
; #define PG8_SCHED __builtin_amdgcn_sched_barrier(0)
; template <class Epi, class Sched>
; DI void gemm_phase(LAS unsigned char* lds, const int tid, const int K, const int lda, const int ldb, const Sched& S_, const Epi& E) {
;     ...
;             PG8_WAIT_V(8); PG8_WAIT_L(0); PG8_BAR; PG8_MMA(1, 0, At, B0); PG8_MMA(1, 1, At, B1); PG8_BAR; PG8_SCHED;
;             PG8_LDB(B0, 1, 0); PG8_LDB(B1, 1, 1); PG8_SCHED; PG8_LDA(At, 1, 0); PG8_STAGE(PG8_SA(0, 1), a2 + hstepA, voffA);
;             PG8_WAIT_V(8); PG8_WAIT_L(0); PG8_BAR; PG8_MMA(0, 0, At, B0); PG8_MMA(0, 1, At, B1); PG8_BAR; PG8_SCHED;
	s_setprio 1
	s_waitcnt lgkmcnt(0)
	v_mfma_f32_16x16x32_bf16 v[60:63], v[140:143], v[178:181], v[60:63]
	v_mfma_f32_16x16x32_bf16 v[56:59], v[154:157], v[178:181], v[56:59]
	v_mfma_f32_16x16x32_bf16 v[52:55], v[140:143], v[186:189], v[52:55]
	v_mfma_f32_16x16x32_bf16 v[48:51], v[154:157], v[186:189], v[48:51]
	v_mfma_f32_16x16x32_bf16 v[36:39], v[140:143], v[194:197], v[36:39]
	v_mfma_f32_16x16x32_bf16 v[32:35], v[154:157], v[194:197], v[32:35]
	v_mfma_f32_16x16x32_bf16 v[20:23], v[140:143], v[202:205], v[20:23]
	v_mfma_f32_16x16x32_bf16 v[16:19], v[154:157], v[202:205], v[16:19]
	v_mfma_f32_16x16x32_bf16 v[60:63], v[150:153], v[182:185], v[60:63]
	v_mfma_f32_16x16x32_bf16 v[56:59], v[158:161], v[182:185], v[56:59]
	v_mfma_f32_16x16x32_bf16 v[52:55], v[150:153], v[190:193], v[52:55]
	v_mfma_f32_16x16x32_bf16 v[48:51], v[158:161], v[190:193], v[48:51]
	v_mfma_f32_16x16x32_bf16 v[36:39], v[150:153], v[198:201], v[36:39]
	v_mfma_f32_16x16x32_bf16 v[32:35], v[158:161], v[198:201], v[32:35]
	v_mfma_f32_16x16x32_bf16 v[20:23], v[150:153], v[206:209], v[20:23]
	v_mfma_f32_16x16x32_bf16 v[16:19], v[158:161], v[206:209], v[16:19]
	v_mfma_f32_16x16x32_bf16 v[44:47], v[162:165], v[178:181], v[44:47]
	v_mfma_f32_16x16x32_bf16 v[40:43], v[170:173], v[178:181], v[40:43]
	v_mfma_f32_16x16x32_bf16 v[28:31], v[162:165], v[186:189], v[28:31]
	v_mfma_f32_16x16x32_bf16 v[24:27], v[170:173], v[186:189], v[24:27]
	v_mfma_f32_16x16x32_bf16 v[12:15], v[162:165], v[194:197], v[12:15]
	v_mfma_f32_16x16x32_bf16 v[8:11], v[170:173], v[194:197], v[8:11]
	v_mfma_f32_16x16x32_bf16 v[4:7], v[162:165], v[202:205], v[4:7]
	v_mfma_f32_16x16x32_bf16 v[0:3], v[170:173], v[202:205], v[0:3]
	v_mfma_f32_16x16x32_bf16 v[44:47], v[166:169], v[182:185], v[44:47]
	v_mfma_f32_16x16x32_bf16 v[40:43], v[174:177], v[182:185], v[40:43]
	v_mfma_f32_16x16x32_bf16 v[28:31], v[166:169], v[190:193], v[28:31]
	v_mfma_f32_16x16x32_bf16 v[24:27], v[174:177], v[190:193], v[24:27]
	v_mfma_f32_16x16x32_bf16 v[12:15], v[166:169], v[198:201], v[12:15]
	v_mfma_f32_16x16x32_bf16 v[8:11], v[174:177], v[198:201], v[8:11]
	v_mfma_f32_16x16x32_bf16 v[4:7], v[166:169], v[206:209], v[4:7]
	v_mfma_f32_16x16x32_bf16 v[0:3], v[174:177], v[206:209], v[0:3]
	s_setprio 0
	s_barrier
	s_add_i32 s29, 0, 0x18000
	s_add_i32 s36, 0, 0x1c000
	v_add_u32_e32 v158, s29, v147
	v_add_u32_e32 v174, s36, v147
	ds_read_b128 v[140:143], v158
	ds_read_b128 v[150:153], v158 offset:1024
	ds_read_b128 v[154:157], v158 offset:2048
	ds_read_b128 v[158:161], v158 offset:3072
	ds_read_b128 v[162:165], v174
	ds_read_b128 v[166:169], v174 offset:1024
	ds_read_b128 v[170:173], v174 offset:2048
	ds_read_b128 v[174:177], v174 offset:3072
	s_add_u32 s48, s48, 0x80000
	s_addc_u32 s49, s49, 0
	s_mov_b32 m0, s53
	v_lshl_add_u64 v[216:217], s[48:49], 0, v[130:131]
	ds_read_b128 v[178:181], v149 offset:32768
	ds_read_b128 v[182:185], v149 offset:33792
	ds_read_b128 v[186:189], v149 offset:34816
	ds_read_b128 v[190:193], v149 offset:35840
	ds_read_b128 v[194:197], v149 offset:36864
	ds_read_b128 v[198:201], v149 offset:37888
	ds_read_b128 v[202:205], v149 offset:38912
	ds_read_b128 v[206:209], v149 offset:39936
	global_load_lds_dwordx4 v[216:217], off
	v_lshl_add_u64 v[216:217], s[48:49], 0, v[132:133]
	s_mov_b32 m0, s54
	s_nop 0
	global_load_lds_dwordx4 v[216:217], off
	s_waitcnt vmcnt(8)
	s_waitcnt lgkmcnt(0)
	s_barrier
	s_setprio 1
	s_waitcnt lgkmcnt(0)
	v_mfma_f32_16x16x32_bf16 v[124:127], v[140:143], v[178:181], v[124:127]
	v_mfma_f32_16x16x32_bf16 v[120:123], v[154:157], v[178:181], v[120:123]
	v_mfma_f32_16x16x32_bf16 v[116:119], v[140:143], v[186:189], v[116:119]
	v_mfma_f32_16x16x32_bf16 v[112:115], v[154:157], v[186:189], v[112:115]
	v_mfma_f32_16x16x32_bf16 v[100:103], v[140:143], v[194:197], v[100:103]
	v_mfma_f32_16x16x32_bf16 v[96:99], v[154:157], v[194:197], v[96:99]
	v_mfma_f32_16x16x32_bf16 v[84:87], v[140:143], v[202:205], v[84:87]
	v_mfma_f32_16x16x32_bf16 v[80:83], v[154:157], v[202:205], v[80:83]
	v_mfma_f32_16x16x32_bf16 v[124:127], v[150:153], v[182:185], v[124:127]
	v_mfma_f32_16x16x32_bf16 v[120:123], v[158:161], v[182:185], v[120:123]
	v_mfma_f32_16x16x32_bf16 v[116:119], v[150:153], v[190:193], v[116:119]
	v_mfma_f32_16x16x32_bf16 v[112:115], v[158:161], v[190:193], v[112:115]
	v_mfma_f32_16x16x32_bf16 v[100:103], v[150:153], v[198:201], v[100:103]
	v_mfma_f32_16x16x32_bf16 v[96:99], v[158:161], v[198:201], v[96:99]
	v_mfma_f32_16x16x32_bf16 v[84:87], v[150:153], v[206:209], v[84:87]
	v_mfma_f32_16x16x32_bf16 v[80:83], v[158:161], v[206:209], v[80:83]
	v_mfma_f32_16x16x32_bf16 v[108:111], v[162:165], v[178:181], v[108:111]
	v_mfma_f32_16x16x32_bf16 v[104:107], v[170:173], v[178:181], v[104:107]
	v_mfma_f32_16x16x32_bf16 v[92:95], v[162:165], v[186:189], v[92:95]
	v_mfma_f32_16x16x32_bf16 v[88:91], v[170:173], v[186:189], v[88:91]
	v_mfma_f32_16x16x32_bf16 v[76:79], v[162:165], v[194:197], v[76:79]
	v_mfma_f32_16x16x32_bf16 v[72:75], v[170:173], v[194:197], v[72:75]
	v_mfma_f32_16x16x32_bf16 v[68:71], v[162:165], v[202:205], v[68:71]
	v_mfma_f32_16x16x32_bf16 v[64:67], v[170:173], v[202:205], v[64:67]
	v_mfma_f32_16x16x32_bf16 v[108:111], v[166:169], v[182:185], v[108:111]
	v_mfma_f32_16x16x32_bf16 v[104:107], v[174:177], v[182:185], v[104:107]
	v_mfma_f32_16x16x32_bf16 v[92:95], v[166:169], v[190:193], v[92:95]
	v_mfma_f32_16x16x32_bf16 v[88:91], v[174:177], v[190:193], v[88:91]
	v_mfma_f32_16x16x32_bf16 v[76:79], v[166:169], v[198:201], v[76:79]
	v_mfma_f32_16x16x32_bf16 v[72:75], v[174:177], v[198:201], v[72:75]
	v_mfma_f32_16x16x32_bf16 v[68:71], v[166:169], v[206:209], v[68:71]
	v_mfma_f32_16x16x32_bf16 v[64:67], v[174:177], v[206:209], v[64:67]
	s_setprio 0
	s_barrier
; #define PG8_STAGE(bufoff, gbase, voff) do { _Pragma("unroll") for (int _i = 0; _i < 2; ++_i) \
;         __builtin_amdgcn_global_load_lds((const unsigned*)((const char*)(gbase) + (voff)[_i]), (LAS unsigned*)(lds + (bufoff) + ldsw + _i * 8192), 16, 0, 0); } while (0)
; #define PG8_LDA(dst, b, h) do { _Pragma("unroll") for (int m = 0; m < 4; ++m) _Pragma("unroll") for (int k = 0; k < 2; ++k) dst[m][k] = *(const LAS bf16x8*)(lds + PG8_SA(b, h) + aoff + m * 2048 + k * 1024); } while (0)
; #define PG8_MMA(ai, bj, At, Bt) do { __builtin_amdgcn_s_setprio(1); _Pragma("unroll") for (int m = 0; m < 4; ++m) _Pragma("unroll") for (int n = 0; n < 2; ++n) _Pragma("unroll") for (int k = 0; k < 2; ++k) \
;         acc[ai][bj][m][n] = __builtin_amdgcn_mfma_f32_16x16x32_bf16(Bt[n][k], At[m][k], acc[ai][bj][m][n], 0, 0, 0); __builtin_amdgcn_s_setprio(0); } while (0)
; #define PG8_WAIT_V(n) asm volatile("s_waitcnt vmcnt(" #n ")" ::: "memory")
; #define PG8_WAIT_L(n) asm volatile("s_waitcnt lgkmcnt(" #n ")" ::: "memory")
; #define PG8_BAR __builtin_amdgcn_s_barrier()
; #define PG8_SCHED __builtin_amdgcn_sched_barrier(0)
; template <class Epi, class Sched>
; DI void gemm_phase(LAS unsigned char* lds, const int tid, const int K, const int lda, const int ldb, const Sched& S_, const Epi& E) {
;     ...
;             PG8_LDA(At, 1, 1); PG8_STAGE(PG8_SB(1, 0), b3, voffB); PG8_STAGE(PG8_SB(1, 1), b3 + hstepB, voffB); PG8_STAGE(PG8_SA(1, 0), a3, voffA);
;             PG8_WAIT_V(8); PG8_WAIT_L(0); PG8_BAR; PG8_MMA(1, 0, At, B0); PG8_MMA(1, 1, At, B1); PG8_BAR; PG8_SCHED;
;             if constexpr (Epi::HOOK) { if (((t + 2) & 7) == 0 && !last) { E.hook(acc, cur, (t + 2) >> 3, wr, wc, fr, fq); PG8_SCHED; } }
;         }
;         if (wr == 0) PG8_BAR;
	s_add_i32 s29, s29, s50
	v_lshl_add_u64 v[144:145], v[144:145], 0, s[94:95]
	s_mov_b32 m0, s29
	ds_read_b128 v[178:181], v149 offset:49152
	ds_read_b128 v[182:185], v149 offset:50176
	ds_read_b128 v[186:189], v149 offset:51200
	ds_read_b128 v[190:193], v149 offset:52224
	ds_read_b128 v[194:197], v149 offset:53248
	ds_read_b128 v[198:201], v149 offset:54272
	ds_read_b128 v[202:205], v149 offset:55296
	ds_read_b128 v[206:209], v149 offset:56320
	global_load_lds_dwordx4 v[144:145], off
	s_add_i32 m0, s29, 0x2000
	s_add_u32 s34, s34, 0x80080
	v_lshl_add_u64 v[144:145], v[210:211], 0, s[94:95]
	s_addc_u32 s35, s35, 0
	s_add_i32 s29, s36, s50
	global_load_lds_dwordx4 v[144:145], off
	v_lshl_add_u64 v[144:145], s[34:35], 0, v[128:129]
	s_mov_b32 m0, s29
	s_nop 0
	global_load_lds_dwordx4 v[144:145], off
	v_lshl_add_u64 v[144:145], s[34:35], 0, v[134:135]
	s_add_i32 m0, s29, 0x2000
	s_nop 0
	global_load_lds_dwordx4 v[144:145], off
	v_lshl_add_u64 v[144:145], v[212:213], 0, s[94:95]
	s_mov_b32 m0, s55
	s_nop 0
	global_load_lds_dwordx4 v[144:145], off
	v_lshl_add_u64 v[144:145], v[214:215], 0, s[94:95]
	s_mov_b32 m0, s62
	s_nop 0
	global_load_lds_dwordx4 v[144:145], off
	s_waitcnt vmcnt(8)
	s_waitcnt lgkmcnt(0)
	s_barrier
	s_setprio 1
	s_waitcnt lgkmcnt(0)
	v_mfma_f32_16x16x32_bf16 v[60:63], v[140:143], v[178:181], v[60:63]
	v_mfma_f32_16x16x32_bf16 v[56:59], v[154:157], v[178:181], v[56:59]
	v_mfma_f32_16x16x32_bf16 v[52:55], v[140:143], v[186:189], v[52:55]
	v_mfma_f32_16x16x32_bf16 v[48:51], v[154:157], v[186:189], v[48:51]
	v_mfma_f32_16x16x32_bf16 v[36:39], v[140:143], v[194:197], v[36:39]
	v_mfma_f32_16x16x32_bf16 v[32:35], v[154:157], v[194:197], v[32:35]
	v_mfma_f32_16x16x32_bf16 v[20:23], v[140:143], v[202:205], v[20:23]
	v_mfma_f32_16x16x32_bf16 v[16:19], v[154:157], v[202:205], v[16:19]
	v_mfma_f32_16x16x32_bf16 v[60:63], v[150:153], v[182:185], v[60:63]
	v_mfma_f32_16x16x32_bf16 v[56:59], v[158:161], v[182:185], v[56:59]
	v_mfma_f32_16x16x32_bf16 v[52:55], v[150:153], v[190:193], v[52:55]
	v_mfma_f32_16x16x32_bf16 v[48:51], v[158:161], v[190:193], v[48:51]
	v_mfma_f32_16x16x32_bf16 v[36:39], v[150:153], v[198:201], v[36:39]
	v_mfma_f32_16x16x32_bf16 v[32:35], v[158:161], v[198:201], v[32:35]
	v_mfma_f32_16x16x32_bf16 v[20:23], v[150:153], v[206:209], v[20:23]
	v_mfma_f32_16x16x32_bf16 v[16:19], v[158:161], v[206:209], v[16:19]
	v_mfma_f32_16x16x32_bf16 v[44:47], v[162:165], v[178:181], v[44:47]
	v_mfma_f32_16x16x32_bf16 v[40:43], v[170:173], v[178:181], v[40:43]
	v_mfma_f32_16x16x32_bf16 v[28:31], v[162:165], v[186:189], v[28:31]
	v_mfma_f32_16x16x32_bf16 v[24:27], v[170:173], v[186:189], v[24:27]
	v_mfma_f32_16x16x32_bf16 v[12:15], v[162:165], v[194:197], v[12:15]
	v_mfma_f32_16x16x32_bf16 v[8:11], v[170:173], v[194:197], v[8:11]
	v_mfma_f32_16x16x32_bf16 v[4:7], v[162:165], v[202:205], v[4:7]
	v_mfma_f32_16x16x32_bf16 v[0:3], v[170:173], v[202:205], v[0:3]
	v_mfma_f32_16x16x32_bf16 v[44:47], v[166:169], v[182:185], v[44:47]
	v_mfma_f32_16x16x32_bf16 v[40:43], v[174:177], v[182:185], v[40:43]
	v_mfma_f32_16x16x32_bf16 v[28:31], v[166:169], v[190:193], v[28:31]
	v_mfma_f32_16x16x32_bf16 v[24:27], v[174:177], v[190:193], v[24:27]
	v_mfma_f32_16x16x32_bf16 v[12:15], v[166:169], v[198:201], v[12:15]
	v_mfma_f32_16x16x32_bf16 v[8:11], v[174:177], v[198:201], v[8:11]
	v_mfma_f32_16x16x32_bf16 v[4:7], v[166:169], v[206:209], v[4:7]
	v_mfma_f32_16x16x32_bf16 v[0:3], v[174:177], v[206:209], v[0:3]
	s_setprio 0
	s_barrier
	s_add_i32 s64, s64, 2
	s_add_u32 s30, s30, 0x100
	s_addc_u32 s31, s31, 0
	s_add_u32 s9, s9, 0x100
	s_addc_u32 s11, s11, 0
	s_cmp_gt_u32 s64, 29
	s_cbranch_scc0 .LBB0_835
	s_and_b64 vcc, exec, s[4:5]
	s_cbranch_vccz .LBB0_838
	s_barrier
